# super
# speedup vs baseline: 1.0150x; 1.0065x over previous
; #define STAGE_A(P, br, kt) do { const char* _base = (const char*)(((kt) < G.ksplit ? G.A1 : A2m) + (long)(br) * G.lda + (long)(kt) * BK); \
;     __builtin_amdgcn_global_load_lds((const unsigned*)(_base + aoff0), (unsigned*)((char*)(P) + sb0), 16, 0, 0); \
;     __builtin_amdgcn_global_load_lds((const unsigned*)(_base + aoff1), (unsigned*)((char*)(P) + sb1), 16, 0, 0); } while (0)
; #define STAGE_B(P, br, kt) do { const char* _base = (const char*)(G.Bt + (long)(br) * G.ldb + (long)(kt) * BK); \
;     __builtin_amdgcn_global_load_lds((const unsigned*)(_base + boff0), (unsigned*)((char*)(P) + sb0), 16, 0, 0); \
;     __builtin_amdgcn_global_load_lds((const unsigned*)(_base + boff1), (unsigned*)((char*)(P) + sb1), 16, 0, 0); } while (0)
; #define LDA(dst, b, h) for (int m = 0; m < 4; ++m) for (int k = 0; k < 2; ++k) \
;     dst[m][k] = *reinterpret_cast<const bf16x8*>(a_rd + ((b) * 2 + (h)) * (HT * 2) + m * 2048 + k * 1024)
; #define LDB(dst, b, h) for (int n = 0; n < 2; ++n) for (int k = 0; k < 2; ++k) \
;     dst[n][k] = *reinterpret_cast<const bf16x8*>(b_rd + ((b) * 2 + (h)) * (HT * 2) + n * 2048 + k * 1024)
; #define MMA(ai, bj, At_, Bt_) do { __builtin_amdgcn_s_setprio(1); \
;     for (int m = 0; m < 4; ++m) for (int n = 0; n < 2; ++n) for (int k = 0; k < 2; ++k) \
;       acc[ai][bj][m][n] = __builtin_amdgcn_mfma_f32_16x16x32_bf16(Bt_[n][k], At_[m][k], acc[ai][bj][m][n], 0, 0, 0); \
;     __builtin_amdgcn_s_setprio(0); } while (0)
; #define WAIT_L(n) asm volatile("s_waitcnt lgkmcnt(" #n ")" ::: "memory")
; #define BAR __builtin_amdgcn_s_barrier()
; #define SCHED __builtin_amdgcn_sched_barrier(0)
;     ...
;   for (int t = 0; t < nt - 2; t += 2) {
;     LDB(B0, 0, 0); SCHED; LDA(At, 0, 0); STAGE_A(SA(1, 1), brow + HALF, t + 1);
;     WAIT_L(8); BAR; WAIT_L(0); MMA(0, 0, At, B0); BAR; SCHED;
;     LDB(B1, 0, 1); STAGE_B(SB(0, 0), bcol, t + 2);
;     BAR; WAIT_L(0); MMA(0, 1, At, B1); BAR;
;     LDA(At, 0, 1); STAGE_A(SA(0, 0), brow, t + 2);
;     BAR; WAIT_L(0); MMA(1, 0, At, B0); BAR; SCHED;
;     STAGE_B(SB(0, 1), bcol + HALF, t + 2);
.LBB0_746:
	ds_read_b128 v[164:167], v155
	ds_read_b128 v[168:171], v155 offset:1024
	ds_read_b128 v[172:175], v155 offset:2048
	ds_read_b128 v[176:179], v155 offset:3072
	v_add_u32_e32 v162, 0xc000, v149
	v_lshl_add_u64 v[222:223], v[134:135], 0, s[8:9]
	v_readfirstlane_b32 s42, v162
	v_add_u32_e32 v163, 0xe000, v149
	v_lshl_add_u64 v[160:161], v[222:223], 0, s[44:45]
	s_mov_b32 m0, s42
	v_lshl_add_u64 v[234:235], v[136:137], 0, s[8:9]
	v_readfirstlane_b32 s42, v163
	ds_read_b128 v[182:185], v151
	ds_read_b128 v[186:189], v151 offset:1024
	ds_read_b128 v[190:193], v151 offset:2048
	ds_read_b128 v[194:197], v151 offset:3072
	ds_read_b128 v[198:201], v151 offset:4096
	ds_read_b128 v[202:205], v151 offset:5120
	ds_read_b128 v[206:209], v151 offset:6144
	ds_read_b128 v[210:213], v151 offset:7168
	global_load_lds_dwordx4 v[160:161], off
	v_lshl_add_u64 v[160:161], v[234:235], 0, s[44:45]
	s_mov_b32 m0, s42
	s_nop 0
	global_load_lds_dwordx4 v[160:161], off
	ds_read_b128 v[214:217], v155 offset:16384
	ds_read_b128 v[218:221], v155 offset:17408
	ds_read_b128 v[230:233], v155 offset:18432
	ds_read_b128 v[238:241], v155 offset:19456
	s_waitcnt lgkmcnt(0)
	s_waitcnt vmcnt(8)
	s_barrier
	s_setprio 1
	v_mfma_f32_16x16x32_bf16 v[124:127], v[164:167], v[182:185], v[124:127]
	v_mfma_f32_16x16x32_bf16 v[120:123], v[172:175], v[182:185], v[120:123]
	v_mfma_f32_16x16x32_bf16 v[116:119], v[164:167], v[190:193], v[116:119]
	v_mfma_f32_16x16x32_bf16 v[112:115], v[172:175], v[190:193], v[112:115]
	v_mfma_f32_16x16x32_bf16 v[108:111], v[164:167], v[198:201], v[108:111]
	v_mfma_f32_16x16x32_bf16 v[104:107], v[172:175], v[198:201], v[104:107]
	v_mfma_f32_16x16x32_bf16 v[100:103], v[164:167], v[206:209], v[100:103]
	v_mfma_f32_16x16x32_bf16 v[96:99], v[172:175], v[206:209], v[96:99]
	v_mfma_f32_16x16x32_bf16 v[124:127], v[168:171], v[186:189], v[124:127]
	v_mfma_f32_16x16x32_bf16 v[120:123], v[176:179], v[186:189], v[120:123]
	v_mfma_f32_16x16x32_bf16 v[116:119], v[168:171], v[194:197], v[116:119]
	v_mfma_f32_16x16x32_bf16 v[112:115], v[176:179], v[194:197], v[112:115]
	v_mfma_f32_16x16x32_bf16 v[108:111], v[168:171], v[202:205], v[108:111]
	v_mfma_f32_16x16x32_bf16 v[104:107], v[176:179], v[202:205], v[104:107]
	v_mfma_f32_16x16x32_bf16 v[100:103], v[168:171], v[210:213], v[100:103]
	v_mfma_f32_16x16x32_bf16 v[96:99], v[176:179], v[210:213], v[96:99]
	v_mfma_f32_16x16x32_bf16 v[92:95], v[214:217], v[182:185], v[92:95]
	v_mfma_f32_16x16x32_bf16 v[88:91], v[230:233], v[182:185], v[88:91]
	v_mfma_f32_16x16x32_bf16 v[84:87], v[214:217], v[190:193], v[84:87]
	v_mfma_f32_16x16x32_bf16 v[80:83], v[230:233], v[190:193], v[80:83]
	v_mfma_f32_16x16x32_bf16 v[76:79], v[214:217], v[198:201], v[76:79]
	v_mfma_f32_16x16x32_bf16 v[72:75], v[230:233], v[198:201], v[72:75]
	v_mfma_f32_16x16x32_bf16 v[68:71], v[214:217], v[206:209], v[68:71]
	v_mfma_f32_16x16x32_bf16 v[64:67], v[230:233], v[206:209], v[64:67]
	v_mfma_f32_16x16x32_bf16 v[92:95], v[218:221], v[186:189], v[92:95]
	v_mfma_f32_16x16x32_bf16 v[88:91], v[238:241], v[186:189], v[88:91]
	v_mfma_f32_16x16x32_bf16 v[84:87], v[218:221], v[194:197], v[84:87]
	v_mfma_f32_16x16x32_bf16 v[80:83], v[238:241], v[194:197], v[80:83]
	v_mfma_f32_16x16x32_bf16 v[76:79], v[218:221], v[202:205], v[76:79]
	v_mfma_f32_16x16x32_bf16 v[72:75], v[238:241], v[202:205], v[72:75]
	s_setprio 2
	s_barrier
	v_mfma_f32_16x16x32_bf16 v[68:71], v[218:221], v[210:213], v[68:71]
	v_mfma_f32_16x16x32_bf16 v[64:67], v[238:241], v[210:213], v[64:67]
	s_setprio 0
	v_add_u32_e32 v159, s10, v146
	v_lshl_add_u64 v[236:237], v[130:131], 0, s[8:9]
	v_readfirstlane_b32 s42, v159
	v_lshl_add_u64 v[160:161], v[236:237], 0, s[46:47]
	s_mov_b32 m0, s42
	global_load_lds_dwordx4 v[160:161], off
	v_add_u32_e32 v160, 0x2000, v159
	v_lshl_add_u64 v[246:247], v[132:133], 0, s[8:9]
	v_readfirstlane_b32 s42, v160
	v_lshl_add_u64 v[248:249], v[246:247], 0, s[46:47]
	s_mov_b32 m0, s42
	s_nop 0
	global_load_lds_dwordx4 v[248:249], off
	v_readfirstlane_b32 s42, v149
	v_lshl_add_u64 v[248:249], v[222:223], 0, s[90:91]
	s_mov_b32 m0, s42
	v_readfirstlane_b32 s42, v147
	ds_read_b128 v[182:185], v151 offset:16384
	ds_read_b128 v[186:189], v151 offset:17408
	ds_read_b128 v[190:193], v151 offset:18432
	ds_read_b128 v[194:197], v151 offset:19456
	ds_read_b128 v[198:201], v151 offset:20480
	ds_read_b128 v[202:205], v151 offset:21504
	ds_read_b128 v[206:209], v151 offset:22528
	ds_read_b128 v[210:213], v151 offset:23552
	global_load_lds_dwordx4 v[248:249], off
	v_lshl_add_u64 v[248:249], v[234:235], 0, s[90:91]
	s_mov_b32 m0, s42
	s_nop 0
	global_load_lds_dwordx4 v[248:249], off
	v_lshl_add_u64 v[248:249], v[138:139], 0, s[8:9]
	v_readfirstlane_b32 s42, v145
	v_add_u32_e32 v161, 0x2000, v145
	v_lshl_add_u64 v[250:251], v[248:249], 0, vcc
	s_mov_b32 m0, s42
	v_lshl_add_u64 v[226:227], v[140:141], 0, s[8:9]
	v_readfirstlane_b32 s42, v161
	global_load_lds_dwordx4 v[250:251], off
	v_lshl_add_u64 v[250:251], v[226:227], 0, vcc
	s_mov_b32 m0, s42
	s_nop 0
	global_load_lds_dwordx4 v[250:251], off
	s_waitcnt lgkmcnt(0)
	s_waitcnt vmcnt(8)
	s_barrier
; #define STAGE_A(P, br, kt) do { const char* _base = (const char*)(((kt) < G.ksplit ? G.A1 : A2m) + (long)(br) * G.lda + (long)(kt) * BK); \
;     __builtin_amdgcn_global_load_lds((const unsigned*)(_base + aoff0), (unsigned*)((char*)(P) + sb0), 16, 0, 0); \
;     __builtin_amdgcn_global_load_lds((const unsigned*)(_base + aoff1), (unsigned*)((char*)(P) + sb1), 16, 0, 0); } while (0)
; #define STAGE_B(P, br, kt) do { const char* _base = (const char*)(G.Bt + (long)(br) * G.ldb + (long)(kt) * BK); \
;     __builtin_amdgcn_global_load_lds((const unsigned*)(_base + boff0), (unsigned*)((char*)(P) + sb0), 16, 0, 0); \
;     __builtin_amdgcn_global_load_lds((const unsigned*)(_base + boff1), (unsigned*)((char*)(P) + sb1), 16, 0, 0); } while (0)
; #define LDA(dst, b, h) for (int m = 0; m < 4; ++m) for (int k = 0; k < 2; ++k) \
;     dst[m][k] = *reinterpret_cast<const bf16x8*>(a_rd + ((b) * 2 + (h)) * (HT * 2) + m * 2048 + k * 1024)
; #define LDB(dst, b, h) for (int n = 0; n < 2; ++n) for (int k = 0; k < 2; ++k) \
;     dst[n][k] = *reinterpret_cast<const bf16x8*>(b_rd + ((b) * 2 + (h)) * (HT * 2) + n * 2048 + k * 1024)
; #define MMA(ai, bj, At_, Bt_) do { __builtin_amdgcn_s_setprio(1); \
;     for (int m = 0; m < 4; ++m) for (int n = 0; n < 2; ++n) for (int k = 0; k < 2; ++k) \
;       acc[ai][bj][m][n] = __builtin_amdgcn_mfma_f32_16x16x32_bf16(Bt_[n][k], At_[m][k], acc[ai][bj][m][n], 0, 0, 0); \
;     __builtin_amdgcn_s_setprio(0); } while (0)
; #define WAIT_V(n) asm volatile("s_waitcnt vmcnt(" #n ")" ::: "memory")
; #define WAIT_L(n) asm volatile("s_waitcnt lgkmcnt(" #n ")" ::: "memory")
; #define BAR __builtin_amdgcn_s_barrier()
; #define SCHED __builtin_amdgcn_sched_barrier(0)
;     ...
;     LDA(At, 0, 1); STAGE_A(SA(0, 0), brow, t + 2);
;     BAR; WAIT_L(0); MMA(1, 0, At, B0); BAR; SCHED;
;     STAGE_B(SB(0, 1), bcol + HALF, t + 2);
;     WAIT_V(6); BAR; MMA(1, 1, At, B1); BAR;
;     LDB(B0, 1, 0); SCHED; LDA(At, 1, 0); STAGE_A(SA(0, 1), brow + HALF, t + 2);
;     WAIT_L(8); BAR; WAIT_L(0); MMA(0, 0, At, B0); BAR; SCHED;
;     LDB(B1, 1, 1); STAGE_B(SB(1, 0), bcol, t + 3);
;     BAR; WAIT_L(0); MMA(0, 1, At, B1); BAR;
;     LDA(At, 1, 1); STAGE_A(SA(1, 0), brow, t + 3);
;     BAR; WAIT_L(0); MMA(1, 0, At, B0); BAR; SCHED;
	s_setprio 1
	v_mfma_f32_16x16x32_bf16 v[60:63], v[164:167], v[182:185], v[60:63]
	v_mfma_f32_16x16x32_bf16 v[56:59], v[172:175], v[182:185], v[56:59]
	v_mfma_f32_16x16x32_bf16 v[52:55], v[164:167], v[190:193], v[52:55]
	v_mfma_f32_16x16x32_bf16 v[48:51], v[172:175], v[190:193], v[48:51]
	v_mfma_f32_16x16x32_bf16 v[44:47], v[164:167], v[198:201], v[44:47]
	v_mfma_f32_16x16x32_bf16 v[40:43], v[172:175], v[198:201], v[40:43]
	v_mfma_f32_16x16x32_bf16 v[36:39], v[164:167], v[206:209], v[36:39]
	v_mfma_f32_16x16x32_bf16 v[32:35], v[172:175], v[206:209], v[32:35]
	v_mfma_f32_16x16x32_bf16 v[60:63], v[168:171], v[186:189], v[60:63]
	v_mfma_f32_16x16x32_bf16 v[56:59], v[176:179], v[186:189], v[56:59]
	v_mfma_f32_16x16x32_bf16 v[52:55], v[168:171], v[194:197], v[52:55]
	v_mfma_f32_16x16x32_bf16 v[48:51], v[176:179], v[194:197], v[48:51]
	v_mfma_f32_16x16x32_bf16 v[44:47], v[168:171], v[202:205], v[44:47]
	v_mfma_f32_16x16x32_bf16 v[40:43], v[176:179], v[202:205], v[40:43]
	v_mfma_f32_16x16x32_bf16 v[36:39], v[168:171], v[210:213], v[36:39]
	v_mfma_f32_16x16x32_bf16 v[32:35], v[176:179], v[210:213], v[32:35]
	v_mfma_f32_16x16x32_bf16 v[28:31], v[214:217], v[182:185], v[28:31]
	v_mfma_f32_16x16x32_bf16 v[24:27], v[230:233], v[182:185], v[24:27]
	v_mfma_f32_16x16x32_bf16 v[20:23], v[214:217], v[190:193], v[20:23]
	v_mfma_f32_16x16x32_bf16 v[16:19], v[230:233], v[190:193], v[16:19]
	v_mfma_f32_16x16x32_bf16 v[12:15], v[214:217], v[198:201], v[12:15]
	v_mfma_f32_16x16x32_bf16 v[8:11], v[230:233], v[198:201], v[8:11]
	v_mfma_f32_16x16x32_bf16 v[4:7], v[214:217], v[206:209], v[4:7]
	v_mfma_f32_16x16x32_bf16 v[0:3], v[230:233], v[206:209], v[0:3]
	v_mfma_f32_16x16x32_bf16 v[28:31], v[218:221], v[186:189], v[28:31]
	v_mfma_f32_16x16x32_bf16 v[24:27], v[238:241], v[186:189], v[24:27]
	v_mfma_f32_16x16x32_bf16 v[20:23], v[218:221], v[194:197], v[20:23]
	v_mfma_f32_16x16x32_bf16 v[16:19], v[238:241], v[194:197], v[16:19]
	v_mfma_f32_16x16x32_bf16 v[12:15], v[218:221], v[202:205], v[12:15]
	v_mfma_f32_16x16x32_bf16 v[8:11], v[238:241], v[202:205], v[8:11]
	s_setprio 2
	s_barrier
	v_mfma_f32_16x16x32_bf16 v[4:7], v[218:221], v[210:213], v[4:7]
	v_mfma_f32_16x16x32_bf16 v[0:3], v[238:241], v[210:213], v[0:3]
	s_setprio 0
	ds_read_b128 v[164:167], v155 offset:32768
	ds_read_b128 v[168:171], v155 offset:33792
	ds_read_b128 v[172:175], v155 offset:34816
	ds_read_b128 v[176:179], v155 offset:35840
	v_readfirstlane_b32 s42, v143
	v_lshl_add_u64 v[214:215], v[222:223], 0, s[64:65]
	s_mov_b32 m0, s42
	v_readfirstlane_b32 s42, v142
	ds_read_b128 v[182:185], v151 offset:32768
	ds_read_b128 v[186:189], v151 offset:33792
	ds_read_b128 v[190:193], v151 offset:34816
	ds_read_b128 v[194:197], v151 offset:35840
	ds_read_b128 v[198:201], v151 offset:36864
	ds_read_b128 v[202:205], v151 offset:37888
	ds_read_b128 v[206:209], v151 offset:38912
	ds_read_b128 v[210:213], v151 offset:39936
	global_load_lds_dwordx4 v[214:215], off
	v_lshl_add_u64 v[214:215], v[234:235], 0, s[64:65]
	s_mov_b32 m0, s42
	s_nop 0
	global_load_lds_dwordx4 v[214:215], off
	ds_read_b128 v[214:217], v155 offset:49152
	ds_read_b128 v[218:221], v155 offset:50176
	ds_read_b128 v[230:233], v155 offset:51200
	ds_read_b128 v[238:241], v155 offset:52224
	s_waitcnt lgkmcnt(0)
	s_waitcnt vmcnt(8)
	s_barrier
	s_setprio 1
	v_mfma_f32_16x16x32_bf16 v[124:127], v[164:167], v[182:185], v[124:127]
	v_mfma_f32_16x16x32_bf16 v[120:123], v[172:175], v[182:185], v[120:123]
	v_mfma_f32_16x16x32_bf16 v[116:119], v[164:167], v[190:193], v[116:119]
	v_mfma_f32_16x16x32_bf16 v[112:115], v[172:175], v[190:193], v[112:115]
	v_mfma_f32_16x16x32_bf16 v[108:111], v[164:167], v[198:201], v[108:111]
	v_mfma_f32_16x16x32_bf16 v[104:107], v[172:175], v[198:201], v[104:107]
	v_mfma_f32_16x16x32_bf16 v[100:103], v[164:167], v[206:209], v[100:103]
	v_mfma_f32_16x16x32_bf16 v[96:99], v[172:175], v[206:209], v[96:99]
	v_mfma_f32_16x16x32_bf16 v[124:127], v[168:171], v[186:189], v[124:127]
	v_mfma_f32_16x16x32_bf16 v[120:123], v[176:179], v[186:189], v[120:123]
	v_mfma_f32_16x16x32_bf16 v[116:119], v[168:171], v[194:197], v[116:119]
	v_mfma_f32_16x16x32_bf16 v[112:115], v[176:179], v[194:197], v[112:115]
	v_mfma_f32_16x16x32_bf16 v[108:111], v[168:171], v[202:205], v[108:111]
	v_mfma_f32_16x16x32_bf16 v[104:107], v[176:179], v[202:205], v[104:107]
	v_mfma_f32_16x16x32_bf16 v[100:103], v[168:171], v[210:213], v[100:103]
	v_mfma_f32_16x16x32_bf16 v[96:99], v[176:179], v[210:213], v[96:99]
	v_mfma_f32_16x16x32_bf16 v[92:95], v[214:217], v[182:185], v[92:95]
	v_mfma_f32_16x16x32_bf16 v[88:91], v[230:233], v[182:185], v[88:91]
	v_mfma_f32_16x16x32_bf16 v[84:87], v[214:217], v[190:193], v[84:87]
	v_mfma_f32_16x16x32_bf16 v[80:83], v[230:233], v[190:193], v[80:83]
	v_mfma_f32_16x16x32_bf16 v[76:79], v[214:217], v[198:201], v[76:79]
	v_mfma_f32_16x16x32_bf16 v[72:75], v[230:233], v[198:201], v[72:75]
	v_mfma_f32_16x16x32_bf16 v[68:71], v[214:217], v[206:209], v[68:71]
	v_mfma_f32_16x16x32_bf16 v[64:67], v[230:233], v[206:209], v[64:67]
	v_mfma_f32_16x16x32_bf16 v[92:95], v[218:221], v[186:189], v[92:95]
	v_mfma_f32_16x16x32_bf16 v[88:91], v[238:241], v[186:189], v[88:91]
	v_mfma_f32_16x16x32_bf16 v[84:87], v[218:221], v[194:197], v[84:87]
	v_mfma_f32_16x16x32_bf16 v[80:83], v[238:241], v[194:197], v[80:83]
	v_mfma_f32_16x16x32_bf16 v[76:79], v[218:221], v[202:205], v[76:79]
	v_mfma_f32_16x16x32_bf16 v[72:75], v[238:241], v[202:205], v[72:75]
	s_setprio 2
	s_barrier
; #define STAGE_A(P, br, kt) do { const char* _base = (const char*)(((kt) < G.ksplit ? G.A1 : A2m) + (long)(br) * G.lda + (long)(kt) * BK); \
;     __builtin_amdgcn_global_load_lds((const unsigned*)(_base + aoff0), (unsigned*)((char*)(P) + sb0), 16, 0, 0); \
;     __builtin_amdgcn_global_load_lds((const unsigned*)(_base + aoff1), (unsigned*)((char*)(P) + sb1), 16, 0, 0); } while (0)
; #define STAGE_B(P, br, kt) do { const char* _base = (const char*)(G.Bt + (long)(br) * G.ldb + (long)(kt) * BK); \
;     __builtin_amdgcn_global_load_lds((const unsigned*)(_base + boff0), (unsigned*)((char*)(P) + sb0), 16, 0, 0); \
;     __builtin_amdgcn_global_load_lds((const unsigned*)(_base + boff1), (unsigned*)((char*)(P) + sb1), 16, 0, 0); } while (0)
; #define LDA(dst, b, h) for (int m = 0; m < 4; ++m) for (int k = 0; k < 2; ++k) \
;     dst[m][k] = *reinterpret_cast<const bf16x8*>(a_rd + ((b) * 2 + (h)) * (HT * 2) + m * 2048 + k * 1024)
; #define LDB(dst, b, h) for (int n = 0; n < 2; ++n) for (int k = 0; k < 2; ++k) \
;     dst[n][k] = *reinterpret_cast<const bf16x8*>(b_rd + ((b) * 2 + (h)) * (HT * 2) + n * 2048 + k * 1024)
; #define MMA(ai, bj, At_, Bt_) do { __builtin_amdgcn_s_setprio(1); \
;     for (int m = 0; m < 4; ++m) for (int n = 0; n < 2; ++n) for (int k = 0; k < 2; ++k) \
;       acc[ai][bj][m][n] = __builtin_amdgcn_mfma_f32_16x16x32_bf16(Bt_[n][k], At_[m][k], acc[ai][bj][m][n], 0, 0, 0); \
;     __builtin_amdgcn_s_setprio(0); } while (0)
; #define WAIT_V(n) asm volatile("s_waitcnt vmcnt(" #n ")" ::: "memory")
; #define BAR __builtin_amdgcn_s_barrier()
;     ...
;     LDB(B0, 1, 0); SCHED; LDA(At, 1, 0); STAGE_A(SA(0, 1), brow + HALF, t + 2);
;     WAIT_L(8); BAR; WAIT_L(0); MMA(0, 0, At, B0); BAR; SCHED;
;     LDB(B1, 1, 1); STAGE_B(SB(1, 0), bcol, t + 3);
;     BAR; WAIT_L(0); MMA(0, 1, At, B1); BAR;
;     LDA(At, 1, 1); STAGE_A(SA(1, 0), brow, t + 3);
;     BAR; WAIT_L(0); MMA(1, 0, At, B0); BAR; SCHED;
;     STAGE_B(SB(1, 1), bcol + HALF, t + 3);
;     WAIT_V(6); BAR; MMA(1, 1, At, B1); BAR;
;   }
;   float ssv[2][4] = {};
;   if constexpr (EPI == EPI_GU || EPI == EPI_EVIN || EPI == EPI_ODIN) {
; #pragma unroll
;     for (int ai = 0; ai < 2; ++ai)
; #pragma unroll
;       for (int m = 0; m < 4; ++m) ssv[ai][m] = G.ssr[brow + ai * HALF + wr * 64 + m * 16 + fr];
;   }
;   { LDB(B0, 0, 0); LDA(At, 0, 0); STAGE_A(SA(1, 1), brow + HALF, nt - 1);
	v_mfma_f32_16x16x32_bf16 v[68:71], v[218:221], v[210:213], v[68:71]
	v_mfma_f32_16x16x32_bf16 v[64:67], v[238:241], v[210:213], v[64:67]
	s_setprio 0
	v_readfirstlane_b32 s42, v152
	v_lshl_add_u64 v[236:237], v[236:237], 0, s[22:23]
	s_mov_b32 m0, s42
	v_readfirstlane_b32 s42, v153
	global_load_lds_dwordx4 v[236:237], off
	v_lshl_add_u64 v[236:237], v[246:247], 0, s[22:23]
	s_mov_b32 m0, s42
	s_nop 0
	global_load_lds_dwordx4 v[236:237], off
	v_readfirstlane_b32 s42, v154
	v_lshl_add_u64 v[222:223], v[222:223], 0, s[88:89]
	s_mov_b32 m0, s42
	v_readfirstlane_b32 s42, v156
	ds_read_b128 v[182:185], v151 offset:49152
	ds_read_b128 v[186:189], v151 offset:50176
	ds_read_b128 v[190:193], v151 offset:51200
	ds_read_b128 v[194:197], v151 offset:52224
	ds_read_b128 v[198:201], v151 offset:53248
	ds_read_b128 v[202:205], v151 offset:54272
	ds_read_b128 v[206:209], v151 offset:55296
	ds_read_b128 v[210:213], v151 offset:56320
	global_load_lds_dwordx4 v[222:223], off
	v_lshl_add_u64 v[222:223], v[234:235], 0, s[88:89]
	s_mov_b32 m0, s42
	s_nop 0
	global_load_lds_dwordx4 v[222:223], off
	v_readfirstlane_b32 s42, v157
	v_lshl_add_u64 v[250:251], v[248:249], 0, s[24:25]
	s_mov_b32 m0, s42
	v_readfirstlane_b32 s42, v158
	global_load_lds_dwordx4 v[250:251], off
	v_lshl_add_u64 v[250:251], v[226:227], 0, s[24:25]
	s_mov_b32 m0, s42
	s_nop 0
	global_load_lds_dwordx4 v[250:251], off
	s_waitcnt lgkmcnt(0)
	s_waitcnt vmcnt(8)
	s_barrier
	s_setprio 1
	v_mfma_f32_16x16x32_bf16 v[60:63], v[164:167], v[182:185], v[60:63]
	v_mfma_f32_16x16x32_bf16 v[56:59], v[172:175], v[182:185], v[56:59]
	v_mfma_f32_16x16x32_bf16 v[52:55], v[164:167], v[190:193], v[52:55]
	v_mfma_f32_16x16x32_bf16 v[48:51], v[172:175], v[190:193], v[48:51]
	v_mfma_f32_16x16x32_bf16 v[44:47], v[164:167], v[198:201], v[44:47]
	v_mfma_f32_16x16x32_bf16 v[40:43], v[172:175], v[198:201], v[40:43]
	v_mfma_f32_16x16x32_bf16 v[36:39], v[164:167], v[206:209], v[36:39]
	v_mfma_f32_16x16x32_bf16 v[32:35], v[172:175], v[206:209], v[32:35]
	v_mfma_f32_16x16x32_bf16 v[60:63], v[168:171], v[186:189], v[60:63]
	v_mfma_f32_16x16x32_bf16 v[56:59], v[176:179], v[186:189], v[56:59]
	v_mfma_f32_16x16x32_bf16 v[52:55], v[168:171], v[194:197], v[52:55]
	v_mfma_f32_16x16x32_bf16 v[48:51], v[176:179], v[194:197], v[48:51]
	v_mfma_f32_16x16x32_bf16 v[44:47], v[168:171], v[202:205], v[44:47]
	v_mfma_f32_16x16x32_bf16 v[40:43], v[176:179], v[202:205], v[40:43]
	v_mfma_f32_16x16x32_bf16 v[36:39], v[168:171], v[210:213], v[36:39]
	v_mfma_f32_16x16x32_bf16 v[32:35], v[176:179], v[210:213], v[32:35]
	v_mfma_f32_16x16x32_bf16 v[28:31], v[214:217], v[182:185], v[28:31]
	v_mfma_f32_16x16x32_bf16 v[24:27], v[230:233], v[182:185], v[24:27]
	v_mfma_f32_16x16x32_bf16 v[20:23], v[214:217], v[190:193], v[20:23]
	v_mfma_f32_16x16x32_bf16 v[16:19], v[230:233], v[190:193], v[16:19]
	v_mfma_f32_16x16x32_bf16 v[12:15], v[214:217], v[198:201], v[12:15]
	v_mfma_f32_16x16x32_bf16 v[8:11], v[230:233], v[198:201], v[8:11]
	v_mfma_f32_16x16x32_bf16 v[4:7], v[214:217], v[206:209], v[4:7]
	v_mfma_f32_16x16x32_bf16 v[0:3], v[230:233], v[206:209], v[0:3]
	v_mfma_f32_16x16x32_bf16 v[28:31], v[218:221], v[186:189], v[28:31]
	v_mfma_f32_16x16x32_bf16 v[24:27], v[238:241], v[186:189], v[24:27]
	v_mfma_f32_16x16x32_bf16 v[20:23], v[218:221], v[194:197], v[20:23]
	v_mfma_f32_16x16x32_bf16 v[16:19], v[238:241], v[194:197], v[16:19]
	v_mfma_f32_16x16x32_bf16 v[12:15], v[218:221], v[202:205], v[12:15]
	v_mfma_f32_16x16x32_bf16 v[8:11], v[238:241], v[202:205], v[8:11]
	s_setprio 2
	s_barrier
	v_mfma_f32_16x16x32_bf16 v[4:7], v[218:221], v[210:213], v[4:7]
	v_mfma_f32_16x16x32_bf16 v[0:3], v[238:241], v[210:213], v[0:3]
	s_setprio 0
	s_add_i32 s11, s11, 2
	s_add_u32 s8, s8, 0x100
	s_addc_u32 s9, s9, 0
	s_cmp_lt_u32 s11, 28
	s_cbranch_scc1 .LBB0_746
	s_waitcnt vmcnt(6)
	v_not_b32_e32 v250, 63
	v_mov_b32_e32 v251, 0x41b17218
	v_or_b32_e32 v130, s40, v150
	v_lshl_add_u32 v130, v148, 6, v130
	v_ashrrev_i32_e32 v131, 31, v130
	v_lshl_add_u64 v[132:133], v[130:131], 2, s[30:31]
	v_add_u32_e32 v134, 0x80, v130
	v_add_u32_e32 v136, 0x90, v130
	v_add_u32_e32 v138, 0xa0, v130
	v_add_u32_e32 v130, 0xb0, v130
	s_or_b32 s57, s40, 0x80
	v_ashrrev_i32_e32 v135, 31, v134
	v_ashrrev_i32_e32 v137, 31, v136
	v_ashrrev_i32_e32 v139, 31, v138
	v_ashrrev_i32_e32 v131, 31, v130
	s_mul_i32 s8, s57, 0x1080
	v_lshl_add_u64 v[134:135], v[134:135], 2, s[30:31]
	v_lshl_add_u64 v[136:137], v[136:137], 2, s[30:31]
	v_lshl_add_u64 v[138:139], v[138:139], 2, s[30:31]
	v_lshl_add_u64 v[140:141], v[130:131], 2, s[30:31]
	global_load_dword v130, v[132:133], off
	global_load_dword v146, v[132:133], off offset:64
	global_load_dword v148, v[132:133], off offset:128
	global_load_dword v156, v[132:133], off offset:192
	global_load_dword v154, v[134:135], off
	global_load_dword v153, v[136:137], off
	global_load_dword v152, v[138:139], off
	global_load_dword v150, v[140:141], off
	s_mul_hi_i32 s9, s57, 0x1080
	s_add_u32 s8, s12, s8
	s_addc_u32 s9, s13, s9
	v_lshl_add_u64 v[140:141], s[8:9], 0, v[180:181]
	s_mov_b64 s[22:23], 0xf80
	v_readfirstlane_b32 s10, v162
	v_lshl_add_u64 v[140:141], v[140:141], 0, s[22:23]
	s_mov_b32 m0, s10
	ds_read_b128 v[132:135], v155
	ds_read_b128 v[136:139], v155 offset:1024
	ds_read_b128 v[164:167], v155 offset:2048
	ds_read_b128 v[168:171], v155 offset:3072
	ds_read_b128 v[172:175], v151
	ds_read_b128 v[176:179], v151 offset:1024
	ds_read_b128 v[182:185], v151 offset:2048
	ds_read_b128 v[186:189], v151 offset:3072
	ds_read_b128 v[190:193], v151 offset:4096
	ds_read_b128 v[194:197], v151 offset:5120
	ds_read_b128 v[198:201], v151 offset:6144
	ds_read_b128 v[202:205], v151 offset:7168
	global_load_lds_dwordx4 v[140:141], off
	v_lshl_add_u64 v[140:141], s[8:9], 0, v[128:129]
	v_readfirstlane_b32 s8, v163
	v_lshl_add_u64 v[140:141], v[140:141], 0, s[22:23]
	s_mov_b32 m0, s8
	s_nop 0
	global_load_lds_dwordx4 v[140:141], off
	s_barrier
; #define STAGE_A(P, br, kt) do { const char* _base = (const char*)(((kt) < G.ksplit ? G.A1 : A2m) + (long)(br) * G.lda + (long)(kt) * BK); \
;     __builtin_amdgcn_global_load_lds((const unsigned*)(_base + aoff0), (unsigned*)((char*)(P) + sb0), 16, 0, 0); \
;     __builtin_amdgcn_global_load_lds((const unsigned*)(_base + aoff1), (unsigned*)((char*)(P) + sb1), 16, 0, 0); } while (0)
; #define LDA(dst, b, h) for (int m = 0; m < 4; ++m) for (int k = 0; k < 2; ++k) \
;     dst[m][k] = *reinterpret_cast<const bf16x8*>(a_rd + ((b) * 2 + (h)) * (HT * 2) + m * 2048 + k * 1024)
; #define LDB(dst, b, h) for (int n = 0; n < 2; ++n) for (int k = 0; k < 2; ++k) \
;     dst[n][k] = *reinterpret_cast<const bf16x8*>(b_rd + ((b) * 2 + (h)) * (HT * 2) + n * 2048 + k * 1024)
; #define MMA(ai, bj, At_, Bt_) do { __builtin_amdgcn_s_setprio(1); \
;     for (int m = 0; m < 4; ++m) for (int n = 0; n < 2; ++n) for (int k = 0; k < 2; ++k) \
;       acc[ai][bj][m][n] = __builtin_amdgcn_mfma_f32_16x16x32_bf16(Bt_[n][k], At_[m][k], acc[ai][bj][m][n], 0, 0, 0); \
;     __builtin_amdgcn_s_setprio(0); } while (0)
; #define WAIT_V(n) asm volatile("s_waitcnt vmcnt(" #n ")" ::: "memory")
; #define WAIT_L(n) asm volatile("s_waitcnt lgkmcnt(" #n ")" ::: "memory")
; #define BAR __builtin_amdgcn_s_barrier()
;     ...
;   { LDB(B0, 0, 0); LDA(At, 0, 0); STAGE_A(SA(1, 1), brow + HALF, nt - 1);
;     BAR; WAIT_L(0); MMA(0, 0, At, B0); BAR;
;     LDB(B1, 0, 1); BAR; WAIT_L(0); MMA(0, 1, At, B1); BAR;
;     LDA(At, 0, 1); WAIT_V(4); BAR; WAIT_L(0); MMA(1, 0, At, B0); MMA(1, 1, At, B1); BAR; }
;   { LDB(B0, 1, 0); LDA(At, 1, 0); WAIT_V(2); BAR; WAIT_L(0); MMA(0, 0, At, B0); BAR;
	s_waitcnt lgkmcnt(0)
	s_setprio 1
	s_waitcnt lgkmcnt(0)
	v_mfma_f32_16x16x32_bf16 v[124:127], v[132:135], v[172:175], v[124:127]
	v_mfma_f32_16x16x32_bf16 v[120:123], v[164:167], v[172:175], v[120:123]
	v_mfma_f32_16x16x32_bf16 v[116:119], v[132:135], v[182:185], v[116:119]
	v_mfma_f32_16x16x32_bf16 v[112:115], v[164:167], v[182:185], v[112:115]
	v_mfma_f32_16x16x32_bf16 v[108:111], v[132:135], v[190:193], v[108:111]
	v_mfma_f32_16x16x32_bf16 v[104:107], v[164:167], v[190:193], v[104:107]
	v_mfma_f32_16x16x32_bf16 v[100:103], v[132:135], v[198:201], v[100:103]
	v_mfma_f32_16x16x32_bf16 v[96:99], v[164:167], v[198:201], v[96:99]
	v_mfma_f32_16x16x32_bf16 v[124:127], v[136:139], v[176:179], v[124:127]
	v_mfma_f32_16x16x32_bf16 v[120:123], v[168:171], v[176:179], v[120:123]
	v_mfma_f32_16x16x32_bf16 v[116:119], v[136:139], v[186:189], v[116:119]
	v_mfma_f32_16x16x32_bf16 v[112:115], v[168:171], v[186:189], v[112:115]
	v_mfma_f32_16x16x32_bf16 v[108:111], v[136:139], v[194:197], v[108:111]
	v_mfma_f32_16x16x32_bf16 v[104:107], v[168:171], v[194:197], v[104:107]
	s_setprio 2
	s_barrier
	v_mfma_f32_16x16x32_bf16 v[100:103], v[136:139], v[202:205], v[100:103]
	v_mfma_f32_16x16x32_bf16 v[96:99], v[168:171], v[202:205], v[96:99]
	s_setprio 0
	ds_read_b128 v[206:209], v155 offset:16384
	ds_read_b128 v[210:213], v155 offset:17408
	ds_read_b128 v[214:217], v155 offset:18432
	ds_read_b128 v[218:221], v155 offset:19456
	s_barrier
	s_waitcnt lgkmcnt(0)
	s_setprio 1
	s_waitcnt lgkmcnt(0)
	v_mfma_f32_16x16x32_bf16 v[92:95], v[206:209], v[172:175], v[92:95]
	v_mfma_f32_16x16x32_bf16 v[88:91], v[214:217], v[172:175], v[88:91]
	v_mfma_f32_16x16x32_bf16 v[84:87], v[206:209], v[182:185], v[84:87]
	v_mfma_f32_16x16x32_bf16 v[80:83], v[214:217], v[182:185], v[80:83]
	v_mfma_f32_16x16x32_bf16 v[76:79], v[206:209], v[190:193], v[76:79]
	v_mfma_f32_16x16x32_bf16 v[72:75], v[214:217], v[190:193], v[72:75]
	v_mfma_f32_16x16x32_bf16 v[68:71], v[206:209], v[198:201], v[68:71]
	v_mfma_f32_16x16x32_bf16 v[64:67], v[214:217], v[198:201], v[64:67]
	v_mfma_f32_16x16x32_bf16 v[92:95], v[210:213], v[176:179], v[92:95]
	v_mfma_f32_16x16x32_bf16 v[88:91], v[218:221], v[176:179], v[88:91]
	v_mfma_f32_16x16x32_bf16 v[84:87], v[210:213], v[186:189], v[84:87]
	v_mfma_f32_16x16x32_bf16 v[80:83], v[218:221], v[186:189], v[80:83]
	v_mfma_f32_16x16x32_bf16 v[76:79], v[210:213], v[194:197], v[76:79]
	v_mfma_f32_16x16x32_bf16 v[72:75], v[218:221], v[194:197], v[72:75]
	s_setprio 2
	s_barrier
	v_mfma_f32_16x16x32_bf16 v[68:71], v[210:213], v[202:205], v[68:71]
	v_mfma_f32_16x16x32_bf16 v[64:67], v[218:221], v[202:205], v[64:67]
	s_setprio 0
	ds_read_b128 v[172:175], v151 offset:16384
	ds_read_b128 v[176:179], v151 offset:17408
	ds_read_b128 v[182:185], v151 offset:18432
	ds_read_b128 v[186:189], v151 offset:19456
	ds_read_b128 v[190:193], v151 offset:20480
	ds_read_b128 v[194:197], v151 offset:21504
	ds_read_b128 v[198:201], v151 offset:22528
	ds_read_b128 v[202:205], v151 offset:23552
	s_waitcnt vmcnt(4)
	s_barrier
	s_waitcnt lgkmcnt(0)
	s_setprio 1
	s_waitcnt lgkmcnt(0)
	v_mfma_f32_16x16x32_bf16 v[60:63], v[132:135], v[172:175], v[60:63]
	v_mfma_f32_16x16x32_bf16 v[56:59], v[164:167], v[172:175], v[56:59]
	v_mfma_f32_16x16x32_bf16 v[52:55], v[132:135], v[182:185], v[52:55]
	v_mfma_f32_16x16x32_bf16 v[48:51], v[164:167], v[182:185], v[48:51]
	v_mfma_f32_16x16x32_bf16 v[44:47], v[132:135], v[190:193], v[44:47]
	v_mfma_f32_16x16x32_bf16 v[40:43], v[164:167], v[190:193], v[40:43]
	v_mfma_f32_16x16x32_bf16 v[36:39], v[132:135], v[198:201], v[36:39]
	v_mfma_f32_16x16x32_bf16 v[32:35], v[164:167], v[198:201], v[32:35]
	v_mfma_f32_16x16x32_bf16 v[60:63], v[136:139], v[176:179], v[60:63]
	v_mfma_f32_16x16x32_bf16 v[56:59], v[168:171], v[176:179], v[56:59]
	v_mfma_f32_16x16x32_bf16 v[52:55], v[136:139], v[186:189], v[52:55]
	v_mfma_f32_16x16x32_bf16 v[48:51], v[168:171], v[186:189], v[48:51]
	v_mfma_f32_16x16x32_bf16 v[44:47], v[136:139], v[194:197], v[44:47]
	v_mfma_f32_16x16x32_bf16 v[40:43], v[168:171], v[194:197], v[40:43]
	v_mfma_f32_16x16x32_bf16 v[36:39], v[136:139], v[202:205], v[36:39]
	v_mfma_f32_16x16x32_bf16 v[32:35], v[168:171], v[202:205], v[32:35]
	s_setprio 0
	s_setprio 1
	v_mfma_f32_16x16x32_bf16 v[28:31], v[206:209], v[172:175], v[28:31]
	v_mfma_f32_16x16x32_bf16 v[24:27], v[214:217], v[172:175], v[24:27]
	v_mfma_f32_16x16x32_bf16 v[20:23], v[206:209], v[182:185], v[20:23]
	v_mfma_f32_16x16x32_bf16 v[16:19], v[214:217], v[182:185], v[16:19]
	v_mfma_f32_16x16x32_bf16 v[12:15], v[206:209], v[190:193], v[12:15]
	v_mfma_f32_16x16x32_bf16 v[8:11], v[214:217], v[190:193], v[8:11]
	v_mfma_f32_16x16x32_bf16 v[4:7], v[206:209], v[198:201], v[4:7]
	v_mfma_f32_16x16x32_bf16 v[0:3], v[214:217], v[198:201], v[0:3]
	v_mfma_f32_16x16x32_bf16 v[28:31], v[210:213], v[176:179], v[28:31]
	v_mfma_f32_16x16x32_bf16 v[24:27], v[218:221], v[176:179], v[24:27]
	v_mfma_f32_16x16x32_bf16 v[20:23], v[210:213], v[186:189], v[20:23]
	v_mfma_f32_16x16x32_bf16 v[16:19], v[218:221], v[186:189], v[16:19]
	v_mfma_f32_16x16x32_bf16 v[12:15], v[210:213], v[194:197], v[12:15]
	v_mfma_f32_16x16x32_bf16 v[8:11], v[218:221], v[194:197], v[8:11]
	s_setprio 2
	s_barrier
	v_mfma_f32_16x16x32_bf16 v[4:7], v[210:213], v[202:205], v[4:7]
	v_mfma_f32_16x16x32_bf16 v[0:3], v[218:221], v[202:205], v[0:3]
	s_setprio 0
	ds_read_b128 v[132:135], v155 offset:32768
	ds_read_b128 v[136:139], v155 offset:33792
	ds_read_b128 v[162:165], v155 offset:34816
	ds_read_b128 v[166:169], v155 offset:35840
	ds_read_b128 v[170:173], v151 offset:32768
	ds_read_b128 v[174:177], v151 offset:33792
	ds_read_b128 v[182:185], v151 offset:34816
	ds_read_b128 v[186:189], v151 offset:35840
	ds_read_b128 v[190:193], v151 offset:36864
	ds_read_b128 v[194:197], v151 offset:37888
	ds_read_b128 v[198:201], v151 offset:38912
	ds_read_b128 v[202:205], v151 offset:39936
	s_waitcnt vmcnt(2)
	s_barrier
; #define LDA(dst, b, h) for (int m = 0; m < 4; ++m) for (int k = 0; k < 2; ++k) \
;     dst[m][k] = *reinterpret_cast<const bf16x8*>(a_rd + ((b) * 2 + (h)) * (HT * 2) + m * 2048 + k * 1024)
; #define LDB(dst, b, h) for (int n = 0; n < 2; ++n) for (int k = 0; k < 2; ++k) \
;     dst[n][k] = *reinterpret_cast<const bf16x8*>(b_rd + ((b) * 2 + (h)) * (HT * 2) + n * 2048 + k * 1024)
; #define MMA(ai, bj, At_, Bt_) do { __builtin_amdgcn_s_setprio(1); \
;     for (int m = 0; m < 4; ++m) for (int n = 0; n < 2; ++n) for (int k = 0; k < 2; ++k) \
;       acc[ai][bj][m][n] = __builtin_amdgcn_mfma_f32_16x16x32_bf16(Bt_[n][k], At_[m][k], acc[ai][bj][m][n], 0, 0, 0); \
;     __builtin_amdgcn_s_setprio(0); } while (0)
; #define WAIT_V(n) asm volatile("s_waitcnt vmcnt(" #n ")" ::: "memory")
; #define WAIT_L(n) asm volatile("s_waitcnt lgkmcnt(" #n ")" ::: "memory")
; #define BAR __builtin_amdgcn_s_barrier()
;     ...
;   { LDB(B0, 1, 0); LDA(At, 1, 0); WAIT_V(2); BAR; WAIT_L(0); MMA(0, 0, At, B0); BAR;
;     LDB(B1, 1, 1); WAIT_V(0); BAR; WAIT_L(0); MMA(0, 1, At, B1); BAR;
;     LDA(At, 1, 1); BAR; WAIT_L(0); MMA(1, 0, At, B0); MMA(1, 1, At, B1); BAR; }
;   if (wr == 0) BAR;
	s_waitcnt lgkmcnt(0)
	s_setprio 1
	s_waitcnt lgkmcnt(0)
	v_mfma_f32_16x16x32_bf16 v[124:127], v[132:135], v[170:173], v[124:127]
	v_mfma_f32_16x16x32_bf16 v[120:123], v[162:165], v[170:173], v[120:123]
	v_mfma_f32_16x16x32_bf16 v[116:119], v[132:135], v[182:185], v[116:119]
	v_mfma_f32_16x16x32_bf16 v[112:115], v[162:165], v[182:185], v[112:115]
	v_mfma_f32_16x16x32_bf16 v[108:111], v[132:135], v[190:193], v[108:111]
	v_mfma_f32_16x16x32_bf16 v[104:107], v[162:165], v[190:193], v[104:107]
	v_mfma_f32_16x16x32_bf16 v[100:103], v[132:135], v[198:201], v[100:103]
	v_mfma_f32_16x16x32_bf16 v[96:99], v[162:165], v[198:201], v[96:99]
	v_mfma_f32_16x16x32_bf16 v[124:127], v[136:139], v[174:177], v[124:127]
	v_mfma_f32_16x16x32_bf16 v[120:123], v[166:169], v[174:177], v[120:123]
	v_mfma_f32_16x16x32_bf16 v[116:119], v[136:139], v[186:189], v[116:119]
	v_mfma_f32_16x16x32_bf16 v[112:115], v[166:169], v[186:189], v[112:115]
	v_mfma_f32_16x16x32_bf16 v[108:111], v[136:139], v[194:197], v[108:111]
	v_mfma_f32_16x16x32_bf16 v[104:107], v[166:169], v[194:197], v[104:107]
	s_setprio 2
	s_barrier
	v_mfma_f32_16x16x32_bf16 v[100:103], v[136:139], v[202:205], v[100:103]
	v_mfma_f32_16x16x32_bf16 v[96:99], v[166:169], v[202:205], v[96:99]
	s_setprio 0
	ds_read_b128 v[206:209], v155 offset:49152
	ds_read_b128 v[210:213], v155 offset:50176
	ds_read_b128 v[214:217], v155 offset:51200
	ds_read_b128 v[218:221], v155 offset:52224
	s_waitcnt vmcnt(0)
	s_barrier
	s_waitcnt lgkmcnt(0)
	s_setprio 1
	s_waitcnt lgkmcnt(0)
	v_mfma_f32_16x16x32_bf16 v[92:95], v[206:209], v[170:173], v[92:95]
	v_mfma_f32_16x16x32_bf16 v[88:91], v[214:217], v[170:173], v[88:91]
	v_mfma_f32_16x16x32_bf16 v[84:87], v[206:209], v[182:185], v[84:87]
	v_mfma_f32_16x16x32_bf16 v[80:83], v[214:217], v[182:185], v[80:83]
	v_mfma_f32_16x16x32_bf16 v[76:79], v[206:209], v[190:193], v[76:79]
	v_mfma_f32_16x16x32_bf16 v[72:75], v[214:217], v[190:193], v[72:75]
	v_mfma_f32_16x16x32_bf16 v[68:71], v[206:209], v[198:201], v[68:71]
	v_mfma_f32_16x16x32_bf16 v[64:67], v[214:217], v[198:201], v[64:67]
	v_mfma_f32_16x16x32_bf16 v[92:95], v[210:213], v[174:177], v[92:95]
	v_mfma_f32_16x16x32_bf16 v[88:91], v[218:221], v[174:177], v[88:91]
	v_mfma_f32_16x16x32_bf16 v[84:87], v[210:213], v[186:189], v[84:87]
	v_mfma_f32_16x16x32_bf16 v[80:83], v[218:221], v[186:189], v[80:83]
	v_mfma_f32_16x16x32_bf16 v[76:79], v[210:213], v[194:197], v[76:79]
	v_mfma_f32_16x16x32_bf16 v[72:75], v[218:221], v[194:197], v[72:75]
	s_setprio 2
	s_barrier
	v_mfma_f32_16x16x32_bf16 v[68:71], v[210:213], v[202:205], v[68:71]
	v_mfma_f32_16x16x32_bf16 v[64:67], v[218:221], v[202:205], v[64:67]
	s_setprio 0
	ds_read_b128 v[170:173], v151 offset:49152
	ds_read_b128 v[174:177], v151 offset:50176
	ds_read_b128 v[182:185], v151 offset:51200
	ds_read_b128 v[186:189], v151 offset:52224
	ds_read_b128 v[190:193], v151 offset:53248
	ds_read_b128 v[194:197], v151 offset:54272
	ds_read_b128 v[198:201], v151 offset:55296
	ds_read_b128 v[202:205], v151 offset:56320
	s_barrier
	s_waitcnt lgkmcnt(0)
	s_setprio 1
	s_waitcnt lgkmcnt(0)
	v_mfma_f32_16x16x32_bf16 v[60:63], v[132:135], v[170:173], v[60:63]
	v_mfma_f32_16x16x32_bf16 v[56:59], v[162:165], v[170:173], v[56:59]
	v_mfma_f32_16x16x32_bf16 v[52:55], v[132:135], v[182:185], v[52:55]
	v_mfma_f32_16x16x32_bf16 v[48:51], v[162:165], v[182:185], v[48:51]
	v_mfma_f32_16x16x32_bf16 v[44:47], v[132:135], v[190:193], v[44:47]
	v_mfma_f32_16x16x32_bf16 v[40:43], v[162:165], v[190:193], v[40:43]
	v_mfma_f32_16x16x32_bf16 v[36:39], v[132:135], v[198:201], v[36:39]
	v_mfma_f32_16x16x32_bf16 v[32:35], v[162:165], v[198:201], v[32:35]
	v_mfma_f32_16x16x32_bf16 v[60:63], v[136:139], v[174:177], v[60:63]
	v_mfma_f32_16x16x32_bf16 v[56:59], v[166:169], v[174:177], v[56:59]
	v_mfma_f32_16x16x32_bf16 v[52:55], v[136:139], v[186:189], v[52:55]
	v_mfma_f32_16x16x32_bf16 v[48:51], v[166:169], v[186:189], v[48:51]
	v_mfma_f32_16x16x32_bf16 v[44:47], v[136:139], v[194:197], v[44:47]
	v_mfma_f32_16x16x32_bf16 v[40:43], v[166:169], v[194:197], v[40:43]
	v_mfma_f32_16x16x32_bf16 v[36:39], v[136:139], v[202:205], v[36:39]
	v_mfma_f32_16x16x32_bf16 v[32:35], v[166:169], v[202:205], v[32:35]
	s_setprio 0
	s_setprio 1
	v_mfma_f32_16x16x32_bf16 v[28:31], v[206:209], v[170:173], v[28:31]
	v_mfma_f32_16x16x32_bf16 v[24:27], v[214:217], v[170:173], v[24:27]
	v_mfma_f32_16x16x32_bf16 v[20:23], v[206:209], v[182:185], v[20:23]
	v_mfma_f32_16x16x32_bf16 v[16:19], v[214:217], v[182:185], v[16:19]
	v_mfma_f32_16x16x32_bf16 v[12:15], v[206:209], v[190:193], v[12:15]
	v_mfma_f32_16x16x32_bf16 v[8:11], v[214:217], v[190:193], v[8:11]
	v_mfma_f32_16x16x32_bf16 v[4:7], v[206:209], v[198:201], v[4:7]
	v_mfma_f32_16x16x32_bf16 v[0:3], v[214:217], v[198:201], v[0:3]
	v_mfma_f32_16x16x32_bf16 v[28:31], v[210:213], v[174:177], v[28:31]
	v_mfma_f32_16x16x32_bf16 v[24:27], v[218:221], v[174:177], v[24:27]
	v_mfma_f32_16x16x32_bf16 v[20:23], v[210:213], v[186:189], v[20:23]
	v_mfma_f32_16x16x32_bf16 v[16:19], v[218:221], v[186:189], v[16:19]
	v_mfma_f32_16x16x32_bf16 v[12:15], v[210:213], v[194:197], v[12:15]
	v_mfma_f32_16x16x32_bf16 v[8:11], v[218:221], v[194:197], v[8:11]
	s_setprio 2
	s_barrier
	v_mfma_f32_16x16x32_bf16 v[4:7], v[210:213], v[202:205], v[4:7]
	v_mfma_f32_16x16x32_bf16 v[0:3], v[218:221], v[202:205], v[0:3]
	s_setprio 0
	v_cmp_gt_u32_e32 vcc, s60, v144
	s_and_saveexec_b64 s[8:9], vcc
	s_cbranch_execz .LBB0_749
	s_barrier

; #define STAGE_A(P, br, kt) do { const char* _base = (const char*)(((kt) < G.ksplit ? G.A1 : A2m) + (long)(br) * G.lda + (long)(kt) * BK); \
;     __builtin_amdgcn_global_load_lds((const unsigned*)(_base + aoff0), (unsigned*)((char*)(P) + sb0), 16, 0, 0); \
;     __builtin_amdgcn_global_load_lds((const unsigned*)(_base + aoff1), (unsigned*)((char*)(P) + sb1), 16, 0, 0); } while (0)
; #define STAGE_B(P, br, kt) do { const char* _base = (const char*)(G.Bt + (long)(br) * G.ldb + (long)(kt) * BK); \
;     __builtin_amdgcn_global_load_lds((const unsigned*)(_base + boff0), (unsigned*)((char*)(P) + sb0), 16, 0, 0); \
;     __builtin_amdgcn_global_load_lds((const unsigned*)(_base + boff1), (unsigned*)((char*)(P) + sb1), 16, 0, 0); } while (0)
; #define LDA(dst, b, h) for (int m = 0; m < 4; ++m) for (int k = 0; k < 2; ++k) \
;     dst[m][k] = *reinterpret_cast<const bf16x8*>(a_rd + ((b) * 2 + (h)) * (HT * 2) + m * 2048 + k * 1024)
; #define LDB(dst, b, h) for (int n = 0; n < 2; ++n) for (int k = 0; k < 2; ++k) \
;     dst[n][k] = *reinterpret_cast<const bf16x8*>(b_rd + ((b) * 2 + (h)) * (HT * 2) + n * 2048 + k * 1024)
; #define MMA(ai, bj, At_, Bt_) do { __builtin_amdgcn_s_setprio(1); \
;     for (int m = 0; m < 4; ++m) for (int n = 0; n < 2; ++n) for (int k = 0; k < 2; ++k) \
;       acc[ai][bj][m][n] = __builtin_amdgcn_mfma_f32_16x16x32_bf16(Bt_[n][k], At_[m][k], acc[ai][bj][m][n], 0, 0, 0); \
;     __builtin_amdgcn_s_setprio(0); } while (0)
; #define WAIT_V(n) asm volatile("s_waitcnt vmcnt(" #n ")" ::: "memory")
; #define WAIT_L(n) asm volatile("s_waitcnt lgkmcnt(" #n ")" ::: "memory")
; #define BAR __builtin_amdgcn_s_barrier()
; #define SCHED __builtin_amdgcn_sched_barrier(0)
;     ...
;     LDB(B0, 0, 0); SCHED; LDA(At, 0, 0); STAGE_A(SA(1, 1), brow + HALF, t + 1);
;     WAIT_L(8); BAR; WAIT_L(0); MMA(0, 0, At, B0); BAR; SCHED;
;     LDB(B1, 0, 1); STAGE_B(SB(0, 0), bcol, t + 2);
;     BAR; WAIT_L(0); MMA(0, 1, At, B1); BAR;
;     LDA(At, 0, 1); STAGE_A(SA(0, 0), brow, t + 2);
;     BAR; WAIT_L(0); MMA(1, 0, At, B0); BAR; SCHED;
;     STAGE_B(SB(0, 1), bcol + HALF, t + 2);
;     WAIT_V(6); BAR; MMA(1, 1, At, B1); BAR;
;     LDB(B0, 1, 0); SCHED; LDA(At, 1, 0); STAGE_A(SA(0, 1), brow + HALF, t + 2);
.LBB0_1801:
	ds_read_b128 v[162:165], v149
	ds_read_b128 v[166:169], v149 offset:1024
	ds_read_b128 v[170:173], v149 offset:2048
	ds_read_b128 v[174:177], v149 offset:3072
	s_add_i32 s24, s24, 2
	s_cmp_lt_u32 s24, 16
	s_cselect_b32 s27, s30, s36
	s_cselect_b32 s26, s29, s35
	v_lshl_add_u64 v[160:161], s[26:27], 0, v[136:137]
	v_add_u32_e32 v159, 0xc000, v147
	v_lshl_add_u64 v[160:161], v[160:161], 0, s[10:11]
	v_readfirstlane_b32 s25, v159
	v_lshl_add_u64 v[160:161], v[160:161], 0, s[38:39]
	s_mov_b32 m0, s25
	ds_read_b128 v[182:185], v146
	ds_read_b128 v[186:189], v146 offset:1024
	ds_read_b128 v[190:193], v146 offset:2048
	ds_read_b128 v[194:197], v146 offset:3072
	ds_read_b128 v[198:201], v146 offset:4096
	ds_read_b128 v[202:205], v146 offset:5120
	ds_read_b128 v[206:209], v146 offset:6144
	ds_read_b128 v[210:213], v146 offset:7168
	global_load_lds_dwordx4 v[160:161], off
	v_lshl_add_u64 v[160:161], s[26:27], 0, v[138:139]
	v_lshl_add_u64 v[160:161], v[160:161], 0, s[10:11]
	v_lshl_add_u64 v[178:179], v[160:161], 0, s[38:39]
	v_add_u32_e32 v160, 0xe000, v147
	s_nop 0
	v_readfirstlane_b32 s25, v160
	s_mov_b32 m0, s25
	s_nop 0
	global_load_lds_dwordx4 v[178:179], off
	ds_read_b128 v[214:217], v149 offset:16384
	ds_read_b128 v[218:221], v149 offset:17408
	ds_read_b128 v[230:233], v149 offset:18432
	ds_read_b128 v[238:241], v149 offset:19456
	s_waitcnt lgkmcnt(0)
	s_waitcnt vmcnt(8)
	s_barrier
	s_setprio 1
	v_mfma_f32_16x16x32_bf16 v[124:127], v[162:165], v[182:185], v[124:127]
	v_mfma_f32_16x16x32_bf16 v[120:123], v[170:173], v[182:185], v[120:123]
	v_mfma_f32_16x16x32_bf16 v[116:119], v[162:165], v[190:193], v[116:119]
	v_mfma_f32_16x16x32_bf16 v[112:115], v[170:173], v[190:193], v[112:115]
	v_mfma_f32_16x16x32_bf16 v[108:111], v[162:165], v[198:201], v[108:111]
	v_mfma_f32_16x16x32_bf16 v[104:107], v[170:173], v[198:201], v[104:107]
	v_mfma_f32_16x16x32_bf16 v[100:103], v[162:165], v[206:209], v[100:103]
	v_mfma_f32_16x16x32_bf16 v[96:99], v[170:173], v[206:209], v[96:99]
	v_mfma_f32_16x16x32_bf16 v[124:127], v[166:169], v[186:189], v[124:127]
	v_mfma_f32_16x16x32_bf16 v[120:123], v[174:177], v[186:189], v[120:123]
	v_mfma_f32_16x16x32_bf16 v[116:119], v[166:169], v[194:197], v[116:119]
	v_mfma_f32_16x16x32_bf16 v[112:115], v[174:177], v[194:197], v[112:115]
	v_mfma_f32_16x16x32_bf16 v[108:111], v[166:169], v[202:205], v[108:111]
	v_mfma_f32_16x16x32_bf16 v[104:107], v[174:177], v[202:205], v[104:107]
	v_mfma_f32_16x16x32_bf16 v[100:103], v[166:169], v[210:213], v[100:103]
	v_mfma_f32_16x16x32_bf16 v[96:99], v[174:177], v[210:213], v[96:99]
	v_mfma_f32_16x16x32_bf16 v[92:95], v[214:217], v[182:185], v[92:95]
	v_mfma_f32_16x16x32_bf16 v[88:91], v[230:233], v[182:185], v[88:91]
	v_mfma_f32_16x16x32_bf16 v[84:87], v[214:217], v[190:193], v[84:87]
	v_mfma_f32_16x16x32_bf16 v[80:83], v[230:233], v[190:193], v[80:83]
	v_mfma_f32_16x16x32_bf16 v[76:79], v[214:217], v[198:201], v[76:79]
	v_mfma_f32_16x16x32_bf16 v[72:75], v[230:233], v[198:201], v[72:75]
	v_mfma_f32_16x16x32_bf16 v[68:71], v[214:217], v[206:209], v[68:71]
	v_mfma_f32_16x16x32_bf16 v[64:67], v[230:233], v[206:209], v[64:67]
	v_mfma_f32_16x16x32_bf16 v[92:95], v[218:221], v[186:189], v[92:95]
	v_mfma_f32_16x16x32_bf16 v[88:91], v[238:241], v[186:189], v[88:91]
	v_mfma_f32_16x16x32_bf16 v[84:87], v[218:221], v[194:197], v[84:87]
	v_mfma_f32_16x16x32_bf16 v[80:83], v[238:241], v[194:197], v[80:83]
	v_mfma_f32_16x16x32_bf16 v[76:79], v[218:221], v[202:205], v[76:79]
	v_mfma_f32_16x16x32_bf16 v[72:75], v[238:241], v[202:205], v[72:75]
	s_setprio 2
	s_barrier
	v_mfma_f32_16x16x32_bf16 v[68:71], v[218:221], v[210:213], v[68:71]
	v_mfma_f32_16x16x32_bf16 v[64:67], v[238:241], v[210:213], v[64:67]
	s_setprio 0
	v_lshl_add_u64 v[178:179], v[132:133], 0, s[10:11]
	v_readfirstlane_b32 s25, v145
	v_lshl_add_u64 v[222:223], v[178:179], 0, s[40:41]
	s_mov_b32 m0, s25
	v_add_u32_e32 v161, 0x2000, v145
	global_load_lds_dwordx4 v[222:223], off
	v_lshl_add_u64 v[222:223], v[134:135], 0, s[10:11]
	v_readfirstlane_b32 s25, v161
	v_lshl_add_u64 v[226:227], v[222:223], 0, s[40:41]
	s_mov_b32 m0, s25
	s_nop 0
	global_load_lds_dwordx4 v[226:227], off
	s_cmp_lt_u32 s24, 14
	s_cselect_b32 s27, s30, s36
	s_cselect_b32 s26, s29, s35
	v_lshl_add_u64 v[226:227], s[26:27], 0, v[136:137]
	v_lshl_add_u64 v[226:227], v[226:227], 0, s[10:11]
	v_readfirstlane_b32 s25, v147
	v_lshl_add_u64 v[234:235], v[226:227], 0, s[90:91]
	s_mov_b32 m0, s25
	ds_read_b128 v[182:185], v146 offset:16384
	ds_read_b128 v[186:189], v146 offset:17408
	ds_read_b128 v[190:193], v146 offset:18432
	ds_read_b128 v[194:197], v146 offset:19456
	ds_read_b128 v[198:201], v146 offset:20480
	ds_read_b128 v[202:205], v146 offset:21504
	ds_read_b128 v[206:209], v146 offset:22528
	ds_read_b128 v[210:213], v146 offset:23552
	global_load_lds_dwordx4 v[234:235], off
	v_lshl_add_u64 v[234:235], s[26:27], 0, v[138:139]
	v_lshl_add_u64 v[234:235], v[234:235], 0, s[10:11]
	v_readfirstlane_b32 s25, v148
	v_lshl_add_u64 v[236:237], v[234:235], 0, s[90:91]
	s_mov_b32 m0, s25
	s_nop 0
	global_load_lds_dwordx4 v[236:237], off
	v_lshl_add_u64 v[236:237], v[140:141], 0, s[10:11]
	v_readfirstlane_b32 s25, v150
	v_add_u32_e32 v161, 0x2000, v150
	v_lshl_add_u64 v[250:251], v[236:237], 0, s[42:43]
	s_mov_b32 m0, s25
	v_lshl_add_u64 v[246:247], v[142:143], 0, s[10:11]
	v_readfirstlane_b32 s25, v161
	global_load_lds_dwordx4 v[250:251], off
	v_lshl_add_u64 v[250:251], v[246:247], 0, s[42:43]
	s_mov_b32 m0, s25
	s_nop 0
	global_load_lds_dwordx4 v[250:251], off
	s_waitcnt lgkmcnt(0)
	s_waitcnt vmcnt(8)
	s_barrier
; #define STAGE_A(P, br, kt) do { const char* _base = (const char*)(((kt) < G.ksplit ? G.A1 : A2m) + (long)(br) * G.lda + (long)(kt) * BK); \
;     __builtin_amdgcn_global_load_lds((const unsigned*)(_base + aoff0), (unsigned*)((char*)(P) + sb0), 16, 0, 0); \
;     __builtin_amdgcn_global_load_lds((const unsigned*)(_base + aoff1), (unsigned*)((char*)(P) + sb1), 16, 0, 0); } while (0)
; #define STAGE_B(P, br, kt) do { const char* _base = (const char*)(G.Bt + (long)(br) * G.ldb + (long)(kt) * BK); \
;     __builtin_amdgcn_global_load_lds((const unsigned*)(_base + boff0), (unsigned*)((char*)(P) + sb0), 16, 0, 0); \
;     __builtin_amdgcn_global_load_lds((const unsigned*)(_base + boff1), (unsigned*)((char*)(P) + sb1), 16, 0, 0); } while (0)
; #define LDA(dst, b, h) for (int m = 0; m < 4; ++m) for (int k = 0; k < 2; ++k) \
;     dst[m][k] = *reinterpret_cast<const bf16x8*>(a_rd + ((b) * 2 + (h)) * (HT * 2) + m * 2048 + k * 1024)
; #define LDB(dst, b, h) for (int n = 0; n < 2; ++n) for (int k = 0; k < 2; ++k) \
;     dst[n][k] = *reinterpret_cast<const bf16x8*>(b_rd + ((b) * 2 + (h)) * (HT * 2) + n * 2048 + k * 1024)
; #define MMA(ai, bj, At_, Bt_) do { __builtin_amdgcn_s_setprio(1); \
;     for (int m = 0; m < 4; ++m) for (int n = 0; n < 2; ++n) for (int k = 0; k < 2; ++k) \
;       acc[ai][bj][m][n] = __builtin_amdgcn_mfma_f32_16x16x32_bf16(Bt_[n][k], At_[m][k], acc[ai][bj][m][n], 0, 0, 0); \
;     __builtin_amdgcn_s_setprio(0); } while (0)
; #define WAIT_V(n) asm volatile("s_waitcnt vmcnt(" #n ")" ::: "memory")
; #define WAIT_L(n) asm volatile("s_waitcnt lgkmcnt(" #n ")" ::: "memory")
; #define BAR __builtin_amdgcn_s_barrier()
; #define SCHED __builtin_amdgcn_sched_barrier(0)
;     ...
;     LDA(At, 0, 1); STAGE_A(SA(0, 0), brow, t + 2);
;     BAR; WAIT_L(0); MMA(1, 0, At, B0); BAR; SCHED;
;     STAGE_B(SB(0, 1), bcol + HALF, t + 2);
;     WAIT_V(6); BAR; MMA(1, 1, At, B1); BAR;
;     LDB(B0, 1, 0); SCHED; LDA(At, 1, 0); STAGE_A(SA(0, 1), brow + HALF, t + 2);
;     WAIT_L(8); BAR; WAIT_L(0); MMA(0, 0, At, B0); BAR; SCHED;
;     LDB(B1, 1, 1); STAGE_B(SB(1, 0), bcol, t + 3);
;     BAR; WAIT_L(0); MMA(0, 1, At, B1); BAR;
;     LDA(At, 1, 1); STAGE_A(SA(1, 0), brow, t + 3);
;     BAR; WAIT_L(0); MMA(1, 0, At, B0); BAR; SCHED;
	s_setprio 1
	v_mfma_f32_16x16x32_bf16 v[60:63], v[162:165], v[182:185], v[60:63]
	v_mfma_f32_16x16x32_bf16 v[56:59], v[170:173], v[182:185], v[56:59]
	v_mfma_f32_16x16x32_bf16 v[52:55], v[162:165], v[190:193], v[52:55]
	v_mfma_f32_16x16x32_bf16 v[48:51], v[170:173], v[190:193], v[48:51]
	v_mfma_f32_16x16x32_bf16 v[44:47], v[162:165], v[198:201], v[44:47]
	v_mfma_f32_16x16x32_bf16 v[40:43], v[170:173], v[198:201], v[40:43]
	v_mfma_f32_16x16x32_bf16 v[36:39], v[162:165], v[206:209], v[36:39]
	v_mfma_f32_16x16x32_bf16 v[32:35], v[170:173], v[206:209], v[32:35]
	v_mfma_f32_16x16x32_bf16 v[60:63], v[166:169], v[186:189], v[60:63]
	v_mfma_f32_16x16x32_bf16 v[56:59], v[174:177], v[186:189], v[56:59]
	v_mfma_f32_16x16x32_bf16 v[52:55], v[166:169], v[194:197], v[52:55]
	v_mfma_f32_16x16x32_bf16 v[48:51], v[174:177], v[194:197], v[48:51]
	v_mfma_f32_16x16x32_bf16 v[44:47], v[166:169], v[202:205], v[44:47]
	v_mfma_f32_16x16x32_bf16 v[40:43], v[174:177], v[202:205], v[40:43]
	v_mfma_f32_16x16x32_bf16 v[36:39], v[166:169], v[210:213], v[36:39]
	v_mfma_f32_16x16x32_bf16 v[32:35], v[174:177], v[210:213], v[32:35]
	v_mfma_f32_16x16x32_bf16 v[28:31], v[214:217], v[182:185], v[28:31]
	v_mfma_f32_16x16x32_bf16 v[24:27], v[230:233], v[182:185], v[24:27]
	v_mfma_f32_16x16x32_bf16 v[20:23], v[214:217], v[190:193], v[20:23]
	v_mfma_f32_16x16x32_bf16 v[16:19], v[230:233], v[190:193], v[16:19]
	v_mfma_f32_16x16x32_bf16 v[12:15], v[214:217], v[198:201], v[12:15]
	v_mfma_f32_16x16x32_bf16 v[8:11], v[230:233], v[198:201], v[8:11]
	v_mfma_f32_16x16x32_bf16 v[4:7], v[214:217], v[206:209], v[4:7]
	v_mfma_f32_16x16x32_bf16 v[0:3], v[230:233], v[206:209], v[0:3]
	v_mfma_f32_16x16x32_bf16 v[28:31], v[218:221], v[186:189], v[28:31]
	v_mfma_f32_16x16x32_bf16 v[24:27], v[238:241], v[186:189], v[24:27]
	v_mfma_f32_16x16x32_bf16 v[20:23], v[218:221], v[194:197], v[20:23]
	v_mfma_f32_16x16x32_bf16 v[16:19], v[238:241], v[194:197], v[16:19]
	v_mfma_f32_16x16x32_bf16 v[12:15], v[218:221], v[202:205], v[12:15]
	v_mfma_f32_16x16x32_bf16 v[8:11], v[238:241], v[202:205], v[8:11]
	s_setprio 2
	s_barrier
	v_mfma_f32_16x16x32_bf16 v[4:7], v[218:221], v[210:213], v[4:7]
	v_mfma_f32_16x16x32_bf16 v[0:3], v[238:241], v[210:213], v[0:3]
	s_setprio 0
	ds_read_b128 v[162:165], v149 offset:32768
	ds_read_b128 v[166:169], v149 offset:33792
	ds_read_b128 v[170:173], v149 offset:34816
	ds_read_b128 v[174:177], v149 offset:35840
	v_readfirstlane_b32 s25, v151
	v_lshl_add_u64 v[214:215], v[226:227], 0, s[44:45]
	s_mov_b32 m0, s25
	v_readfirstlane_b32 s25, v152
	ds_read_b128 v[182:185], v146 offset:32768
	ds_read_b128 v[186:189], v146 offset:33792
	ds_read_b128 v[190:193], v146 offset:34816
	ds_read_b128 v[194:197], v146 offset:35840
	ds_read_b128 v[198:201], v146 offset:36864
	ds_read_b128 v[202:205], v146 offset:37888
	ds_read_b128 v[206:209], v146 offset:38912
	ds_read_b128 v[210:213], v146 offset:39936
	global_load_lds_dwordx4 v[214:215], off
	v_lshl_add_u64 v[214:215], v[234:235], 0, s[44:45]
	s_mov_b32 m0, s25
	s_nop 0
	global_load_lds_dwordx4 v[214:215], off
	ds_read_b128 v[214:217], v149 offset:49152
	ds_read_b128 v[218:221], v149 offset:50176
	ds_read_b128 v[230:233], v149 offset:51200
	ds_read_b128 v[238:241], v149 offset:52224
	s_waitcnt lgkmcnt(0)
	s_waitcnt vmcnt(8)
	s_barrier
	s_setprio 1
	v_mfma_f32_16x16x32_bf16 v[124:127], v[162:165], v[182:185], v[124:127]
	v_mfma_f32_16x16x32_bf16 v[120:123], v[170:173], v[182:185], v[120:123]
	v_mfma_f32_16x16x32_bf16 v[116:119], v[162:165], v[190:193], v[116:119]
	v_mfma_f32_16x16x32_bf16 v[112:115], v[170:173], v[190:193], v[112:115]
	v_mfma_f32_16x16x32_bf16 v[108:111], v[162:165], v[198:201], v[108:111]
	v_mfma_f32_16x16x32_bf16 v[104:107], v[170:173], v[198:201], v[104:107]
	v_mfma_f32_16x16x32_bf16 v[100:103], v[162:165], v[206:209], v[100:103]
	v_mfma_f32_16x16x32_bf16 v[96:99], v[170:173], v[206:209], v[96:99]
	v_mfma_f32_16x16x32_bf16 v[124:127], v[166:169], v[186:189], v[124:127]
	v_mfma_f32_16x16x32_bf16 v[120:123], v[174:177], v[186:189], v[120:123]
	v_mfma_f32_16x16x32_bf16 v[116:119], v[166:169], v[194:197], v[116:119]
	v_mfma_f32_16x16x32_bf16 v[112:115], v[174:177], v[194:197], v[112:115]
	v_mfma_f32_16x16x32_bf16 v[108:111], v[166:169], v[202:205], v[108:111]
	v_mfma_f32_16x16x32_bf16 v[104:107], v[174:177], v[202:205], v[104:107]
	v_mfma_f32_16x16x32_bf16 v[100:103], v[166:169], v[210:213], v[100:103]
	v_mfma_f32_16x16x32_bf16 v[96:99], v[174:177], v[210:213], v[96:99]
	v_mfma_f32_16x16x32_bf16 v[92:95], v[214:217], v[182:185], v[92:95]
	v_mfma_f32_16x16x32_bf16 v[88:91], v[230:233], v[182:185], v[88:91]
	v_mfma_f32_16x16x32_bf16 v[84:87], v[214:217], v[190:193], v[84:87]
	v_mfma_f32_16x16x32_bf16 v[80:83], v[230:233], v[190:193], v[80:83]
	v_mfma_f32_16x16x32_bf16 v[76:79], v[214:217], v[198:201], v[76:79]
	v_mfma_f32_16x16x32_bf16 v[72:75], v[230:233], v[198:201], v[72:75]
	v_mfma_f32_16x16x32_bf16 v[68:71], v[214:217], v[206:209], v[68:71]
	v_mfma_f32_16x16x32_bf16 v[64:67], v[230:233], v[206:209], v[64:67]
	v_mfma_f32_16x16x32_bf16 v[92:95], v[218:221], v[186:189], v[92:95]
	v_mfma_f32_16x16x32_bf16 v[88:91], v[238:241], v[186:189], v[88:91]
	v_mfma_f32_16x16x32_bf16 v[84:87], v[218:221], v[194:197], v[84:87]
	v_mfma_f32_16x16x32_bf16 v[80:83], v[238:241], v[194:197], v[80:83]
	v_mfma_f32_16x16x32_bf16 v[76:79], v[218:221], v[202:205], v[76:79]
	v_mfma_f32_16x16x32_bf16 v[72:75], v[238:241], v[202:205], v[72:75]
	s_setprio 2
	s_barrier
; #define STAGE_A(P, br, kt) do { const char* _base = (const char*)(((kt) < G.ksplit ? G.A1 : A2m) + (long)(br) * G.lda + (long)(kt) * BK); \
;     __builtin_amdgcn_global_load_lds((const unsigned*)(_base + aoff0), (unsigned*)((char*)(P) + sb0), 16, 0, 0); \
;     __builtin_amdgcn_global_load_lds((const unsigned*)(_base + aoff1), (unsigned*)((char*)(P) + sb1), 16, 0, 0); } while (0)
; #define STAGE_B(P, br, kt) do { const char* _base = (const char*)(G.Bt + (long)(br) * G.ldb + (long)(kt) * BK); \
;     __builtin_amdgcn_global_load_lds((const unsigned*)(_base + boff0), (unsigned*)((char*)(P) + sb0), 16, 0, 0); \
;     __builtin_amdgcn_global_load_lds((const unsigned*)(_base + boff1), (unsigned*)((char*)(P) + sb1), 16, 0, 0); } while (0)
; #define LDA(dst, b, h) for (int m = 0; m < 4; ++m) for (int k = 0; k < 2; ++k) \
;     dst[m][k] = *reinterpret_cast<const bf16x8*>(a_rd + ((b) * 2 + (h)) * (HT * 2) + m * 2048 + k * 1024)
; #define LDB(dst, b, h) for (int n = 0; n < 2; ++n) for (int k = 0; k < 2; ++k) \
;     dst[n][k] = *reinterpret_cast<const bf16x8*>(b_rd + ((b) * 2 + (h)) * (HT * 2) + n * 2048 + k * 1024)
; #define MMA(ai, bj, At_, Bt_) do { __builtin_amdgcn_s_setprio(1); \
;     for (int m = 0; m < 4; ++m) for (int n = 0; n < 2; ++n) for (int k = 0; k < 2; ++k) \
;       acc[ai][bj][m][n] = __builtin_amdgcn_mfma_f32_16x16x32_bf16(Bt_[n][k], At_[m][k], acc[ai][bj][m][n], 0, 0, 0); \
;     __builtin_amdgcn_s_setprio(0); } while (0)
; #define WAIT_V(n) asm volatile("s_waitcnt vmcnt(" #n ")" ::: "memory")
; #define WAIT_L(n) asm volatile("s_waitcnt lgkmcnt(" #n ")" ::: "memory")
; #define BAR __builtin_amdgcn_s_barrier()
; #define SCHED __builtin_amdgcn_sched_barrier(0)
;     ...
;     LDB(B1, 1, 1); STAGE_B(SB(1, 0), bcol, t + 3);
;     BAR; WAIT_L(0); MMA(0, 1, At, B1); BAR;
;     LDA(At, 1, 1); STAGE_A(SA(1, 0), brow, t + 3);
;     BAR; WAIT_L(0); MMA(1, 0, At, B0); BAR; SCHED;
;     STAGE_B(SB(1, 1), bcol + HALF, t + 3);
;     WAIT_V(6); BAR; MMA(1, 1, At, B1); BAR;
;   }
;   float ssv[2][4] = {};
;   if constexpr (EPI == EPI_GU || EPI == EPI_EVIN || EPI == EPI_ODIN) {
; #pragma unroll
;     for (int ai = 0; ai < 2; ++ai)
; #pragma unroll
;       for (int m = 0; m < 4; ++m) ssv[ai][m] = G.ssr[brow + ai * HALF + wr * 64 + m * 16 + fr];
;   }
;   { LDB(B0, 0, 0); LDA(At, 0, 0); STAGE_A(SA(1, 1), brow + HALF, nt - 1);
	v_mfma_f32_16x16x32_bf16 v[68:71], v[218:221], v[210:213], v[68:71]
	v_mfma_f32_16x16x32_bf16 v[64:67], v[238:241], v[210:213], v[64:67]
	s_setprio 0
	v_readfirstlane_b32 s25, v153
	v_lshl_add_u64 v[178:179], v[178:179], 0, s[46:47]
	s_mov_b32 m0, s25
	v_readfirstlane_b32 s25, v154
	global_load_lds_dwordx4 v[178:179], off
	v_lshl_add_u64 v[178:179], v[222:223], 0, s[46:47]
	s_mov_b32 m0, s25
	s_nop 0
	global_load_lds_dwordx4 v[178:179], off
	s_cmp_lt_u32 s24, 13
	s_cselect_b32 s27, s30, s36
	s_cselect_b32 s26, s29, s35
	v_lshl_add_u64 v[178:179], s[26:27], 0, v[136:137]
	v_lshl_add_u64 v[178:179], v[178:179], 0, s[10:11]
	v_readfirstlane_b32 s25, v155
	v_lshl_add_u64 v[178:179], v[178:179], 0, s[88:89]
	s_mov_b32 m0, s25
	ds_read_b128 v[182:185], v146 offset:49152
	ds_read_b128 v[186:189], v146 offset:50176
	ds_read_b128 v[190:193], v146 offset:51200
	ds_read_b128 v[194:197], v146 offset:52224
	ds_read_b128 v[198:201], v146 offset:53248
	ds_read_b128 v[202:205], v146 offset:54272
	ds_read_b128 v[206:209], v146 offset:55296
	ds_read_b128 v[210:213], v146 offset:56320
	global_load_lds_dwordx4 v[178:179], off
	v_lshl_add_u64 v[178:179], s[26:27], 0, v[138:139]
	v_lshl_add_u64 v[178:179], v[178:179], 0, s[10:11]
	v_readfirstlane_b32 s25, v156
	v_lshl_add_u64 v[178:179], v[178:179], 0, s[88:89]
	s_mov_b32 m0, s25
	s_nop 0
	global_load_lds_dwordx4 v[178:179], off
	v_readfirstlane_b32 s25, v157
	v_lshl_add_u64 v[250:251], v[236:237], 0, s[48:49]
	s_mov_b32 m0, s25
	v_readfirstlane_b32 s25, v158
	global_load_lds_dwordx4 v[250:251], off
	v_lshl_add_u64 v[250:251], v[246:247], 0, s[48:49]
	s_mov_b32 m0, s25
	s_nop 0
	global_load_lds_dwordx4 v[250:251], off
	s_waitcnt lgkmcnt(0)
	s_waitcnt vmcnt(8)
	s_barrier
	s_setprio 1
	v_mfma_f32_16x16x32_bf16 v[60:63], v[162:165], v[182:185], v[60:63]
	v_mfma_f32_16x16x32_bf16 v[56:59], v[170:173], v[182:185], v[56:59]
	v_mfma_f32_16x16x32_bf16 v[52:55], v[162:165], v[190:193], v[52:55]
	v_mfma_f32_16x16x32_bf16 v[48:51], v[170:173], v[190:193], v[48:51]
	v_mfma_f32_16x16x32_bf16 v[44:47], v[162:165], v[198:201], v[44:47]
	v_mfma_f32_16x16x32_bf16 v[40:43], v[170:173], v[198:201], v[40:43]
	v_mfma_f32_16x16x32_bf16 v[36:39], v[162:165], v[206:209], v[36:39]
	v_mfma_f32_16x16x32_bf16 v[32:35], v[170:173], v[206:209], v[32:35]
	v_mfma_f32_16x16x32_bf16 v[60:63], v[166:169], v[186:189], v[60:63]
	v_mfma_f32_16x16x32_bf16 v[56:59], v[174:177], v[186:189], v[56:59]
	v_mfma_f32_16x16x32_bf16 v[52:55], v[166:169], v[194:197], v[52:55]
	v_mfma_f32_16x16x32_bf16 v[48:51], v[174:177], v[194:197], v[48:51]
	v_mfma_f32_16x16x32_bf16 v[44:47], v[166:169], v[202:205], v[44:47]
	v_mfma_f32_16x16x32_bf16 v[40:43], v[174:177], v[202:205], v[40:43]
	v_mfma_f32_16x16x32_bf16 v[36:39], v[166:169], v[210:213], v[36:39]
	v_mfma_f32_16x16x32_bf16 v[32:35], v[174:177], v[210:213], v[32:35]
	v_mfma_f32_16x16x32_bf16 v[28:31], v[214:217], v[182:185], v[28:31]
	v_mfma_f32_16x16x32_bf16 v[24:27], v[230:233], v[182:185], v[24:27]
	v_mfma_f32_16x16x32_bf16 v[20:23], v[214:217], v[190:193], v[20:23]
	v_mfma_f32_16x16x32_bf16 v[16:19], v[230:233], v[190:193], v[16:19]
	v_mfma_f32_16x16x32_bf16 v[12:15], v[214:217], v[198:201], v[12:15]
	v_mfma_f32_16x16x32_bf16 v[8:11], v[230:233], v[198:201], v[8:11]
	v_mfma_f32_16x16x32_bf16 v[4:7], v[214:217], v[206:209], v[4:7]
	v_mfma_f32_16x16x32_bf16 v[0:3], v[230:233], v[206:209], v[0:3]
	v_mfma_f32_16x16x32_bf16 v[28:31], v[218:221], v[186:189], v[28:31]
	v_mfma_f32_16x16x32_bf16 v[24:27], v[238:241], v[186:189], v[24:27]
	v_mfma_f32_16x16x32_bf16 v[20:23], v[218:221], v[194:197], v[20:23]
	v_mfma_f32_16x16x32_bf16 v[16:19], v[238:241], v[194:197], v[16:19]
	v_mfma_f32_16x16x32_bf16 v[12:15], v[218:221], v[202:205], v[12:15]
	v_mfma_f32_16x16x32_bf16 v[8:11], v[238:241], v[202:205], v[8:11]
	s_setprio 2
	s_barrier
	v_mfma_f32_16x16x32_bf16 v[4:7], v[218:221], v[210:213], v[4:7]
	v_mfma_f32_16x16x32_bf16 v[0:3], v[238:241], v[210:213], v[0:3]
	s_setprio 0
	s_add_u32 s10, s10, 0x100
	s_addc_u32 s11, s11, 0
	s_cmp_lt_u32 s24, 28
	s_cbranch_scc1 .LBB0_1801
	s_waitcnt vmcnt(6)
	v_not_b32_e32 v250, 63
	v_mov_b32_e32 v251, 0x41b17218
	s_lshl_b64 s[8:9], s[8:9], 1
	s_add_u32 s8, s35, s8
	s_addc_u32 s9, s36, s9
	v_lshl_add_u64 v[130:131], s[8:9], 0, v[130:131]
	s_mov_b64 s[24:25], 0xf80
	v_readfirstlane_b32 s10, v159
	v_lshl_add_u64 v[130:131], v[130:131], 0, s[24:25]
	s_mov_b32 m0, s10
	v_lshl_add_u64 v[128:129], s[8:9], 0, v[128:129]
	v_readfirstlane_b32 s8, v160
	ds_read_b128 v[132:135], v149
	ds_read_b128 v[136:139], v149 offset:1024
	ds_read_b128 v[140:143], v149 offset:2048
	ds_read_b128 v[150:153], v149 offset:3072
	ds_read_b128 v[154:157], v146
	ds_read_b128 v[162:165], v146 offset:1024
	ds_read_b128 v[166:169], v146 offset:2048
	ds_read_b128 v[170:173], v146 offset:3072
	ds_read_b128 v[174:177], v146 offset:4096
	ds_read_b128 v[182:185], v146 offset:5120
	ds_read_b128 v[186:189], v146 offset:6144
	ds_read_b128 v[190:193], v146 offset:7168
	global_load_lds_dwordx4 v[130:131], off
	v_lshl_add_u64 v[128:129], v[128:129], 0, s[24:25]
	s_mov_b32 m0, s8
	s_nop 0
	global_load_lds_dwordx4 v[128:129], off
	s_barrier
; #define STAGE_A(P, br, kt) do { const char* _base = (const char*)(((kt) < G.ksplit ? G.A1 : A2m) + (long)(br) * G.lda + (long)(kt) * BK); \
;     __builtin_amdgcn_global_load_lds((const unsigned*)(_base + aoff0), (unsigned*)((char*)(P) + sb0), 16, 0, 0); \
;     __builtin_amdgcn_global_load_lds((const unsigned*)(_base + aoff1), (unsigned*)((char*)(P) + sb1), 16, 0, 0); } while (0)
; #define LDA(dst, b, h) for (int m = 0; m < 4; ++m) for (int k = 0; k < 2; ++k) \
;     dst[m][k] = *reinterpret_cast<const bf16x8*>(a_rd + ((b) * 2 + (h)) * (HT * 2) + m * 2048 + k * 1024)
; #define LDB(dst, b, h) for (int n = 0; n < 2; ++n) for (int k = 0; k < 2; ++k) \
;     dst[n][k] = *reinterpret_cast<const bf16x8*>(b_rd + ((b) * 2 + (h)) * (HT * 2) + n * 2048 + k * 1024)
; #define MMA(ai, bj, At_, Bt_) do { __builtin_amdgcn_s_setprio(1); \
;     for (int m = 0; m < 4; ++m) for (int n = 0; n < 2; ++n) for (int k = 0; k < 2; ++k) \
;       acc[ai][bj][m][n] = __builtin_amdgcn_mfma_f32_16x16x32_bf16(Bt_[n][k], At_[m][k], acc[ai][bj][m][n], 0, 0, 0); \
;     __builtin_amdgcn_s_setprio(0); } while (0)
; #define WAIT_V(n) asm volatile("s_waitcnt vmcnt(" #n ")" ::: "memory")
; #define WAIT_L(n) asm volatile("s_waitcnt lgkmcnt(" #n ")" ::: "memory")
; #define BAR __builtin_amdgcn_s_barrier()
;     ...
;   { LDB(B0, 0, 0); LDA(At, 0, 0); STAGE_A(SA(1, 1), brow + HALF, nt - 1);
;     BAR; WAIT_L(0); MMA(0, 0, At, B0); BAR;
;     LDB(B1, 0, 1); BAR; WAIT_L(0); MMA(0, 1, At, B1); BAR;
;     LDA(At, 0, 1); WAIT_V(4); BAR; WAIT_L(0); MMA(1, 0, At, B0); MMA(1, 1, At, B1); BAR; }
;   { LDB(B0, 1, 0); LDA(At, 1, 0); WAIT_V(2); BAR; WAIT_L(0); MMA(0, 0, At, B0); BAR;
	s_waitcnt lgkmcnt(0)
	s_setprio 1
	s_waitcnt lgkmcnt(0)
	v_mfma_f32_16x16x32_bf16 v[124:127], v[132:135], v[154:157], v[124:127]
	v_mfma_f32_16x16x32_bf16 v[120:123], v[140:143], v[154:157], v[120:123]
	v_mfma_f32_16x16x32_bf16 v[116:119], v[132:135], v[166:169], v[116:119]
	v_mfma_f32_16x16x32_bf16 v[112:115], v[140:143], v[166:169], v[112:115]
	v_mfma_f32_16x16x32_bf16 v[108:111], v[132:135], v[174:177], v[108:111]
	v_mfma_f32_16x16x32_bf16 v[104:107], v[140:143], v[174:177], v[104:107]
	v_mfma_f32_16x16x32_bf16 v[100:103], v[132:135], v[186:189], v[100:103]
	v_mfma_f32_16x16x32_bf16 v[96:99], v[140:143], v[186:189], v[96:99]
	v_mfma_f32_16x16x32_bf16 v[124:127], v[136:139], v[162:165], v[124:127]
	v_mfma_f32_16x16x32_bf16 v[120:123], v[150:153], v[162:165], v[120:123]
	v_mfma_f32_16x16x32_bf16 v[116:119], v[136:139], v[170:173], v[116:119]
	v_mfma_f32_16x16x32_bf16 v[112:115], v[150:153], v[170:173], v[112:115]
	v_mfma_f32_16x16x32_bf16 v[108:111], v[136:139], v[182:185], v[108:111]
	v_mfma_f32_16x16x32_bf16 v[104:107], v[150:153], v[182:185], v[104:107]
	s_setprio 2
	s_barrier
	v_mfma_f32_16x16x32_bf16 v[100:103], v[136:139], v[190:193], v[100:103]
	v_mfma_f32_16x16x32_bf16 v[96:99], v[150:153], v[190:193], v[96:99]
	s_setprio 0
	ds_read_b128 v[128:131], v149 offset:16384
	ds_read_b128 v[158:161], v149 offset:17408
	ds_read_b128 v[194:197], v149 offset:18432
	ds_read_b128 v[198:201], v149 offset:19456
	s_barrier
	s_waitcnt lgkmcnt(0)
	s_setprio 1
	s_waitcnt lgkmcnt(0)
	v_mfma_f32_16x16x32_bf16 v[92:95], v[128:131], v[154:157], v[92:95]
	v_mfma_f32_16x16x32_bf16 v[88:91], v[194:197], v[154:157], v[88:91]
	v_mfma_f32_16x16x32_bf16 v[84:87], v[128:131], v[166:169], v[84:87]
	v_mfma_f32_16x16x32_bf16 v[80:83], v[194:197], v[166:169], v[80:83]
	v_mfma_f32_16x16x32_bf16 v[76:79], v[128:131], v[174:177], v[76:79]
	v_mfma_f32_16x16x32_bf16 v[72:75], v[194:197], v[174:177], v[72:75]
	v_mfma_f32_16x16x32_bf16 v[68:71], v[128:131], v[186:189], v[68:71]
	v_mfma_f32_16x16x32_bf16 v[64:67], v[194:197], v[186:189], v[64:67]
	v_mfma_f32_16x16x32_bf16 v[202:205], v[158:161], v[162:165], v[92:95]
	v_mfma_f32_16x16x32_bf16 v[154:157], v[198:201], v[162:165], v[88:91]
	v_mfma_f32_16x16x32_bf16 v[162:165], v[158:161], v[170:173], v[84:87]
	v_mfma_f32_16x16x32_bf16 v[166:169], v[198:201], v[170:173], v[80:83]
	v_mfma_f32_16x16x32_bf16 v[170:173], v[158:161], v[182:185], v[76:79]
	v_mfma_f32_16x16x32_bf16 v[174:177], v[198:201], v[182:185], v[72:75]
	s_setprio 2
	s_barrier
	v_mfma_f32_16x16x32_bf16 v[182:185], v[158:161], v[190:193], v[68:71]
	v_mfma_f32_16x16x32_bf16 v[186:189], v[198:201], v[190:193], v[64:67]
	s_setprio 0
	s_nop 0
	ds_read_b128 v[64:67], v146 offset:16384
	ds_read_b128 v[68:71], v146 offset:17408
	ds_read_b128 v[72:75], v146 offset:18432
	ds_read_b128 v[76:79], v146 offset:19456
	ds_read_b128 v[80:83], v146 offset:20480
	ds_read_b128 v[84:87], v146 offset:21504
	ds_read_b128 v[88:91], v146 offset:22528
	ds_read_b128 v[92:95], v146 offset:23552
	s_waitcnt vmcnt(4)
	s_barrier
	s_waitcnt lgkmcnt(0)
	s_setprio 1
	s_waitcnt lgkmcnt(0)
	v_mfma_f32_16x16x32_bf16 v[60:63], v[132:135], v[64:67], v[60:63]
	v_mfma_f32_16x16x32_bf16 v[56:59], v[140:143], v[64:67], v[56:59]
	v_mfma_f32_16x16x32_bf16 v[52:55], v[132:135], v[72:75], v[52:55]
	v_mfma_f32_16x16x32_bf16 v[48:51], v[140:143], v[72:75], v[48:51]
	v_mfma_f32_16x16x32_bf16 v[44:47], v[132:135], v[80:83], v[44:47]
	v_mfma_f32_16x16x32_bf16 v[40:43], v[140:143], v[80:83], v[40:43]
	v_mfma_f32_16x16x32_bf16 v[36:39], v[132:135], v[88:91], v[36:39]
	v_mfma_f32_16x16x32_bf16 v[32:35], v[140:143], v[88:91], v[32:35]
	v_mfma_f32_16x16x32_bf16 v[60:63], v[136:139], v[68:71], v[60:63]
	v_mfma_f32_16x16x32_bf16 v[56:59], v[150:153], v[68:71], v[56:59]
	v_mfma_f32_16x16x32_bf16 v[52:55], v[136:139], v[76:79], v[52:55]
	v_mfma_f32_16x16x32_bf16 v[48:51], v[150:153], v[76:79], v[48:51]
	v_mfma_f32_16x16x32_bf16 v[44:47], v[136:139], v[84:87], v[44:47]
	v_mfma_f32_16x16x32_bf16 v[40:43], v[150:153], v[84:87], v[40:43]
	v_mfma_f32_16x16x32_bf16 v[36:39], v[136:139], v[92:95], v[36:39]
	v_mfma_f32_16x16x32_bf16 v[32:35], v[150:153], v[92:95], v[32:35]
	s_setprio 0
	s_setprio 1
	v_mfma_f32_16x16x32_bf16 v[28:31], v[128:131], v[64:67], v[28:31]
	v_mfma_f32_16x16x32_bf16 v[24:27], v[194:197], v[64:67], v[24:27]
	v_mfma_f32_16x16x32_bf16 v[20:23], v[128:131], v[72:75], v[20:23]
	v_mfma_f32_16x16x32_bf16 v[16:19], v[194:197], v[72:75], v[16:19]
	v_mfma_f32_16x16x32_bf16 v[12:15], v[128:131], v[80:83], v[12:15]
	v_mfma_f32_16x16x32_bf16 v[8:11], v[194:197], v[80:83], v[8:11]
	v_mfma_f32_16x16x32_bf16 v[4:7], v[128:131], v[88:91], v[4:7]
	v_mfma_f32_16x16x32_bf16 v[0:3], v[194:197], v[88:91], v[0:3]
	v_mfma_f32_16x16x32_bf16 v[132:135], v[158:161], v[68:71], v[28:31]
	v_mfma_f32_16x16x32_bf16 v[136:139], v[198:201], v[68:71], v[24:27]
	v_mfma_f32_16x16x32_bf16 v[140:143], v[158:161], v[76:79], v[20:23]
	v_mfma_f32_16x16x32_bf16 v[150:153], v[198:201], v[76:79], v[16:19]
	v_mfma_f32_16x16x32_bf16 v[190:193], v[158:161], v[84:87], v[12:15]
	v_mfma_f32_16x16x32_bf16 v[206:209], v[198:201], v[84:87], v[8:11]
	s_setprio 2
	s_barrier
	v_mfma_f32_16x16x32_bf16 v[128:131], v[158:161], v[92:95], v[4:7]
	v_mfma_f32_16x16x32_bf16 v[158:161], v[198:201], v[92:95], v[0:3]
	s_setprio 0
	ds_read_b128 v[24:27], v149 offset:32768
	ds_read_b128 v[28:31], v149 offset:33792
	ds_read_b128 v[194:197], v149 offset:34816
	ds_read_b128 v[198:201], v149 offset:35840
	ds_read_b128 v[0:3], v146 offset:32768
	ds_read_b128 v[4:7], v146 offset:33792
	ds_read_b128 v[8:11], v146 offset:34816
	ds_read_b128 v[12:15], v146 offset:35840
	ds_read_b128 v[16:19], v146 offset:36864
	ds_read_b128 v[20:23], v146 offset:37888
	ds_read_b128 v[210:213], v146 offset:38912
	ds_read_b128 v[214:217], v146 offset:39936
	s_waitcnt vmcnt(2)
	s_barrier
; #define LDA(dst, b, h) for (int m = 0; m < 4; ++m) for (int k = 0; k < 2; ++k) \
;     dst[m][k] = *reinterpret_cast<const bf16x8*>(a_rd + ((b) * 2 + (h)) * (HT * 2) + m * 2048 + k * 1024)
; #define LDB(dst, b, h) for (int n = 0; n < 2; ++n) for (int k = 0; k < 2; ++k) \
;     dst[n][k] = *reinterpret_cast<const bf16x8*>(b_rd + ((b) * 2 + (h)) * (HT * 2) + n * 2048 + k * 1024)
; #define MMA(ai, bj, At_, Bt_) do { __builtin_amdgcn_s_setprio(1); \
;     for (int m = 0; m < 4; ++m) for (int n = 0; n < 2; ++n) for (int k = 0; k < 2; ++k) \
;       acc[ai][bj][m][n] = __builtin_amdgcn_mfma_f32_16x16x32_bf16(Bt_[n][k], At_[m][k], acc[ai][bj][m][n], 0, 0, 0); \
;     __builtin_amdgcn_s_setprio(0); } while (0)
; #define WAIT_V(n) asm volatile("s_waitcnt vmcnt(" #n ")" ::: "memory")
; #define WAIT_L(n) asm volatile("s_waitcnt lgkmcnt(" #n ")" ::: "memory")
; #define BAR __builtin_amdgcn_s_barrier()
;     ...
;   { LDB(B0, 1, 0); LDA(At, 1, 0); WAIT_V(2); BAR; WAIT_L(0); MMA(0, 0, At, B0); BAR;
;     LDB(B1, 1, 1); WAIT_V(0); BAR; WAIT_L(0); MMA(0, 1, At, B1); BAR;
;     LDA(At, 1, 1); BAR; WAIT_L(0); MMA(1, 0, At, B0); MMA(1, 1, At, B1); BAR; }
;   if (wr == 0) BAR;
	s_waitcnt lgkmcnt(0)
	s_setprio 1
	s_waitcnt lgkmcnt(0)
	v_mfma_f32_16x16x32_bf16 v[64:67], v[24:27], v[0:3], v[124:127]
	v_mfma_f32_16x16x32_bf16 v[68:71], v[194:197], v[0:3], v[120:123]
	v_mfma_f32_16x16x32_bf16 v[72:75], v[24:27], v[8:11], v[116:119]
	v_mfma_f32_16x16x32_bf16 v[76:79], v[194:197], v[8:11], v[112:115]
	v_mfma_f32_16x16x32_bf16 v[80:83], v[24:27], v[16:19], v[108:111]
	v_mfma_f32_16x16x32_bf16 v[84:87], v[194:197], v[16:19], v[104:107]
	v_mfma_f32_16x16x32_bf16 v[88:91], v[24:27], v[210:213], v[100:103]
	v_mfma_f32_16x16x32_bf16 v[92:95], v[194:197], v[210:213], v[96:99]
	v_mfma_f32_16x16x32_bf16 v[64:67], v[28:31], v[4:7], v[64:67]
	v_mfma_f32_16x16x32_bf16 v[68:71], v[198:201], v[4:7], v[68:71]
	v_mfma_f32_16x16x32_bf16 v[72:75], v[28:31], v[12:15], v[72:75]
	v_mfma_f32_16x16x32_bf16 v[76:79], v[198:201], v[12:15], v[76:79]
	v_mfma_f32_16x16x32_bf16 v[80:83], v[28:31], v[20:23], v[80:83]
	v_mfma_f32_16x16x32_bf16 v[84:87], v[198:201], v[20:23], v[84:87]
	s_setprio 2
	s_barrier
	v_mfma_f32_16x16x32_bf16 v[88:91], v[28:31], v[214:217], v[88:91]
	v_mfma_f32_16x16x32_bf16 v[92:95], v[198:201], v[214:217], v[92:95]
	s_setprio 0
	ds_read_b128 v[218:221], v149 offset:49152
	ds_read_b128 v[230:233], v149 offset:50176
	ds_read_b128 v[238:241], v149 offset:51200
	ds_read_b128 v[246:249], v149 offset:52224
	s_waitcnt vmcnt(0)
	s_barrier
	s_waitcnt lgkmcnt(0)
	s_setprio 1
	s_waitcnt lgkmcnt(0)
	v_mfma_f32_16x16x32_bf16 v[96:99], v[218:221], v[0:3], v[202:205]
	v_mfma_f32_16x16x32_bf16 v[0:3], v[238:241], v[0:3], v[154:157]
	v_mfma_f32_16x16x32_bf16 v[100:103], v[246:249], v[4:7], v[0:3]
	v_mfma_f32_16x16x32_bf16 v[0:3], v[218:221], v[8:11], v[162:165]
	v_mfma_f32_16x16x32_bf16 v[104:107], v[230:233], v[12:15], v[0:3]
	v_mfma_f32_16x16x32_bf16 v[0:3], v[238:241], v[8:11], v[166:169]
	v_mfma_f32_16x16x32_bf16 v[108:111], v[246:249], v[12:15], v[0:3]
	v_mfma_f32_16x16x32_bf16 v[0:3], v[218:221], v[16:19], v[170:173]
	v_mfma_f32_16x16x32_bf16 v[112:115], v[230:233], v[20:23], v[0:3]
	v_mfma_f32_16x16x32_bf16 v[0:3], v[238:241], v[16:19], v[174:177]
	v_mfma_f32_16x16x32_bf16 v[116:119], v[246:249], v[20:23], v[0:3]
	v_mfma_f32_16x16x32_bf16 v[0:3], v[218:221], v[210:213], v[182:185]
	v_mfma_f32_16x16x32_bf16 v[120:123], v[230:233], v[214:217], v[0:3]
	v_mfma_f32_16x16x32_bf16 v[0:3], v[238:241], v[210:213], v[186:189]
	s_setprio 2
	s_barrier
	v_mfma_f32_16x16x32_bf16 v[96:99], v[230:233], v[4:7], v[96:99]
	v_mfma_f32_16x16x32_bf16 v[124:127], v[246:249], v[214:217], v[0:3]
	s_setprio 0
	ds_read_b128 v[154:157], v146 offset:49152
	ds_read_b128 v[162:165], v146 offset:50176
	ds_read_b128 v[166:169], v146 offset:51200
	ds_read_b128 v[170:173], v146 offset:52224
	ds_read_b128 v[174:177], v146 offset:53248
	ds_read_b128 v[182:185], v146 offset:54272
	ds_read_b128 v[186:189], v146 offset:55296
	ds_read_b128 v[146:149], v146 offset:56320
	s_barrier
	s_waitcnt lgkmcnt(0)
	s_setprio 1
	s_waitcnt lgkmcnt(0)
	v_mfma_f32_16x16x32_bf16 v[0:3], v[24:27], v[154:157], v[60:63]
	v_mfma_f32_16x16x32_bf16 v[8:11], v[24:27], v[166:169], v[52:55]
	v_mfma_f32_16x16x32_bf16 v[16:19], v[24:27], v[174:177], v[44:47]
	v_mfma_f32_16x16x32_bf16 v[24:27], v[24:27], v[186:189], v[36:39]
	v_mfma_f32_16x16x32_bf16 v[0:3], v[28:31], v[162:165], v[0:3]
	v_mfma_f32_16x16x32_bf16 v[4:7], v[194:197], v[154:157], v[56:59]
	v_mfma_f32_16x16x32_bf16 v[8:11], v[28:31], v[170:173], v[8:11]
	v_mfma_f32_16x16x32_bf16 v[12:15], v[194:197], v[166:169], v[48:51]
	v_mfma_f32_16x16x32_bf16 v[16:19], v[28:31], v[182:185], v[16:19]
	v_mfma_f32_16x16x32_bf16 v[20:23], v[194:197], v[174:177], v[40:43]
	v_mfma_f32_16x16x32_bf16 v[24:27], v[28:31], v[146:149], v[24:27]
	v_mfma_f32_16x16x32_bf16 v[28:31], v[194:197], v[186:189], v[32:35]
	v_mfma_f32_16x16x32_bf16 v[4:7], v[198:201], v[162:165], v[4:7]
	v_mfma_f32_16x16x32_bf16 v[12:15], v[198:201], v[170:173], v[12:15]
	v_mfma_f32_16x16x32_bf16 v[20:23], v[198:201], v[182:185], v[20:23]
	v_mfma_f32_16x16x32_bf16 v[28:31], v[198:201], v[146:149], v[28:31]
	s_setprio 0
	s_setprio 1
	v_mfma_f32_16x16x32_bf16 v[32:35], v[218:221], v[154:157], v[132:135]
	v_mfma_f32_16x16x32_bf16 v[36:39], v[238:241], v[154:157], v[136:139]
	v_mfma_f32_16x16x32_bf16 v[40:43], v[218:221], v[166:169], v[140:143]
	v_mfma_f32_16x16x32_bf16 v[44:47], v[238:241], v[166:169], v[150:153]
	v_mfma_f32_16x16x32_bf16 v[48:51], v[218:221], v[174:177], v[190:193]
	v_mfma_f32_16x16x32_bf16 v[52:55], v[238:241], v[174:177], v[206:209]
	v_mfma_f32_16x16x32_bf16 v[56:59], v[218:221], v[186:189], v[128:131]
	v_mfma_f32_16x16x32_bf16 v[60:63], v[238:241], v[186:189], v[158:161]
	v_mfma_f32_16x16x32_bf16 v[32:35], v[230:233], v[162:165], v[32:35]
	v_mfma_f32_16x16x32_bf16 v[36:39], v[246:249], v[162:165], v[36:39]
	v_mfma_f32_16x16x32_bf16 v[40:43], v[230:233], v[170:173], v[40:43]
	v_mfma_f32_16x16x32_bf16 v[44:47], v[246:249], v[170:173], v[44:47]
	v_mfma_f32_16x16x32_bf16 v[48:51], v[230:233], v[182:185], v[48:51]
	v_mfma_f32_16x16x32_bf16 v[52:55], v[246:249], v[182:185], v[52:55]
	s_setprio 2
	s_barrier
	v_mfma_f32_16x16x32_bf16 v[56:59], v[230:233], v[146:149], v[56:59]
	v_mfma_f32_16x16x32_bf16 v[60:63], v[246:249], v[146:149], v[60:63]
	s_setprio 0
	v_cmp_gt_u32_e32 vcc, s60, v144
	s_and_saveexec_b64 s[8:9], vcc
	s_cbranch_execz .LBB0_1804
	s_barrier

; #define STAGE_A(P, br, kt) do { const char* _base = (const char*)(((kt) < G.ksplit ? G.A1 : A2m) + (long)(br) * G.lda + (long)(kt) * BK); \
;     __builtin_amdgcn_global_load_lds((const unsigned*)(_base + aoff0), (unsigned*)((char*)(P) + sb0), 16, 0, 0); \
;     __builtin_amdgcn_global_load_lds((const unsigned*)(_base + aoff1), (unsigned*)((char*)(P) + sb1), 16, 0, 0); } while (0)
; #define STAGE_B(P, br, kt) do { const char* _base = (const char*)(G.Bt + (long)(br) * G.ldb + (long)(kt) * BK); \
;     __builtin_amdgcn_global_load_lds((const unsigned*)(_base + boff0), (unsigned*)((char*)(P) + sb0), 16, 0, 0); \
;     __builtin_amdgcn_global_load_lds((const unsigned*)(_base + boff1), (unsigned*)((char*)(P) + sb1), 16, 0, 0); } while (0)
; #define LDA(dst, b, h) for (int m = 0; m < 4; ++m) for (int k = 0; k < 2; ++k) \
;     dst[m][k] = *reinterpret_cast<const bf16x8*>(a_rd + ((b) * 2 + (h)) * (HT * 2) + m * 2048 + k * 1024)
; #define LDB(dst, b, h) for (int n = 0; n < 2; ++n) for (int k = 0; k < 2; ++k) \
;     dst[n][k] = *reinterpret_cast<const bf16x8*>(b_rd + ((b) * 2 + (h)) * (HT * 2) + n * 2048 + k * 1024)
; #define MMA(ai, bj, At_, Bt_) do { __builtin_amdgcn_s_setprio(1); \
;     for (int m = 0; m < 4; ++m) for (int n = 0; n < 2; ++n) for (int k = 0; k < 2; ++k) \
;       acc[ai][bj][m][n] = __builtin_amdgcn_mfma_f32_16x16x32_bf16(Bt_[n][k], At_[m][k], acc[ai][bj][m][n], 0, 0, 0); \
;     __builtin_amdgcn_s_setprio(0); } while (0)
; #define WAIT_V(n) asm volatile("s_waitcnt vmcnt(" #n ")" ::: "memory")
; #define WAIT_L(n) asm volatile("s_waitcnt lgkmcnt(" #n ")" ::: "memory")
; #define BAR __builtin_amdgcn_s_barrier()
; #define SCHED __builtin_amdgcn_sched_barrier(0)
;     ...
;     LDB(B0, 0, 0); SCHED; LDA(At, 0, 0); STAGE_A(SA(1, 1), brow + HALF, t + 1);
;     WAIT_L(8); BAR; WAIT_L(0); MMA(0, 0, At, B0); BAR; SCHED;
;     LDB(B1, 0, 1); STAGE_B(SB(0, 0), bcol, t + 2);
;     BAR; WAIT_L(0); MMA(0, 1, At, B1); BAR;
;     LDA(At, 0, 1); STAGE_A(SA(0, 0), brow, t + 2);
;     BAR; WAIT_L(0); MMA(1, 0, At, B0); BAR; SCHED;
;     STAGE_B(SB(0, 1), bcol + HALF, t + 2);
;     WAIT_V(6); BAR; MMA(1, 1, At, B1); BAR;
;     LDB(B0, 1, 0); SCHED; LDA(At, 1, 0); STAGE_A(SA(0, 1), brow + HALF, t + 2);
.LBB0_1865:
	ds_read_b128 v[160:163], v149
	ds_read_b128 v[164:167], v149 offset:1024
	ds_read_b128 v[168:171], v149 offset:2048
	ds_read_b128 v[172:175], v149 offset:3072
	v_add_u32_e32 v158, 0xc000, v147
	v_lshl_add_u64 v[222:223], s[26:27], 0, v[134:135]
	v_readfirstlane_b32 s35, v158
	v_add_u32_e32 v159, 0xe000, v147
	v_lshl_add_u64 v[156:157], v[222:223], 0, s[94:95]
	s_mov_b32 m0, s35
	v_lshl_add_u64 v[230:231], s[26:27], 0, v[136:137]
	v_readfirstlane_b32 s35, v159
	ds_read_b128 v[176:179], v148
	ds_read_b128 v[182:185], v148 offset:1024
	ds_read_b128 v[186:189], v148 offset:2048
	ds_read_b128 v[190:193], v148 offset:3072
	ds_read_b128 v[194:197], v148 offset:4096
	ds_read_b128 v[198:201], v148 offset:5120
	ds_read_b128 v[202:205], v148 offset:6144
	ds_read_b128 v[206:209], v148 offset:7168
	global_load_lds_dwordx4 v[156:157], off
	v_lshl_add_u64 v[156:157], v[230:231], 0, s[94:95]
	s_mov_b32 m0, s35
	s_nop 0
	global_load_lds_dwordx4 v[156:157], off
	ds_read_b128 v[210:213], v149 offset:16384
	ds_read_b128 v[214:217], v149 offset:17408
	ds_read_b128 v[218:221], v149 offset:18432
	ds_read_b128 v[246:249], v149 offset:19456
	s_waitcnt lgkmcnt(0)
	s_waitcnt vmcnt(8)
	s_barrier
	s_setprio 1
	v_mfma_f32_16x16x32_bf16 v[124:127], v[160:163], v[176:179], v[124:127]
	v_mfma_f32_16x16x32_bf16 v[120:123], v[168:171], v[176:179], v[120:123]
	v_mfma_f32_16x16x32_bf16 v[116:119], v[160:163], v[186:189], v[116:119]
	v_mfma_f32_16x16x32_bf16 v[112:115], v[168:171], v[186:189], v[112:115]
	v_mfma_f32_16x16x32_bf16 v[108:111], v[160:163], v[194:197], v[108:111]
	v_mfma_f32_16x16x32_bf16 v[104:107], v[168:171], v[194:197], v[104:107]
	v_mfma_f32_16x16x32_bf16 v[100:103], v[160:163], v[202:205], v[100:103]
	v_mfma_f32_16x16x32_bf16 v[96:99], v[168:171], v[202:205], v[96:99]
	v_mfma_f32_16x16x32_bf16 v[124:127], v[164:167], v[182:185], v[124:127]
	v_mfma_f32_16x16x32_bf16 v[120:123], v[172:175], v[182:185], v[120:123]
	v_mfma_f32_16x16x32_bf16 v[116:119], v[164:167], v[190:193], v[116:119]
	v_mfma_f32_16x16x32_bf16 v[112:115], v[172:175], v[190:193], v[112:115]
	v_mfma_f32_16x16x32_bf16 v[108:111], v[164:167], v[198:201], v[108:111]
	v_mfma_f32_16x16x32_bf16 v[104:107], v[172:175], v[198:201], v[104:107]
	v_mfma_f32_16x16x32_bf16 v[100:103], v[164:167], v[206:209], v[100:103]
	v_mfma_f32_16x16x32_bf16 v[96:99], v[172:175], v[206:209], v[96:99]
	v_mfma_f32_16x16x32_bf16 v[92:95], v[210:213], v[176:179], v[92:95]
	v_mfma_f32_16x16x32_bf16 v[88:91], v[218:221], v[176:179], v[88:91]
	v_mfma_f32_16x16x32_bf16 v[84:87], v[210:213], v[186:189], v[84:87]
	v_mfma_f32_16x16x32_bf16 v[80:83], v[218:221], v[186:189], v[80:83]
	v_mfma_f32_16x16x32_bf16 v[76:79], v[210:213], v[194:197], v[76:79]
	v_mfma_f32_16x16x32_bf16 v[72:75], v[218:221], v[194:197], v[72:75]
	v_mfma_f32_16x16x32_bf16 v[68:71], v[210:213], v[202:205], v[68:71]
	v_mfma_f32_16x16x32_bf16 v[64:67], v[218:221], v[202:205], v[64:67]
	v_mfma_f32_16x16x32_bf16 v[92:95], v[214:217], v[182:185], v[92:95]
	v_mfma_f32_16x16x32_bf16 v[88:91], v[246:249], v[182:185], v[88:91]
	v_mfma_f32_16x16x32_bf16 v[84:87], v[214:217], v[190:193], v[84:87]
	v_mfma_f32_16x16x32_bf16 v[80:83], v[246:249], v[190:193], v[80:83]
	v_mfma_f32_16x16x32_bf16 v[76:79], v[214:217], v[198:201], v[76:79]
	v_mfma_f32_16x16x32_bf16 v[72:75], v[246:249], v[198:201], v[72:75]
	s_setprio 2
	s_barrier
	v_mfma_f32_16x16x32_bf16 v[68:71], v[214:217], v[206:209], v[68:71]
	v_mfma_f32_16x16x32_bf16 v[64:67], v[246:249], v[206:209], v[64:67]
	s_setprio 0
	v_add_u32_e32 v155, s30, v142
	v_lshl_add_u64 v[232:233], s[26:27], 0, v[130:131]
	v_readfirstlane_b32 s35, v155
	v_lshl_add_u64 v[156:157], v[232:233], 0, s[42:43]
	s_mov_b32 m0, s35
	global_load_lds_dwordx4 v[156:157], off
	v_add_u32_e32 v156, 0x2000, v155
	v_lshl_add_u64 v[234:235], s[26:27], 0, v[132:133]
	v_readfirstlane_b32 s35, v156
	v_lshl_add_u64 v[236:237], v[234:235], 0, s[42:43]
	s_mov_b32 m0, s35
	s_nop 0
	global_load_lds_dwordx4 v[236:237], off
	v_readfirstlane_b32 s35, v147
	v_lshl_add_u64 v[236:237], v[222:223], 0, s[4:5]
	s_mov_b32 m0, s35
	v_readfirstlane_b32 s35, v146
	ds_read_b128 v[176:179], v148 offset:16384
	ds_read_b128 v[182:185], v148 offset:17408
	ds_read_b128 v[186:189], v148 offset:18432
	ds_read_b128 v[190:193], v148 offset:19456
	ds_read_b128 v[194:197], v148 offset:20480
	ds_read_b128 v[198:201], v148 offset:21504
	ds_read_b128 v[202:205], v148 offset:22528
	ds_read_b128 v[206:209], v148 offset:23552
	global_load_lds_dwordx4 v[236:237], off
	v_lshl_add_u64 v[236:237], v[230:231], 0, s[4:5]
	s_mov_b32 m0, s35
	s_nop 0
	global_load_lds_dwordx4 v[236:237], off
	v_readfirstlane_b32 s35, v141
	v_add_u32_e32 v157, 0x2000, v141
	v_lshl_add_u64 v[250:251], v[232:233], 0, s[46:47]
	s_mov_b32 m0, s35
	v_readfirstlane_b32 s35, v157
	global_load_lds_dwordx4 v[250:251], off
	v_lshl_add_u64 v[250:251], v[234:235], 0, s[46:47]
	s_mov_b32 m0, s35
	s_nop 0
	global_load_lds_dwordx4 v[250:251], off
	s_waitcnt lgkmcnt(0)
	s_waitcnt vmcnt(8)
	s_barrier
; #define STAGE_A(P, br, kt) do { const char* _base = (const char*)(((kt) < G.ksplit ? G.A1 : A2m) + (long)(br) * G.lda + (long)(kt) * BK); \
;     __builtin_amdgcn_global_load_lds((const unsigned*)(_base + aoff0), (unsigned*)((char*)(P) + sb0), 16, 0, 0); \
;     __builtin_amdgcn_global_load_lds((const unsigned*)(_base + aoff1), (unsigned*)((char*)(P) + sb1), 16, 0, 0); } while (0)
; #define STAGE_B(P, br, kt) do { const char* _base = (const char*)(G.Bt + (long)(br) * G.ldb + (long)(kt) * BK); \
;     __builtin_amdgcn_global_load_lds((const unsigned*)(_base + boff0), (unsigned*)((char*)(P) + sb0), 16, 0, 0); \
;     __builtin_amdgcn_global_load_lds((const unsigned*)(_base + boff1), (unsigned*)((char*)(P) + sb1), 16, 0, 0); } while (0)
; #define LDA(dst, b, h) for (int m = 0; m < 4; ++m) for (int k = 0; k < 2; ++k) \
;     dst[m][k] = *reinterpret_cast<const bf16x8*>(a_rd + ((b) * 2 + (h)) * (HT * 2) + m * 2048 + k * 1024)
; #define LDB(dst, b, h) for (int n = 0; n < 2; ++n) for (int k = 0; k < 2; ++k) \
;     dst[n][k] = *reinterpret_cast<const bf16x8*>(b_rd + ((b) * 2 + (h)) * (HT * 2) + n * 2048 + k * 1024)
; #define MMA(ai, bj, At_, Bt_) do { __builtin_amdgcn_s_setprio(1); \
;     for (int m = 0; m < 4; ++m) for (int n = 0; n < 2; ++n) for (int k = 0; k < 2; ++k) \
;       acc[ai][bj][m][n] = __builtin_amdgcn_mfma_f32_16x16x32_bf16(Bt_[n][k], At_[m][k], acc[ai][bj][m][n], 0, 0, 0); \
;     __builtin_amdgcn_s_setprio(0); } while (0)
; #define WAIT_V(n) asm volatile("s_waitcnt vmcnt(" #n ")" ::: "memory")
; #define WAIT_L(n) asm volatile("s_waitcnt lgkmcnt(" #n ")" ::: "memory")
; #define BAR __builtin_amdgcn_s_barrier()
; #define SCHED __builtin_amdgcn_sched_barrier(0)
;     ...
;     LDA(At, 0, 1); STAGE_A(SA(0, 0), brow, t + 2);
;     BAR; WAIT_L(0); MMA(1, 0, At, B0); BAR; SCHED;
;     STAGE_B(SB(0, 1), bcol + HALF, t + 2);
;     WAIT_V(6); BAR; MMA(1, 1, At, B1); BAR;
;     LDB(B0, 1, 0); SCHED; LDA(At, 1, 0); STAGE_A(SA(0, 1), brow + HALF, t + 2);
;     WAIT_L(8); BAR; WAIT_L(0); MMA(0, 0, At, B0); BAR; SCHED;
;     LDB(B1, 1, 1); STAGE_B(SB(1, 0), bcol, t + 3);
;     BAR; WAIT_L(0); MMA(0, 1, At, B1); BAR;
;     LDA(At, 1, 1); STAGE_A(SA(1, 0), brow, t + 3);
;     BAR; WAIT_L(0); MMA(1, 0, At, B0); BAR; SCHED;
	s_setprio 1
	v_mfma_f32_16x16x32_bf16 v[60:63], v[160:163], v[176:179], v[60:63]
	v_mfma_f32_16x16x32_bf16 v[56:59], v[168:171], v[176:179], v[56:59]
	v_mfma_f32_16x16x32_bf16 v[52:55], v[160:163], v[186:189], v[52:55]
	v_mfma_f32_16x16x32_bf16 v[48:51], v[168:171], v[186:189], v[48:51]
	v_mfma_f32_16x16x32_bf16 v[44:47], v[160:163], v[194:197], v[44:47]
	v_mfma_f32_16x16x32_bf16 v[40:43], v[168:171], v[194:197], v[40:43]
	v_mfma_f32_16x16x32_bf16 v[36:39], v[160:163], v[202:205], v[36:39]
	v_mfma_f32_16x16x32_bf16 v[32:35], v[168:171], v[202:205], v[32:35]
	v_mfma_f32_16x16x32_bf16 v[60:63], v[164:167], v[182:185], v[60:63]
	v_mfma_f32_16x16x32_bf16 v[56:59], v[172:175], v[182:185], v[56:59]
	v_mfma_f32_16x16x32_bf16 v[52:55], v[164:167], v[190:193], v[52:55]
	v_mfma_f32_16x16x32_bf16 v[48:51], v[172:175], v[190:193], v[48:51]
	v_mfma_f32_16x16x32_bf16 v[44:47], v[164:167], v[198:201], v[44:47]
	v_mfma_f32_16x16x32_bf16 v[40:43], v[172:175], v[198:201], v[40:43]
	v_mfma_f32_16x16x32_bf16 v[36:39], v[164:167], v[206:209], v[36:39]
	v_mfma_f32_16x16x32_bf16 v[32:35], v[172:175], v[206:209], v[32:35]
	v_mfma_f32_16x16x32_bf16 v[28:31], v[210:213], v[176:179], v[28:31]
	v_mfma_f32_16x16x32_bf16 v[24:27], v[218:221], v[176:179], v[24:27]
	v_mfma_f32_16x16x32_bf16 v[20:23], v[210:213], v[186:189], v[20:23]
	v_mfma_f32_16x16x32_bf16 v[16:19], v[218:221], v[186:189], v[16:19]
	v_mfma_f32_16x16x32_bf16 v[12:15], v[210:213], v[194:197], v[12:15]
	v_mfma_f32_16x16x32_bf16 v[8:11], v[218:221], v[194:197], v[8:11]
	v_mfma_f32_16x16x32_bf16 v[4:7], v[210:213], v[202:205], v[4:7]
	v_mfma_f32_16x16x32_bf16 v[0:3], v[218:221], v[202:205], v[0:3]
	v_mfma_f32_16x16x32_bf16 v[28:31], v[214:217], v[182:185], v[28:31]
	v_mfma_f32_16x16x32_bf16 v[24:27], v[246:249], v[182:185], v[24:27]
	v_mfma_f32_16x16x32_bf16 v[20:23], v[214:217], v[190:193], v[20:23]
	v_mfma_f32_16x16x32_bf16 v[16:19], v[246:249], v[190:193], v[16:19]
	v_mfma_f32_16x16x32_bf16 v[12:15], v[214:217], v[198:201], v[12:15]
	v_mfma_f32_16x16x32_bf16 v[8:11], v[246:249], v[198:201], v[8:11]
	s_setprio 2
	s_barrier
	v_mfma_f32_16x16x32_bf16 v[4:7], v[214:217], v[206:209], v[4:7]
	v_mfma_f32_16x16x32_bf16 v[0:3], v[246:249], v[206:209], v[0:3]
	s_setprio 0
	ds_read_b128 v[160:163], v149 offset:32768
	ds_read_b128 v[164:167], v149 offset:33792
	ds_read_b128 v[168:171], v149 offset:34816
	ds_read_b128 v[172:175], v149 offset:35840
	v_readfirstlane_b32 s35, v140
	v_lshl_add_u64 v[210:211], v[222:223], 0, s[96:97]
	s_mov_b32 m0, s35
	v_readfirstlane_b32 s35, v138
	ds_read_b128 v[176:179], v148 offset:32768
	ds_read_b128 v[182:185], v148 offset:33792
	ds_read_b128 v[186:189], v148 offset:34816
	ds_read_b128 v[190:193], v148 offset:35840
	ds_read_b128 v[194:197], v148 offset:36864
	ds_read_b128 v[198:201], v148 offset:37888
	ds_read_b128 v[202:205], v148 offset:38912
	ds_read_b128 v[206:209], v148 offset:39936
	global_load_lds_dwordx4 v[210:211], off
	v_lshl_add_u64 v[210:211], v[230:231], 0, s[96:97]
	s_mov_b32 m0, s35
	s_nop 0
	global_load_lds_dwordx4 v[210:211], off
	ds_read_b128 v[210:213], v149 offset:49152
	ds_read_b128 v[214:217], v149 offset:50176
	ds_read_b128 v[218:221], v149 offset:51200
	ds_read_b128 v[246:249], v149 offset:52224
	s_waitcnt lgkmcnt(0)
	s_waitcnt vmcnt(8)
	s_barrier
	s_setprio 1
	v_mfma_f32_16x16x32_bf16 v[124:127], v[160:163], v[176:179], v[124:127]
	v_mfma_f32_16x16x32_bf16 v[120:123], v[168:171], v[176:179], v[120:123]
	v_mfma_f32_16x16x32_bf16 v[116:119], v[160:163], v[186:189], v[116:119]
	v_mfma_f32_16x16x32_bf16 v[112:115], v[168:171], v[186:189], v[112:115]
	v_mfma_f32_16x16x32_bf16 v[108:111], v[160:163], v[194:197], v[108:111]
	v_mfma_f32_16x16x32_bf16 v[104:107], v[168:171], v[194:197], v[104:107]
	v_mfma_f32_16x16x32_bf16 v[100:103], v[160:163], v[202:205], v[100:103]
	v_mfma_f32_16x16x32_bf16 v[96:99], v[168:171], v[202:205], v[96:99]
	v_mfma_f32_16x16x32_bf16 v[124:127], v[164:167], v[182:185], v[124:127]
	v_mfma_f32_16x16x32_bf16 v[120:123], v[172:175], v[182:185], v[120:123]
	v_mfma_f32_16x16x32_bf16 v[116:119], v[164:167], v[190:193], v[116:119]
	v_mfma_f32_16x16x32_bf16 v[112:115], v[172:175], v[190:193], v[112:115]
	v_mfma_f32_16x16x32_bf16 v[108:111], v[164:167], v[198:201], v[108:111]
	v_mfma_f32_16x16x32_bf16 v[104:107], v[172:175], v[198:201], v[104:107]
	v_mfma_f32_16x16x32_bf16 v[100:103], v[164:167], v[206:209], v[100:103]
	v_mfma_f32_16x16x32_bf16 v[96:99], v[172:175], v[206:209], v[96:99]
	v_mfma_f32_16x16x32_bf16 v[92:95], v[210:213], v[176:179], v[92:95]
	v_mfma_f32_16x16x32_bf16 v[88:91], v[218:221], v[176:179], v[88:91]
	v_mfma_f32_16x16x32_bf16 v[84:87], v[210:213], v[186:189], v[84:87]
	v_mfma_f32_16x16x32_bf16 v[80:83], v[218:221], v[186:189], v[80:83]
	v_mfma_f32_16x16x32_bf16 v[76:79], v[210:213], v[194:197], v[76:79]
	v_mfma_f32_16x16x32_bf16 v[72:75], v[218:221], v[194:197], v[72:75]
	v_mfma_f32_16x16x32_bf16 v[68:71], v[210:213], v[202:205], v[68:71]
	v_mfma_f32_16x16x32_bf16 v[64:67], v[218:221], v[202:205], v[64:67]
	v_mfma_f32_16x16x32_bf16 v[92:95], v[214:217], v[182:185], v[92:95]
	v_mfma_f32_16x16x32_bf16 v[88:91], v[246:249], v[182:185], v[88:91]
	v_mfma_f32_16x16x32_bf16 v[84:87], v[214:217], v[190:193], v[84:87]
	v_mfma_f32_16x16x32_bf16 v[80:83], v[246:249], v[190:193], v[80:83]
	v_mfma_f32_16x16x32_bf16 v[76:79], v[214:217], v[198:201], v[76:79]
	v_mfma_f32_16x16x32_bf16 v[72:75], v[246:249], v[198:201], v[72:75]
	s_setprio 2
	s_barrier
; #define STAGE_A(P, br, kt) do { const char* _base = (const char*)(((kt) < G.ksplit ? G.A1 : A2m) + (long)(br) * G.lda + (long)(kt) * BK); \
;     __builtin_amdgcn_global_load_lds((const unsigned*)(_base + aoff0), (unsigned*)((char*)(P) + sb0), 16, 0, 0); \
;     __builtin_amdgcn_global_load_lds((const unsigned*)(_base + aoff1), (unsigned*)((char*)(P) + sb1), 16, 0, 0); } while (0)
; #define STAGE_B(P, br, kt) do { const char* _base = (const char*)(G.Bt + (long)(br) * G.ldb + (long)(kt) * BK); \
;     __builtin_amdgcn_global_load_lds((const unsigned*)(_base + boff0), (unsigned*)((char*)(P) + sb0), 16, 0, 0); \
;     __builtin_amdgcn_global_load_lds((const unsigned*)(_base + boff1), (unsigned*)((char*)(P) + sb1), 16, 0, 0); } while (0)
; #define LDA(dst, b, h) for (int m = 0; m < 4; ++m) for (int k = 0; k < 2; ++k) \
;     dst[m][k] = *reinterpret_cast<const bf16x8*>(a_rd + ((b) * 2 + (h)) * (HT * 2) + m * 2048 + k * 1024)
; #define LDB(dst, b, h) for (int n = 0; n < 2; ++n) for (int k = 0; k < 2; ++k) \
;     dst[n][k] = *reinterpret_cast<const bf16x8*>(b_rd + ((b) * 2 + (h)) * (HT * 2) + n * 2048 + k * 1024)
; #define MMA(ai, bj, At_, Bt_) do { __builtin_amdgcn_s_setprio(1); \
;     for (int m = 0; m < 4; ++m) for (int n = 0; n < 2; ++n) for (int k = 0; k < 2; ++k) \
;       acc[ai][bj][m][n] = __builtin_amdgcn_mfma_f32_16x16x32_bf16(Bt_[n][k], At_[m][k], acc[ai][bj][m][n], 0, 0, 0); \
;     __builtin_amdgcn_s_setprio(0); } while (0)
; #define WAIT_V(n) asm volatile("s_waitcnt vmcnt(" #n ")" ::: "memory")
; #define BAR __builtin_amdgcn_s_barrier()
;     ...
;     LDB(B0, 1, 0); SCHED; LDA(At, 1, 0); STAGE_A(SA(0, 1), brow + HALF, t + 2);
;     WAIT_L(8); BAR; WAIT_L(0); MMA(0, 0, At, B0); BAR; SCHED;
;     LDB(B1, 1, 1); STAGE_B(SB(1, 0), bcol, t + 3);
;     BAR; WAIT_L(0); MMA(0, 1, At, B1); BAR;
;     LDA(At, 1, 1); STAGE_A(SA(1, 0), brow, t + 3);
;     BAR; WAIT_L(0); MMA(1, 0, At, B0); BAR; SCHED;
;     STAGE_B(SB(1, 1), bcol + HALF, t + 3);
;     WAIT_V(6); BAR; MMA(1, 1, At, B1); BAR;
;   }
;   float ssv[2][4] = {};
;   if constexpr (EPI == EPI_GU || EPI == EPI_EVIN || EPI == EPI_ODIN) {
; #pragma unroll
;     for (int ai = 0; ai < 2; ++ai)
; #pragma unroll
;       for (int m = 0; m < 4; ++m) ssv[ai][m] = G.ssr[brow + ai * HALF + wr * 64 + m * 16 + fr];
;   }
;   { LDB(B0, 0, 0); LDA(At, 0, 0); STAGE_A(SA(1, 1), brow + HALF, nt - 1);
	v_mfma_f32_16x16x32_bf16 v[68:71], v[214:217], v[206:209], v[68:71]
	v_mfma_f32_16x16x32_bf16 v[64:67], v[246:249], v[206:209], v[64:67]
	s_setprio 0
	v_readfirstlane_b32 s35, v145
	v_lshl_add_u64 v[236:237], v[232:233], 0, s[44:45]
	s_mov_b32 m0, s35
	v_readfirstlane_b32 s35, v150
	global_load_lds_dwordx4 v[236:237], off
	v_lshl_add_u64 v[236:237], v[234:235], 0, s[44:45]
	s_mov_b32 m0, s35
	s_nop 0
	global_load_lds_dwordx4 v[236:237], off
	v_readfirstlane_b32 s35, v151
	v_lshl_add_u64 v[222:223], v[222:223], 0, s[2:3]
	s_mov_b32 m0, s35
	v_readfirstlane_b32 s35, v152
	ds_read_b128 v[176:179], v148 offset:49152
	ds_read_b128 v[182:185], v148 offset:50176
	ds_read_b128 v[186:189], v148 offset:51200
	ds_read_b128 v[190:193], v148 offset:52224
	ds_read_b128 v[194:197], v148 offset:53248
	ds_read_b128 v[198:201], v148 offset:54272
	ds_read_b128 v[202:205], v148 offset:55296
	ds_read_b128 v[206:209], v148 offset:56320
	global_load_lds_dwordx4 v[222:223], off
	v_lshl_add_u64 v[222:223], v[230:231], 0, s[2:3]
	s_mov_b32 m0, s35
	s_nop 0
	global_load_lds_dwordx4 v[222:223], off
	v_readfirstlane_b32 s35, v153
	v_lshl_add_u64 v[250:251], v[232:233], 0, s[48:49]
	s_mov_b32 m0, s35
	v_readfirstlane_b32 s35, v154
	global_load_lds_dwordx4 v[250:251], off
	v_lshl_add_u64 v[250:251], v[234:235], 0, s[48:49]
	s_mov_b32 m0, s35
	s_nop 0
	global_load_lds_dwordx4 v[250:251], off
	s_waitcnt lgkmcnt(0)
	s_waitcnt vmcnt(8)
	s_barrier
	s_setprio 1
	v_mfma_f32_16x16x32_bf16 v[60:63], v[160:163], v[176:179], v[60:63]
	v_mfma_f32_16x16x32_bf16 v[56:59], v[168:171], v[176:179], v[56:59]
	v_mfma_f32_16x16x32_bf16 v[52:55], v[160:163], v[186:189], v[52:55]
	v_mfma_f32_16x16x32_bf16 v[48:51], v[168:171], v[186:189], v[48:51]
	v_mfma_f32_16x16x32_bf16 v[44:47], v[160:163], v[194:197], v[44:47]
	v_mfma_f32_16x16x32_bf16 v[40:43], v[168:171], v[194:197], v[40:43]
	v_mfma_f32_16x16x32_bf16 v[36:39], v[160:163], v[202:205], v[36:39]
	v_mfma_f32_16x16x32_bf16 v[32:35], v[168:171], v[202:205], v[32:35]
	v_mfma_f32_16x16x32_bf16 v[60:63], v[164:167], v[182:185], v[60:63]
	v_mfma_f32_16x16x32_bf16 v[56:59], v[172:175], v[182:185], v[56:59]
	v_mfma_f32_16x16x32_bf16 v[52:55], v[164:167], v[190:193], v[52:55]
	v_mfma_f32_16x16x32_bf16 v[48:51], v[172:175], v[190:193], v[48:51]
	v_mfma_f32_16x16x32_bf16 v[44:47], v[164:167], v[198:201], v[44:47]
	v_mfma_f32_16x16x32_bf16 v[40:43], v[172:175], v[198:201], v[40:43]
	v_mfma_f32_16x16x32_bf16 v[36:39], v[164:167], v[206:209], v[36:39]
	v_mfma_f32_16x16x32_bf16 v[32:35], v[172:175], v[206:209], v[32:35]
	v_mfma_f32_16x16x32_bf16 v[28:31], v[210:213], v[176:179], v[28:31]
	v_mfma_f32_16x16x32_bf16 v[24:27], v[218:221], v[176:179], v[24:27]
	v_mfma_f32_16x16x32_bf16 v[20:23], v[210:213], v[186:189], v[20:23]
	v_mfma_f32_16x16x32_bf16 v[16:19], v[218:221], v[186:189], v[16:19]
	v_mfma_f32_16x16x32_bf16 v[12:15], v[210:213], v[194:197], v[12:15]
	v_mfma_f32_16x16x32_bf16 v[8:11], v[218:221], v[194:197], v[8:11]
	v_mfma_f32_16x16x32_bf16 v[4:7], v[210:213], v[202:205], v[4:7]
	v_mfma_f32_16x16x32_bf16 v[0:3], v[218:221], v[202:205], v[0:3]
	v_mfma_f32_16x16x32_bf16 v[28:31], v[214:217], v[182:185], v[28:31]
	v_mfma_f32_16x16x32_bf16 v[24:27], v[246:249], v[182:185], v[24:27]
	v_mfma_f32_16x16x32_bf16 v[20:23], v[214:217], v[190:193], v[20:23]
	v_mfma_f32_16x16x32_bf16 v[16:19], v[246:249], v[190:193], v[16:19]
	v_mfma_f32_16x16x32_bf16 v[12:15], v[214:217], v[198:201], v[12:15]
	v_mfma_f32_16x16x32_bf16 v[8:11], v[246:249], v[198:201], v[8:11]
	s_setprio 2
	s_barrier
	v_mfma_f32_16x16x32_bf16 v[4:7], v[214:217], v[206:209], v[4:7]
	v_mfma_f32_16x16x32_bf16 v[0:3], v[246:249], v[206:209], v[0:3]
	s_setprio 0
	s_add_i32 s31, s31, 2
	s_add_u32 s26, s26, 0x100
	s_addc_u32 s27, s27, 0
	s_cmp_lt_u32 s31, 28
	s_cbranch_scc1 .LBB0_1865
	s_waitcnt vmcnt(6)
	v_not_b32_e32 v250, 63
	v_mov_b32_e32 v251, 0x41b17218
	v_or_b32_e32 v130, s29, v144
	v_lshl_add_u32 v130, v143, 6, v130
	v_ashrrev_i32_e32 v131, 31, v130
	v_add_u32_e32 v142, 0xa0, v130
	v_lshl_add_u64 v[132:133], v[130:131], 2, s[20:21]
	v_add_u32_e32 v134, 0x80, v130
	v_add_u32_e32 v136, 0x90, v130
	v_ashrrev_i32_e32 v143, 31, v142
	v_add_u32_e32 v130, 0xb0, v130
	s_or_b32 s42, s29, 0x80
	v_ashrrev_i32_e32 v135, 31, v134
	v_ashrrev_i32_e32 v137, 31, v136
	v_lshl_add_u64 v[142:143], v[142:143], 2, s[20:21]
	v_ashrrev_i32_e32 v131, 31, v130
	s_mul_i32 s26, s42, 0x1080
	v_lshl_add_u64 v[134:135], v[134:135], 2, s[20:21]
	v_lshl_add_u64 v[136:137], v[136:137], 2, s[20:21]
	v_lshl_add_u64 v[160:161], v[130:131], 2, s[20:21]
	global_load_dword v130, v[132:133], off
	global_load_dword v152, v[132:133], off offset:64
	global_load_dword v151, v[132:133], off offset:128
	global_load_dword v150, v[132:133], off offset:192
	global_load_dword v145, v[134:135], off
	global_load_dword v144, v[136:137], off
	s_nop 0
	global_load_dword v143, v[142:143], off
	s_nop 0
	global_load_dword v142, v[160:161], off
	s_mul_hi_i32 s27, s42, 0x1080
	s_add_u32 s26, s37, s26
	s_addc_u32 s27, s38, s27
	v_lshl_add_u64 v[136:137], s[26:27], 0, v[180:181]
	s_mov_b64 s[44:45], 0xf80
	v_readfirstlane_b32 s30, v158
	v_lshl_add_u64 v[136:137], v[136:137], 0, s[44:45]
	s_mov_b32 m0, s30
	ds_read_b128 v[132:135], v149
	ds_read_b128 v[160:163], v149 offset:1024
	ds_read_b128 v[164:167], v149 offset:2048
	ds_read_b128 v[168:171], v149 offset:3072
	ds_read_b128 v[172:175], v148
	ds_read_b128 v[176:179], v148 offset:1024
	ds_read_b128 v[182:185], v148 offset:2048
	ds_read_b128 v[186:189], v148 offset:3072
	ds_read_b128 v[190:193], v148 offset:4096
	ds_read_b128 v[194:197], v148 offset:5120
	ds_read_b128 v[198:201], v148 offset:6144
	ds_read_b128 v[202:205], v148 offset:7168
	global_load_lds_dwordx4 v[136:137], off
	v_lshl_add_u64 v[136:137], s[26:27], 0, v[128:129]
	v_readfirstlane_b32 s26, v159
	v_lshl_add_u64 v[136:137], v[136:137], 0, s[44:45]
	s_mov_b32 m0, s26
	s_nop 0
	global_load_lds_dwordx4 v[136:137], off
	s_barrier
; #define STAGE_A(P, br, kt) do { const char* _base = (const char*)(((kt) < G.ksplit ? G.A1 : A2m) + (long)(br) * G.lda + (long)(kt) * BK); \
;     __builtin_amdgcn_global_load_lds((const unsigned*)(_base + aoff0), (unsigned*)((char*)(P) + sb0), 16, 0, 0); \
;     __builtin_amdgcn_global_load_lds((const unsigned*)(_base + aoff1), (unsigned*)((char*)(P) + sb1), 16, 0, 0); } while (0)
; #define LDA(dst, b, h) for (int m = 0; m < 4; ++m) for (int k = 0; k < 2; ++k) \
;     dst[m][k] = *reinterpret_cast<const bf16x8*>(a_rd + ((b) * 2 + (h)) * (HT * 2) + m * 2048 + k * 1024)
; #define LDB(dst, b, h) for (int n = 0; n < 2; ++n) for (int k = 0; k < 2; ++k) \
;     dst[n][k] = *reinterpret_cast<const bf16x8*>(b_rd + ((b) * 2 + (h)) * (HT * 2) + n * 2048 + k * 1024)
; #define MMA(ai, bj, At_, Bt_) do { __builtin_amdgcn_s_setprio(1); \
;     for (int m = 0; m < 4; ++m) for (int n = 0; n < 2; ++n) for (int k = 0; k < 2; ++k) \
;       acc[ai][bj][m][n] = __builtin_amdgcn_mfma_f32_16x16x32_bf16(Bt_[n][k], At_[m][k], acc[ai][bj][m][n], 0, 0, 0); \
;     __builtin_amdgcn_s_setprio(0); } while (0)
; #define WAIT_V(n) asm volatile("s_waitcnt vmcnt(" #n ")" ::: "memory")
; #define WAIT_L(n) asm volatile("s_waitcnt lgkmcnt(" #n ")" ::: "memory")
; #define BAR __builtin_amdgcn_s_barrier()
;     ...
;   { LDB(B0, 0, 0); LDA(At, 0, 0); STAGE_A(SA(1, 1), brow + HALF, nt - 1);
;     BAR; WAIT_L(0); MMA(0, 0, At, B0); BAR;
;     LDB(B1, 0, 1); BAR; WAIT_L(0); MMA(0, 1, At, B1); BAR;
;     LDA(At, 0, 1); WAIT_V(4); BAR; WAIT_L(0); MMA(1, 0, At, B0); MMA(1, 1, At, B1); BAR; }
;   { LDB(B0, 1, 0); LDA(At, 1, 0); WAIT_V(2); BAR; WAIT_L(0); MMA(0, 0, At, B0); BAR;
	s_waitcnt lgkmcnt(0)
	s_setprio 1
	s_waitcnt lgkmcnt(0)
	v_mfma_f32_16x16x32_bf16 v[124:127], v[132:135], v[172:175], v[124:127]
	v_mfma_f32_16x16x32_bf16 v[120:123], v[164:167], v[172:175], v[120:123]
	v_mfma_f32_16x16x32_bf16 v[116:119], v[132:135], v[182:185], v[116:119]
	v_mfma_f32_16x16x32_bf16 v[112:115], v[164:167], v[182:185], v[112:115]
	v_mfma_f32_16x16x32_bf16 v[108:111], v[132:135], v[190:193], v[108:111]
	v_mfma_f32_16x16x32_bf16 v[104:107], v[164:167], v[190:193], v[104:107]
	v_mfma_f32_16x16x32_bf16 v[100:103], v[132:135], v[198:201], v[100:103]
	v_mfma_f32_16x16x32_bf16 v[96:99], v[164:167], v[198:201], v[96:99]
	v_mfma_f32_16x16x32_bf16 v[124:127], v[160:163], v[176:179], v[124:127]
	v_mfma_f32_16x16x32_bf16 v[120:123], v[168:171], v[176:179], v[120:123]
	v_mfma_f32_16x16x32_bf16 v[116:119], v[160:163], v[186:189], v[116:119]
	v_mfma_f32_16x16x32_bf16 v[112:115], v[168:171], v[186:189], v[112:115]
	v_mfma_f32_16x16x32_bf16 v[108:111], v[160:163], v[194:197], v[108:111]
	v_mfma_f32_16x16x32_bf16 v[104:107], v[168:171], v[194:197], v[104:107]
	s_setprio 2
	s_barrier
	v_mfma_f32_16x16x32_bf16 v[100:103], v[160:163], v[202:205], v[100:103]
	v_mfma_f32_16x16x32_bf16 v[96:99], v[168:171], v[202:205], v[96:99]
	s_setprio 0
	ds_read_b128 v[206:209], v149 offset:16384
	ds_read_b128 v[210:213], v149 offset:17408
	ds_read_b128 v[214:217], v149 offset:18432
	ds_read_b128 v[218:221], v149 offset:19456
	s_barrier
	s_waitcnt lgkmcnt(0)
	s_setprio 1
	s_waitcnt lgkmcnt(0)
	v_mfma_f32_16x16x32_bf16 v[92:95], v[206:209], v[172:175], v[92:95]
	v_mfma_f32_16x16x32_bf16 v[88:91], v[214:217], v[172:175], v[88:91]
	v_mfma_f32_16x16x32_bf16 v[84:87], v[206:209], v[182:185], v[84:87]
	v_mfma_f32_16x16x32_bf16 v[80:83], v[214:217], v[182:185], v[80:83]
	v_mfma_f32_16x16x32_bf16 v[76:79], v[206:209], v[190:193], v[76:79]
	v_mfma_f32_16x16x32_bf16 v[72:75], v[214:217], v[190:193], v[72:75]
	v_mfma_f32_16x16x32_bf16 v[68:71], v[206:209], v[198:201], v[68:71]
	v_mfma_f32_16x16x32_bf16 v[64:67], v[214:217], v[198:201], v[64:67]
	v_mfma_f32_16x16x32_bf16 v[92:95], v[210:213], v[176:179], v[92:95]
	v_mfma_f32_16x16x32_bf16 v[88:91], v[218:221], v[176:179], v[88:91]
	v_mfma_f32_16x16x32_bf16 v[84:87], v[210:213], v[186:189], v[84:87]
	v_mfma_f32_16x16x32_bf16 v[80:83], v[218:221], v[186:189], v[80:83]
	v_mfma_f32_16x16x32_bf16 v[76:79], v[210:213], v[194:197], v[76:79]
	v_mfma_f32_16x16x32_bf16 v[72:75], v[218:221], v[194:197], v[72:75]
	s_setprio 2
	s_barrier
	v_mfma_f32_16x16x32_bf16 v[68:71], v[210:213], v[202:205], v[68:71]
	v_mfma_f32_16x16x32_bf16 v[64:67], v[218:221], v[202:205], v[64:67]
	s_setprio 0
	ds_read_b128 v[172:175], v148 offset:16384
	ds_read_b128 v[176:179], v148 offset:17408
	ds_read_b128 v[182:185], v148 offset:18432
	ds_read_b128 v[186:189], v148 offset:19456
	ds_read_b128 v[190:193], v148 offset:20480
	ds_read_b128 v[194:197], v148 offset:21504
	ds_read_b128 v[198:201], v148 offset:22528
	ds_read_b128 v[202:205], v148 offset:23552
	s_waitcnt vmcnt(4)
	s_barrier
	s_waitcnt lgkmcnt(0)
	s_setprio 1
	s_waitcnt lgkmcnt(0)
	v_mfma_f32_16x16x32_bf16 v[60:63], v[132:135], v[172:175], v[60:63]
	v_mfma_f32_16x16x32_bf16 v[56:59], v[164:167], v[172:175], v[56:59]
	v_mfma_f32_16x16x32_bf16 v[52:55], v[132:135], v[182:185], v[52:55]
	v_mfma_f32_16x16x32_bf16 v[48:51], v[164:167], v[182:185], v[48:51]
	v_mfma_f32_16x16x32_bf16 v[44:47], v[132:135], v[190:193], v[44:47]
	v_mfma_f32_16x16x32_bf16 v[40:43], v[164:167], v[190:193], v[40:43]
	v_mfma_f32_16x16x32_bf16 v[36:39], v[132:135], v[198:201], v[36:39]
	v_mfma_f32_16x16x32_bf16 v[32:35], v[164:167], v[198:201], v[32:35]
	v_mfma_f32_16x16x32_bf16 v[60:63], v[160:163], v[176:179], v[60:63]
	v_mfma_f32_16x16x32_bf16 v[56:59], v[168:171], v[176:179], v[56:59]
	v_mfma_f32_16x16x32_bf16 v[52:55], v[160:163], v[186:189], v[52:55]
	v_mfma_f32_16x16x32_bf16 v[48:51], v[168:171], v[186:189], v[48:51]
	v_mfma_f32_16x16x32_bf16 v[44:47], v[160:163], v[194:197], v[44:47]
	v_mfma_f32_16x16x32_bf16 v[40:43], v[168:171], v[194:197], v[40:43]
	v_mfma_f32_16x16x32_bf16 v[36:39], v[160:163], v[202:205], v[36:39]
	v_mfma_f32_16x16x32_bf16 v[32:35], v[168:171], v[202:205], v[32:35]
	s_setprio 0
	s_setprio 1
	v_mfma_f32_16x16x32_bf16 v[28:31], v[206:209], v[172:175], v[28:31]
	v_mfma_f32_16x16x32_bf16 v[24:27], v[214:217], v[172:175], v[24:27]
	v_mfma_f32_16x16x32_bf16 v[20:23], v[206:209], v[182:185], v[20:23]
	v_mfma_f32_16x16x32_bf16 v[16:19], v[214:217], v[182:185], v[16:19]
	v_mfma_f32_16x16x32_bf16 v[12:15], v[206:209], v[190:193], v[12:15]
	v_mfma_f32_16x16x32_bf16 v[8:11], v[214:217], v[190:193], v[8:11]
	v_mfma_f32_16x16x32_bf16 v[4:7], v[206:209], v[198:201], v[4:7]
	v_mfma_f32_16x16x32_bf16 v[0:3], v[214:217], v[198:201], v[0:3]
	v_mfma_f32_16x16x32_bf16 v[28:31], v[210:213], v[176:179], v[28:31]
	v_mfma_f32_16x16x32_bf16 v[24:27], v[218:221], v[176:179], v[24:27]
	v_mfma_f32_16x16x32_bf16 v[20:23], v[210:213], v[186:189], v[20:23]
	v_mfma_f32_16x16x32_bf16 v[16:19], v[218:221], v[186:189], v[16:19]
	v_mfma_f32_16x16x32_bf16 v[12:15], v[210:213], v[194:197], v[12:15]
	v_mfma_f32_16x16x32_bf16 v[8:11], v[218:221], v[194:197], v[8:11]
	s_setprio 2
	s_barrier
	v_mfma_f32_16x16x32_bf16 v[4:7], v[210:213], v[202:205], v[4:7]
	v_mfma_f32_16x16x32_bf16 v[0:3], v[218:221], v[202:205], v[0:3]
	s_setprio 0
	ds_read_b128 v[132:135], v149 offset:32768
	ds_read_b128 v[158:161], v149 offset:33792
	ds_read_b128 v[162:165], v149 offset:34816
	ds_read_b128 v[166:169], v149 offset:35840
	ds_read_b128 v[170:173], v148 offset:32768
	ds_read_b128 v[174:177], v148 offset:33792
	ds_read_b128 v[182:185], v148 offset:34816
	ds_read_b128 v[186:189], v148 offset:35840
	ds_read_b128 v[190:193], v148 offset:36864
	ds_read_b128 v[194:197], v148 offset:37888
	ds_read_b128 v[198:201], v148 offset:38912
	ds_read_b128 v[202:205], v148 offset:39936
	s_waitcnt vmcnt(2)
	s_barrier
; #define LDA(dst, b, h) for (int m = 0; m < 4; ++m) for (int k = 0; k < 2; ++k) \
;     dst[m][k] = *reinterpret_cast<const bf16x8*>(a_rd + ((b) * 2 + (h)) * (HT * 2) + m * 2048 + k * 1024)
; #define LDB(dst, b, h) for (int n = 0; n < 2; ++n) for (int k = 0; k < 2; ++k) \
;     dst[n][k] = *reinterpret_cast<const bf16x8*>(b_rd + ((b) * 2 + (h)) * (HT * 2) + n * 2048 + k * 1024)
; #define MMA(ai, bj, At_, Bt_) do { __builtin_amdgcn_s_setprio(1); \
;     for (int m = 0; m < 4; ++m) for (int n = 0; n < 2; ++n) for (int k = 0; k < 2; ++k) \
;       acc[ai][bj][m][n] = __builtin_amdgcn_mfma_f32_16x16x32_bf16(Bt_[n][k], At_[m][k], acc[ai][bj][m][n], 0, 0, 0); \
;     __builtin_amdgcn_s_setprio(0); } while (0)
; #define WAIT_V(n) asm volatile("s_waitcnt vmcnt(" #n ")" ::: "memory")
; #define WAIT_L(n) asm volatile("s_waitcnt lgkmcnt(" #n ")" ::: "memory")
; #define BAR __builtin_amdgcn_s_barrier()
;     ...
;   { LDB(B0, 1, 0); LDA(At, 1, 0); WAIT_V(2); BAR; WAIT_L(0); MMA(0, 0, At, B0); BAR;
;     LDB(B1, 1, 1); WAIT_V(0); BAR; WAIT_L(0); MMA(0, 1, At, B1); BAR;
;     LDA(At, 1, 1); BAR; WAIT_L(0); MMA(1, 0, At, B0); MMA(1, 1, At, B1); BAR; }
;   if (wr == 0) BAR;
	s_waitcnt lgkmcnt(0)
	s_setprio 1
	s_waitcnt lgkmcnt(0)
	v_mfma_f32_16x16x32_bf16 v[124:127], v[132:135], v[170:173], v[124:127]
	v_mfma_f32_16x16x32_bf16 v[120:123], v[162:165], v[170:173], v[120:123]
	v_mfma_f32_16x16x32_bf16 v[116:119], v[132:135], v[182:185], v[116:119]
	v_mfma_f32_16x16x32_bf16 v[112:115], v[162:165], v[182:185], v[112:115]
	v_mfma_f32_16x16x32_bf16 v[108:111], v[132:135], v[190:193], v[108:111]
	v_mfma_f32_16x16x32_bf16 v[104:107], v[162:165], v[190:193], v[104:107]
	v_mfma_f32_16x16x32_bf16 v[100:103], v[132:135], v[198:201], v[100:103]
	v_mfma_f32_16x16x32_bf16 v[96:99], v[162:165], v[198:201], v[96:99]
	v_mfma_f32_16x16x32_bf16 v[124:127], v[158:161], v[174:177], v[124:127]
	v_mfma_f32_16x16x32_bf16 v[120:123], v[166:169], v[174:177], v[120:123]
	v_mfma_f32_16x16x32_bf16 v[116:119], v[158:161], v[186:189], v[116:119]
	v_mfma_f32_16x16x32_bf16 v[112:115], v[166:169], v[186:189], v[112:115]
	v_mfma_f32_16x16x32_bf16 v[108:111], v[158:161], v[194:197], v[108:111]
	v_mfma_f32_16x16x32_bf16 v[104:107], v[166:169], v[194:197], v[104:107]
	s_setprio 2
	s_barrier
	v_mfma_f32_16x16x32_bf16 v[100:103], v[158:161], v[202:205], v[100:103]
	v_mfma_f32_16x16x32_bf16 v[96:99], v[166:169], v[202:205], v[96:99]
	s_setprio 0
	ds_read_b128 v[206:209], v149 offset:49152
	ds_read_b128 v[210:213], v149 offset:50176
	ds_read_b128 v[214:217], v149 offset:51200
	ds_read_b128 v[218:221], v149 offset:52224
	s_waitcnt vmcnt(0)
	s_barrier
	s_waitcnt lgkmcnt(0)
	s_setprio 1
	s_waitcnt lgkmcnt(0)
	v_mfma_f32_16x16x32_bf16 v[92:95], v[206:209], v[170:173], v[92:95]
	v_mfma_f32_16x16x32_bf16 v[88:91], v[214:217], v[170:173], v[88:91]
	v_mfma_f32_16x16x32_bf16 v[84:87], v[206:209], v[182:185], v[84:87]
	v_mfma_f32_16x16x32_bf16 v[80:83], v[214:217], v[182:185], v[80:83]
	v_mfma_f32_16x16x32_bf16 v[76:79], v[206:209], v[190:193], v[76:79]
	v_mfma_f32_16x16x32_bf16 v[72:75], v[214:217], v[190:193], v[72:75]
	v_mfma_f32_16x16x32_bf16 v[68:71], v[206:209], v[198:201], v[68:71]
	v_mfma_f32_16x16x32_bf16 v[64:67], v[214:217], v[198:201], v[64:67]
	v_mfma_f32_16x16x32_bf16 v[92:95], v[210:213], v[174:177], v[92:95]
	v_mfma_f32_16x16x32_bf16 v[88:91], v[218:221], v[174:177], v[88:91]
	v_mfma_f32_16x16x32_bf16 v[84:87], v[210:213], v[186:189], v[84:87]
	v_mfma_f32_16x16x32_bf16 v[80:83], v[218:221], v[186:189], v[80:83]
	v_mfma_f32_16x16x32_bf16 v[76:79], v[210:213], v[194:197], v[76:79]
	v_mfma_f32_16x16x32_bf16 v[72:75], v[218:221], v[194:197], v[72:75]
	s_setprio 2
	s_barrier
	v_mfma_f32_16x16x32_bf16 v[68:71], v[210:213], v[202:205], v[68:71]
	v_mfma_f32_16x16x32_bf16 v[64:67], v[218:221], v[202:205], v[64:67]
	s_setprio 0
	ds_read_b128 v[170:173], v148 offset:49152
	ds_read_b128 v[174:177], v148 offset:50176
	ds_read_b128 v[182:185], v148 offset:51200
	ds_read_b128 v[186:189], v148 offset:52224
	ds_read_b128 v[190:193], v148 offset:53248
	ds_read_b128 v[194:197], v148 offset:54272
	ds_read_b128 v[198:201], v148 offset:55296
	ds_read_b128 v[202:205], v148 offset:56320
	s_barrier
	s_waitcnt lgkmcnt(0)
	s_setprio 1
	s_waitcnt lgkmcnt(0)
	v_mfma_f32_16x16x32_bf16 v[60:63], v[132:135], v[170:173], v[60:63]
	v_mfma_f32_16x16x32_bf16 v[56:59], v[162:165], v[170:173], v[56:59]
	v_mfma_f32_16x16x32_bf16 v[52:55], v[132:135], v[182:185], v[52:55]
	v_mfma_f32_16x16x32_bf16 v[48:51], v[162:165], v[182:185], v[48:51]
	v_mfma_f32_16x16x32_bf16 v[44:47], v[132:135], v[190:193], v[44:47]
	v_mfma_f32_16x16x32_bf16 v[40:43], v[162:165], v[190:193], v[40:43]
	v_mfma_f32_16x16x32_bf16 v[36:39], v[132:135], v[198:201], v[36:39]
	v_mfma_f32_16x16x32_bf16 v[32:35], v[162:165], v[198:201], v[32:35]
	v_mfma_f32_16x16x32_bf16 v[60:63], v[158:161], v[174:177], v[60:63]
	v_mfma_f32_16x16x32_bf16 v[56:59], v[166:169], v[174:177], v[56:59]
	v_mfma_f32_16x16x32_bf16 v[52:55], v[158:161], v[186:189], v[52:55]
	v_mfma_f32_16x16x32_bf16 v[48:51], v[166:169], v[186:189], v[48:51]
	v_mfma_f32_16x16x32_bf16 v[44:47], v[158:161], v[194:197], v[44:47]
	v_mfma_f32_16x16x32_bf16 v[40:43], v[166:169], v[194:197], v[40:43]
	v_mfma_f32_16x16x32_bf16 v[36:39], v[158:161], v[202:205], v[36:39]
	v_mfma_f32_16x16x32_bf16 v[32:35], v[166:169], v[202:205], v[32:35]
	s_setprio 0
	s_setprio 1
	v_mfma_f32_16x16x32_bf16 v[28:31], v[206:209], v[170:173], v[28:31]
	v_mfma_f32_16x16x32_bf16 v[24:27], v[214:217], v[170:173], v[24:27]
	v_mfma_f32_16x16x32_bf16 v[20:23], v[206:209], v[182:185], v[20:23]
	v_mfma_f32_16x16x32_bf16 v[16:19], v[214:217], v[182:185], v[16:19]
	v_mfma_f32_16x16x32_bf16 v[12:15], v[206:209], v[190:193], v[12:15]
	v_mfma_f32_16x16x32_bf16 v[8:11], v[214:217], v[190:193], v[8:11]
	v_mfma_f32_16x16x32_bf16 v[4:7], v[206:209], v[198:201], v[4:7]
	v_mfma_f32_16x16x32_bf16 v[0:3], v[214:217], v[198:201], v[0:3]
	v_mfma_f32_16x16x32_bf16 v[28:31], v[210:213], v[174:177], v[28:31]
	v_mfma_f32_16x16x32_bf16 v[24:27], v[218:221], v[174:177], v[24:27]
	v_mfma_f32_16x16x32_bf16 v[20:23], v[210:213], v[186:189], v[20:23]
	v_mfma_f32_16x16x32_bf16 v[16:19], v[218:221], v[186:189], v[16:19]
	v_mfma_f32_16x16x32_bf16 v[12:15], v[210:213], v[194:197], v[12:15]
	v_mfma_f32_16x16x32_bf16 v[8:11], v[218:221], v[194:197], v[8:11]
	s_setprio 2
	s_barrier
	v_mfma_f32_16x16x32_bf16 v[4:7], v[210:213], v[202:205], v[4:7]
	v_mfma_f32_16x16x32_bf16 v[0:3], v[218:221], v[202:205], v[0:3]
	s_setprio 0
	v_cmp_gt_u32_e32 vcc, s60, v139
	s_and_saveexec_b64 s[26:27], vcc
	s_cbranch_execz .LBB0_1868
	s_barrier

; #define STAGE_A(P, br, kt) do { const char* _base = (const char*)(((kt) < G.ksplit ? G.A1 : A2m) + (long)(br) * G.lda + (long)(kt) * BK); \
;     __builtin_amdgcn_global_load_lds((const unsigned*)(_base + aoff0), (unsigned*)((char*)(P) + sb0), 16, 0, 0); \
;     __builtin_amdgcn_global_load_lds((const unsigned*)(_base + aoff1), (unsigned*)((char*)(P) + sb1), 16, 0, 0); } while (0)
; #define STAGE_B(P, br, kt) do { const char* _base = (const char*)(G.Bt + (long)(br) * G.ldb + (long)(kt) * BK); \
;     __builtin_amdgcn_global_load_lds((const unsigned*)(_base + boff0), (unsigned*)((char*)(P) + sb0), 16, 0, 0); \
;     __builtin_amdgcn_global_load_lds((const unsigned*)(_base + boff1), (unsigned*)((char*)(P) + sb1), 16, 0, 0); } while (0)
; #define LDA(dst, b, h) for (int m = 0; m < 4; ++m) for (int k = 0; k < 2; ++k) \
;     dst[m][k] = *reinterpret_cast<const bf16x8*>(a_rd + ((b) * 2 + (h)) * (HT * 2) + m * 2048 + k * 1024)
; #define LDB(dst, b, h) for (int n = 0; n < 2; ++n) for (int k = 0; k < 2; ++k) \
;     dst[n][k] = *reinterpret_cast<const bf16x8*>(b_rd + ((b) * 2 + (h)) * (HT * 2) + n * 2048 + k * 1024)
; #define MMA(ai, bj, At_, Bt_) do { __builtin_amdgcn_s_setprio(1); \
;     for (int m = 0; m < 4; ++m) for (int n = 0; n < 2; ++n) for (int k = 0; k < 2; ++k) \
;       acc[ai][bj][m][n] = __builtin_amdgcn_mfma_f32_16x16x32_bf16(Bt_[n][k], At_[m][k], acc[ai][bj][m][n], 0, 0, 0); \
;     __builtin_amdgcn_s_setprio(0); } while (0)
; #define WAIT_V(n) asm volatile("s_waitcnt vmcnt(" #n ")" ::: "memory")
; #define WAIT_L(n) asm volatile("s_waitcnt lgkmcnt(" #n ")" ::: "memory")
; #define BAR __builtin_amdgcn_s_barrier()
; #define SCHED __builtin_amdgcn_sched_barrier(0)
;     ...
;     LDB(B0, 0, 0); SCHED; LDA(At, 0, 0); STAGE_A(SA(1, 1), brow + HALF, t + 1);
;     WAIT_L(8); BAR; WAIT_L(0); MMA(0, 0, At, B0); BAR; SCHED;
;     LDB(B1, 0, 1); STAGE_B(SB(0, 0), bcol, t + 2);
;     BAR; WAIT_L(0); MMA(0, 1, At, B1); BAR;
;     LDA(At, 0, 1); STAGE_A(SA(0, 0), brow, t + 2);
;     BAR; WAIT_L(0); MMA(1, 0, At, B0); BAR; SCHED;
;     STAGE_B(SB(0, 1), bcol + HALF, t + 2);
;     WAIT_V(6); BAR; MMA(1, 1, At, B1); BAR;
;     LDB(B0, 1, 0); SCHED; LDA(At, 1, 0); STAGE_A(SA(0, 1), brow + HALF, t + 2);
.LBB0_2501:
	ds_read_b128 v[162:165], v149
	ds_read_b128 v[166:169], v149 offset:1024
	ds_read_b128 v[170:173], v149 offset:2048
	ds_read_b128 v[174:177], v149 offset:3072
	s_add_i32 s22, s22, 2
	s_cmp_lt_u32 s22, 16
	s_cselect_b32 s25, s28, s34
	s_cselect_b32 s24, s27, s31
	v_lshl_add_u64 v[160:161], s[24:25], 0, v[136:137]
	v_add_u32_e32 v159, 0xc000, v147
	v_lshl_add_u64 v[160:161], v[160:161], 0, s[10:11]
	v_readfirstlane_b32 s23, v159
	v_lshl_add_u64 v[160:161], v[160:161], 0, s[36:37]
	s_mov_b32 m0, s23
	ds_read_b128 v[182:185], v146
	ds_read_b128 v[186:189], v146 offset:1024
	ds_read_b128 v[190:193], v146 offset:2048
	ds_read_b128 v[194:197], v146 offset:3072
	ds_read_b128 v[198:201], v146 offset:4096
	ds_read_b128 v[202:205], v146 offset:5120
	ds_read_b128 v[206:209], v146 offset:6144
	ds_read_b128 v[210:213], v146 offset:7168
	global_load_lds_dwordx4 v[160:161], off
	v_lshl_add_u64 v[160:161], s[24:25], 0, v[138:139]
	v_lshl_add_u64 v[160:161], v[160:161], 0, s[10:11]
	v_lshl_add_u64 v[178:179], v[160:161], 0, s[36:37]
	v_add_u32_e32 v160, 0xe000, v147
	s_nop 0
	v_readfirstlane_b32 s23, v160
	s_mov_b32 m0, s23
	s_nop 0
	global_load_lds_dwordx4 v[178:179], off
	ds_read_b128 v[214:217], v149 offset:16384
	ds_read_b128 v[218:221], v149 offset:17408
	ds_read_b128 v[246:249], v149 offset:18432
	ds_read_b128 v[230:233], v149 offset:19456
	s_waitcnt lgkmcnt(0)
	s_waitcnt vmcnt(8)
	s_barrier
	s_setprio 1
	v_mfma_f32_16x16x32_bf16 v[124:127], v[162:165], v[182:185], v[124:127]
	v_mfma_f32_16x16x32_bf16 v[120:123], v[170:173], v[182:185], v[120:123]
	v_mfma_f32_16x16x32_bf16 v[116:119], v[162:165], v[190:193], v[116:119]
	v_mfma_f32_16x16x32_bf16 v[112:115], v[170:173], v[190:193], v[112:115]
	v_mfma_f32_16x16x32_bf16 v[108:111], v[162:165], v[198:201], v[108:111]
	v_mfma_f32_16x16x32_bf16 v[104:107], v[170:173], v[198:201], v[104:107]
	v_mfma_f32_16x16x32_bf16 v[100:103], v[162:165], v[206:209], v[100:103]
	v_mfma_f32_16x16x32_bf16 v[96:99], v[170:173], v[206:209], v[96:99]
	v_mfma_f32_16x16x32_bf16 v[124:127], v[166:169], v[186:189], v[124:127]
	v_mfma_f32_16x16x32_bf16 v[120:123], v[174:177], v[186:189], v[120:123]
	v_mfma_f32_16x16x32_bf16 v[116:119], v[166:169], v[194:197], v[116:119]
	v_mfma_f32_16x16x32_bf16 v[112:115], v[174:177], v[194:197], v[112:115]
	v_mfma_f32_16x16x32_bf16 v[108:111], v[166:169], v[202:205], v[108:111]
	v_mfma_f32_16x16x32_bf16 v[104:107], v[174:177], v[202:205], v[104:107]
	v_mfma_f32_16x16x32_bf16 v[100:103], v[166:169], v[210:213], v[100:103]
	v_mfma_f32_16x16x32_bf16 v[96:99], v[174:177], v[210:213], v[96:99]
	v_mfma_f32_16x16x32_bf16 v[92:95], v[214:217], v[182:185], v[92:95]
	v_mfma_f32_16x16x32_bf16 v[88:91], v[246:249], v[182:185], v[88:91]
	v_mfma_f32_16x16x32_bf16 v[84:87], v[214:217], v[190:193], v[84:87]
	v_mfma_f32_16x16x32_bf16 v[80:83], v[246:249], v[190:193], v[80:83]
	v_mfma_f32_16x16x32_bf16 v[76:79], v[214:217], v[198:201], v[76:79]
	v_mfma_f32_16x16x32_bf16 v[72:75], v[246:249], v[198:201], v[72:75]
	v_mfma_f32_16x16x32_bf16 v[68:71], v[214:217], v[206:209], v[68:71]
	v_mfma_f32_16x16x32_bf16 v[64:67], v[246:249], v[206:209], v[64:67]
	v_mfma_f32_16x16x32_bf16 v[92:95], v[218:221], v[186:189], v[92:95]
	v_mfma_f32_16x16x32_bf16 v[88:91], v[230:233], v[186:189], v[88:91]
	v_mfma_f32_16x16x32_bf16 v[84:87], v[218:221], v[194:197], v[84:87]
	v_mfma_f32_16x16x32_bf16 v[80:83], v[230:233], v[194:197], v[80:83]
	v_mfma_f32_16x16x32_bf16 v[76:79], v[218:221], v[202:205], v[76:79]
	v_mfma_f32_16x16x32_bf16 v[72:75], v[230:233], v[202:205], v[72:75]
	s_setprio 2
	s_barrier
	v_mfma_f32_16x16x32_bf16 v[68:71], v[218:221], v[210:213], v[68:71]
	v_mfma_f32_16x16x32_bf16 v[64:67], v[230:233], v[210:213], v[64:67]
	s_setprio 0
	v_lshl_add_u64 v[178:179], v[132:133], 0, s[10:11]
	v_readfirstlane_b32 s23, v145
	v_lshl_add_u64 v[222:223], v[178:179], 0, s[38:39]
	s_mov_b32 m0, s23
	v_add_u32_e32 v161, 0x2000, v145
	global_load_lds_dwordx4 v[222:223], off
	v_lshl_add_u64 v[222:223], v[134:135], 0, s[10:11]
	v_readfirstlane_b32 s23, v161
	v_lshl_add_u64 v[234:235], v[222:223], 0, s[38:39]
	s_mov_b32 m0, s23
	s_nop 0
	global_load_lds_dwordx4 v[234:235], off
	s_cmp_lt_u32 s22, 14
	s_cselect_b32 s25, s28, s34
	s_cselect_b32 s24, s27, s31
	v_lshl_add_u64 v[234:235], s[24:25], 0, v[136:137]
	v_lshl_add_u64 v[234:235], v[234:235], 0, s[10:11]
	v_readfirstlane_b32 s23, v147
	v_lshl_add_u64 v[236:237], v[234:235], 0, s[90:91]
	s_mov_b32 m0, s23
	ds_read_b128 v[182:185], v146 offset:16384
	ds_read_b128 v[186:189], v146 offset:17408
	ds_read_b128 v[190:193], v146 offset:18432
	ds_read_b128 v[194:197], v146 offset:19456
	ds_read_b128 v[198:201], v146 offset:20480
	ds_read_b128 v[202:205], v146 offset:21504
	ds_read_b128 v[206:209], v146 offset:22528
	ds_read_b128 v[210:213], v146 offset:23552
	global_load_lds_dwordx4 v[236:237], off
	v_lshl_add_u64 v[236:237], s[24:25], 0, v[138:139]
	v_lshl_add_u64 v[236:237], v[236:237], 0, s[10:11]
	v_readfirstlane_b32 s23, v148
	v_lshl_add_u64 v[238:239], v[236:237], 0, s[90:91]
	s_mov_b32 m0, s23
	s_nop 0
	global_load_lds_dwordx4 v[238:239], off
	v_lshl_add_u64 v[238:239], v[140:141], 0, s[10:11]
	v_readfirstlane_b32 s23, v150
	v_add_u32_e32 v161, 0x2000, v150
	v_lshl_add_u64 v[250:251], v[238:239], 0, s[40:41]
	s_mov_b32 m0, s23
	v_lshl_add_u64 v[240:241], v[142:143], 0, s[10:11]
	v_readfirstlane_b32 s23, v161
	global_load_lds_dwordx4 v[250:251], off
	v_lshl_add_u64 v[250:251], v[240:241], 0, s[40:41]
	s_mov_b32 m0, s23
	s_nop 0
	global_load_lds_dwordx4 v[250:251], off
	s_waitcnt lgkmcnt(0)
	s_waitcnt vmcnt(8)
	s_barrier
; #define STAGE_A(P, br, kt) do { const char* _base = (const char*)(((kt) < G.ksplit ? G.A1 : A2m) + (long)(br) * G.lda + (long)(kt) * BK); \
;     __builtin_amdgcn_global_load_lds((const unsigned*)(_base + aoff0), (unsigned*)((char*)(P) + sb0), 16, 0, 0); \
;     __builtin_amdgcn_global_load_lds((const unsigned*)(_base + aoff1), (unsigned*)((char*)(P) + sb1), 16, 0, 0); } while (0)
; #define STAGE_B(P, br, kt) do { const char* _base = (const char*)(G.Bt + (long)(br) * G.ldb + (long)(kt) * BK); \
;     __builtin_amdgcn_global_load_lds((const unsigned*)(_base + boff0), (unsigned*)((char*)(P) + sb0), 16, 0, 0); \
;     __builtin_amdgcn_global_load_lds((const unsigned*)(_base + boff1), (unsigned*)((char*)(P) + sb1), 16, 0, 0); } while (0)
; #define LDA(dst, b, h) for (int m = 0; m < 4; ++m) for (int k = 0; k < 2; ++k) \
;     dst[m][k] = *reinterpret_cast<const bf16x8*>(a_rd + ((b) * 2 + (h)) * (HT * 2) + m * 2048 + k * 1024)
; #define LDB(dst, b, h) for (int n = 0; n < 2; ++n) for (int k = 0; k < 2; ++k) \
;     dst[n][k] = *reinterpret_cast<const bf16x8*>(b_rd + ((b) * 2 + (h)) * (HT * 2) + n * 2048 + k * 1024)
; #define MMA(ai, bj, At_, Bt_) do { __builtin_amdgcn_s_setprio(1); \
;     for (int m = 0; m < 4; ++m) for (int n = 0; n < 2; ++n) for (int k = 0; k < 2; ++k) \
;       acc[ai][bj][m][n] = __builtin_amdgcn_mfma_f32_16x16x32_bf16(Bt_[n][k], At_[m][k], acc[ai][bj][m][n], 0, 0, 0); \
;     __builtin_amdgcn_s_setprio(0); } while (0)
; #define WAIT_V(n) asm volatile("s_waitcnt vmcnt(" #n ")" ::: "memory")
; #define WAIT_L(n) asm volatile("s_waitcnt lgkmcnt(" #n ")" ::: "memory")
; #define BAR __builtin_amdgcn_s_barrier()
; #define SCHED __builtin_amdgcn_sched_barrier(0)
;     ...
;     LDA(At, 0, 1); STAGE_A(SA(0, 0), brow, t + 2);
;     BAR; WAIT_L(0); MMA(1, 0, At, B0); BAR; SCHED;
;     STAGE_B(SB(0, 1), bcol + HALF, t + 2);
;     WAIT_V(6); BAR; MMA(1, 1, At, B1); BAR;
;     LDB(B0, 1, 0); SCHED; LDA(At, 1, 0); STAGE_A(SA(0, 1), brow + HALF, t + 2);
;     WAIT_L(8); BAR; WAIT_L(0); MMA(0, 0, At, B0); BAR; SCHED;
;     LDB(B1, 1, 1); STAGE_B(SB(1, 0), bcol, t + 3);
;     BAR; WAIT_L(0); MMA(0, 1, At, B1); BAR;
;     LDA(At, 1, 1); STAGE_A(SA(1, 0), brow, t + 3);
;     BAR; WAIT_L(0); MMA(1, 0, At, B0); BAR; SCHED;
	s_setprio 1
	v_mfma_f32_16x16x32_bf16 v[60:63], v[162:165], v[182:185], v[60:63]
	v_mfma_f32_16x16x32_bf16 v[56:59], v[170:173], v[182:185], v[56:59]
	v_mfma_f32_16x16x32_bf16 v[52:55], v[162:165], v[190:193], v[52:55]
	v_mfma_f32_16x16x32_bf16 v[48:51], v[170:173], v[190:193], v[48:51]
	v_mfma_f32_16x16x32_bf16 v[44:47], v[162:165], v[198:201], v[44:47]
	v_mfma_f32_16x16x32_bf16 v[40:43], v[170:173], v[198:201], v[40:43]
	v_mfma_f32_16x16x32_bf16 v[36:39], v[162:165], v[206:209], v[36:39]
	v_mfma_f32_16x16x32_bf16 v[32:35], v[170:173], v[206:209], v[32:35]
	v_mfma_f32_16x16x32_bf16 v[60:63], v[166:169], v[186:189], v[60:63]
	v_mfma_f32_16x16x32_bf16 v[56:59], v[174:177], v[186:189], v[56:59]
	v_mfma_f32_16x16x32_bf16 v[52:55], v[166:169], v[194:197], v[52:55]
	v_mfma_f32_16x16x32_bf16 v[48:51], v[174:177], v[194:197], v[48:51]
	v_mfma_f32_16x16x32_bf16 v[44:47], v[166:169], v[202:205], v[44:47]
	v_mfma_f32_16x16x32_bf16 v[40:43], v[174:177], v[202:205], v[40:43]
	v_mfma_f32_16x16x32_bf16 v[36:39], v[166:169], v[210:213], v[36:39]
	v_mfma_f32_16x16x32_bf16 v[32:35], v[174:177], v[210:213], v[32:35]
	v_mfma_f32_16x16x32_bf16 v[28:31], v[214:217], v[182:185], v[28:31]
	v_mfma_f32_16x16x32_bf16 v[24:27], v[246:249], v[182:185], v[24:27]
	v_mfma_f32_16x16x32_bf16 v[20:23], v[214:217], v[190:193], v[20:23]
	v_mfma_f32_16x16x32_bf16 v[16:19], v[246:249], v[190:193], v[16:19]
	v_mfma_f32_16x16x32_bf16 v[12:15], v[214:217], v[198:201], v[12:15]
	v_mfma_f32_16x16x32_bf16 v[8:11], v[246:249], v[198:201], v[8:11]
	v_mfma_f32_16x16x32_bf16 v[4:7], v[214:217], v[206:209], v[4:7]
	v_mfma_f32_16x16x32_bf16 v[0:3], v[246:249], v[206:209], v[0:3]
	v_mfma_f32_16x16x32_bf16 v[28:31], v[218:221], v[186:189], v[28:31]
	v_mfma_f32_16x16x32_bf16 v[24:27], v[230:233], v[186:189], v[24:27]
	v_mfma_f32_16x16x32_bf16 v[20:23], v[218:221], v[194:197], v[20:23]
	v_mfma_f32_16x16x32_bf16 v[16:19], v[230:233], v[194:197], v[16:19]
	v_mfma_f32_16x16x32_bf16 v[12:15], v[218:221], v[202:205], v[12:15]
	v_mfma_f32_16x16x32_bf16 v[8:11], v[230:233], v[202:205], v[8:11]
	s_setprio 2
	s_barrier
	v_mfma_f32_16x16x32_bf16 v[4:7], v[218:221], v[210:213], v[4:7]
	v_mfma_f32_16x16x32_bf16 v[0:3], v[230:233], v[210:213], v[0:3]
	s_setprio 0
	ds_read_b128 v[162:165], v149 offset:32768
	ds_read_b128 v[166:169], v149 offset:33792
	ds_read_b128 v[170:173], v149 offset:34816
	ds_read_b128 v[174:177], v149 offset:35840
	v_readfirstlane_b32 s23, v151
	v_lshl_add_u64 v[214:215], v[234:235], 0, s[42:43]
	s_mov_b32 m0, s23
	v_readfirstlane_b32 s23, v152
	ds_read_b128 v[182:185], v146 offset:32768
	ds_read_b128 v[186:189], v146 offset:33792
	ds_read_b128 v[190:193], v146 offset:34816
	ds_read_b128 v[194:197], v146 offset:35840
	ds_read_b128 v[198:201], v146 offset:36864
	ds_read_b128 v[202:205], v146 offset:37888
	ds_read_b128 v[206:209], v146 offset:38912
	ds_read_b128 v[210:213], v146 offset:39936
	global_load_lds_dwordx4 v[214:215], off
	v_lshl_add_u64 v[214:215], v[236:237], 0, s[42:43]
	s_mov_b32 m0, s23
	s_nop 0
	global_load_lds_dwordx4 v[214:215], off
	ds_read_b128 v[214:217], v149 offset:49152
	ds_read_b128 v[218:221], v149 offset:50176
	ds_read_b128 v[230:233], v149 offset:51200
	ds_read_b128 v[246:249], v149 offset:52224
	s_waitcnt lgkmcnt(0)
	s_waitcnt vmcnt(8)
	s_barrier
	s_setprio 1
	v_mfma_f32_16x16x32_bf16 v[124:127], v[162:165], v[182:185], v[124:127]
	v_mfma_f32_16x16x32_bf16 v[120:123], v[170:173], v[182:185], v[120:123]
	v_mfma_f32_16x16x32_bf16 v[116:119], v[162:165], v[190:193], v[116:119]
	v_mfma_f32_16x16x32_bf16 v[112:115], v[170:173], v[190:193], v[112:115]
	v_mfma_f32_16x16x32_bf16 v[108:111], v[162:165], v[198:201], v[108:111]
	v_mfma_f32_16x16x32_bf16 v[104:107], v[170:173], v[198:201], v[104:107]
	v_mfma_f32_16x16x32_bf16 v[100:103], v[162:165], v[206:209], v[100:103]
	v_mfma_f32_16x16x32_bf16 v[96:99], v[170:173], v[206:209], v[96:99]
	v_mfma_f32_16x16x32_bf16 v[124:127], v[166:169], v[186:189], v[124:127]
	v_mfma_f32_16x16x32_bf16 v[120:123], v[174:177], v[186:189], v[120:123]
	v_mfma_f32_16x16x32_bf16 v[116:119], v[166:169], v[194:197], v[116:119]
	v_mfma_f32_16x16x32_bf16 v[112:115], v[174:177], v[194:197], v[112:115]
	v_mfma_f32_16x16x32_bf16 v[108:111], v[166:169], v[202:205], v[108:111]
	v_mfma_f32_16x16x32_bf16 v[104:107], v[174:177], v[202:205], v[104:107]
	v_mfma_f32_16x16x32_bf16 v[100:103], v[166:169], v[210:213], v[100:103]
	v_mfma_f32_16x16x32_bf16 v[96:99], v[174:177], v[210:213], v[96:99]
	v_mfma_f32_16x16x32_bf16 v[92:95], v[214:217], v[182:185], v[92:95]
	v_mfma_f32_16x16x32_bf16 v[88:91], v[230:233], v[182:185], v[88:91]
	v_mfma_f32_16x16x32_bf16 v[84:87], v[214:217], v[190:193], v[84:87]
	v_mfma_f32_16x16x32_bf16 v[80:83], v[230:233], v[190:193], v[80:83]
	v_mfma_f32_16x16x32_bf16 v[76:79], v[214:217], v[198:201], v[76:79]
	v_mfma_f32_16x16x32_bf16 v[72:75], v[230:233], v[198:201], v[72:75]
	v_mfma_f32_16x16x32_bf16 v[68:71], v[214:217], v[206:209], v[68:71]
	v_mfma_f32_16x16x32_bf16 v[64:67], v[230:233], v[206:209], v[64:67]
	v_mfma_f32_16x16x32_bf16 v[92:95], v[218:221], v[186:189], v[92:95]
	v_mfma_f32_16x16x32_bf16 v[88:91], v[246:249], v[186:189], v[88:91]
	v_mfma_f32_16x16x32_bf16 v[84:87], v[218:221], v[194:197], v[84:87]
	v_mfma_f32_16x16x32_bf16 v[80:83], v[246:249], v[194:197], v[80:83]
	v_mfma_f32_16x16x32_bf16 v[76:79], v[218:221], v[202:205], v[76:79]
	v_mfma_f32_16x16x32_bf16 v[72:75], v[246:249], v[202:205], v[72:75]
	s_setprio 2
	s_barrier
; #define STAGE_A(P, br, kt) do { const char* _base = (const char*)(((kt) < G.ksplit ? G.A1 : A2m) + (long)(br) * G.lda + (long)(kt) * BK); \
;     __builtin_amdgcn_global_load_lds((const unsigned*)(_base + aoff0), (unsigned*)((char*)(P) + sb0), 16, 0, 0); \
;     __builtin_amdgcn_global_load_lds((const unsigned*)(_base + aoff1), (unsigned*)((char*)(P) + sb1), 16, 0, 0); } while (0)
; #define STAGE_B(P, br, kt) do { const char* _base = (const char*)(G.Bt + (long)(br) * G.ldb + (long)(kt) * BK); \
;     __builtin_amdgcn_global_load_lds((const unsigned*)(_base + boff0), (unsigned*)((char*)(P) + sb0), 16, 0, 0); \
;     __builtin_amdgcn_global_load_lds((const unsigned*)(_base + boff1), (unsigned*)((char*)(P) + sb1), 16, 0, 0); } while (0)
; #define LDA(dst, b, h) for (int m = 0; m < 4; ++m) for (int k = 0; k < 2; ++k) \
;     dst[m][k] = *reinterpret_cast<const bf16x8*>(a_rd + ((b) * 2 + (h)) * (HT * 2) + m * 2048 + k * 1024)
; #define LDB(dst, b, h) for (int n = 0; n < 2; ++n) for (int k = 0; k < 2; ++k) \
;     dst[n][k] = *reinterpret_cast<const bf16x8*>(b_rd + ((b) * 2 + (h)) * (HT * 2) + n * 2048 + k * 1024)
; #define MMA(ai, bj, At_, Bt_) do { __builtin_amdgcn_s_setprio(1); \
;     for (int m = 0; m < 4; ++m) for (int n = 0; n < 2; ++n) for (int k = 0; k < 2; ++k) \
;       acc[ai][bj][m][n] = __builtin_amdgcn_mfma_f32_16x16x32_bf16(Bt_[n][k], At_[m][k], acc[ai][bj][m][n], 0, 0, 0); \
;     __builtin_amdgcn_s_setprio(0); } while (0)
; #define WAIT_V(n) asm volatile("s_waitcnt vmcnt(" #n ")" ::: "memory")
; #define WAIT_L(n) asm volatile("s_waitcnt lgkmcnt(" #n ")" ::: "memory")
; #define BAR __builtin_amdgcn_s_barrier()
; #define SCHED __builtin_amdgcn_sched_barrier(0)
;     ...
;     LDB(B1, 1, 1); STAGE_B(SB(1, 0), bcol, t + 3);
;     BAR; WAIT_L(0); MMA(0, 1, At, B1); BAR;
;     LDA(At, 1, 1); STAGE_A(SA(1, 0), brow, t + 3);
;     BAR; WAIT_L(0); MMA(1, 0, At, B0); BAR; SCHED;
;     STAGE_B(SB(1, 1), bcol + HALF, t + 3);
;     WAIT_V(6); BAR; MMA(1, 1, At, B1); BAR;
;   }
;   float ssv[2][4] = {};
;   if constexpr (EPI == EPI_GU || EPI == EPI_EVIN || EPI == EPI_ODIN) {
; #pragma unroll
;     for (int ai = 0; ai < 2; ++ai)
; #pragma unroll
;       for (int m = 0; m < 4; ++m) ssv[ai][m] = G.ssr[brow + ai * HALF + wr * 64 + m * 16 + fr];
;   }
;   { LDB(B0, 0, 0); LDA(At, 0, 0); STAGE_A(SA(1, 1), brow + HALF, nt - 1);
	v_mfma_f32_16x16x32_bf16 v[68:71], v[218:221], v[210:213], v[68:71]
	v_mfma_f32_16x16x32_bf16 v[64:67], v[246:249], v[210:213], v[64:67]
	s_setprio 0
	v_readfirstlane_b32 s23, v153
	v_lshl_add_u64 v[178:179], v[178:179], 0, s[44:45]
	s_mov_b32 m0, s23
	v_readfirstlane_b32 s23, v154
	global_load_lds_dwordx4 v[178:179], off
	v_lshl_add_u64 v[178:179], v[222:223], 0, s[44:45]
	s_mov_b32 m0, s23
	s_nop 0
	global_load_lds_dwordx4 v[178:179], off
	s_cmp_lt_u32 s22, 13
	s_cselect_b32 s25, s28, s34
	s_cselect_b32 s24, s27, s31
	v_lshl_add_u64 v[178:179], s[24:25], 0, v[136:137]
	v_lshl_add_u64 v[178:179], v[178:179], 0, s[10:11]
	v_readfirstlane_b32 s23, v155
	v_lshl_add_u64 v[178:179], v[178:179], 0, s[88:89]
	s_mov_b32 m0, s23
	ds_read_b128 v[182:185], v146 offset:49152
	ds_read_b128 v[186:189], v146 offset:50176
	ds_read_b128 v[190:193], v146 offset:51200
	ds_read_b128 v[194:197], v146 offset:52224
	ds_read_b128 v[198:201], v146 offset:53248
	ds_read_b128 v[202:205], v146 offset:54272
	ds_read_b128 v[206:209], v146 offset:55296
	ds_read_b128 v[210:213], v146 offset:56320
	global_load_lds_dwordx4 v[178:179], off
	v_lshl_add_u64 v[178:179], s[24:25], 0, v[138:139]
	v_lshl_add_u64 v[178:179], v[178:179], 0, s[10:11]
	v_readfirstlane_b32 s23, v156
	v_lshl_add_u64 v[178:179], v[178:179], 0, s[88:89]
	s_mov_b32 m0, s23
	s_nop 0
	global_load_lds_dwordx4 v[178:179], off
	v_readfirstlane_b32 s23, v157
	v_lshl_add_u64 v[250:251], v[238:239], 0, s[46:47]
	s_mov_b32 m0, s23
	v_readfirstlane_b32 s23, v158
	global_load_lds_dwordx4 v[250:251], off
	v_lshl_add_u64 v[250:251], v[240:241], 0, s[46:47]
	s_mov_b32 m0, s23
	s_nop 0
	global_load_lds_dwordx4 v[250:251], off
	s_waitcnt lgkmcnt(0)
	s_waitcnt vmcnt(8)
	s_barrier
	s_setprio 1
	v_mfma_f32_16x16x32_bf16 v[60:63], v[162:165], v[182:185], v[60:63]
	v_mfma_f32_16x16x32_bf16 v[56:59], v[170:173], v[182:185], v[56:59]
	v_mfma_f32_16x16x32_bf16 v[52:55], v[162:165], v[190:193], v[52:55]
	v_mfma_f32_16x16x32_bf16 v[48:51], v[170:173], v[190:193], v[48:51]
	v_mfma_f32_16x16x32_bf16 v[44:47], v[162:165], v[198:201], v[44:47]
	v_mfma_f32_16x16x32_bf16 v[40:43], v[170:173], v[198:201], v[40:43]
	v_mfma_f32_16x16x32_bf16 v[36:39], v[162:165], v[206:209], v[36:39]
	v_mfma_f32_16x16x32_bf16 v[32:35], v[170:173], v[206:209], v[32:35]
	v_mfma_f32_16x16x32_bf16 v[60:63], v[166:169], v[186:189], v[60:63]
	v_mfma_f32_16x16x32_bf16 v[56:59], v[174:177], v[186:189], v[56:59]
	v_mfma_f32_16x16x32_bf16 v[52:55], v[166:169], v[194:197], v[52:55]
	v_mfma_f32_16x16x32_bf16 v[48:51], v[174:177], v[194:197], v[48:51]
	v_mfma_f32_16x16x32_bf16 v[44:47], v[166:169], v[202:205], v[44:47]
	v_mfma_f32_16x16x32_bf16 v[40:43], v[174:177], v[202:205], v[40:43]
	v_mfma_f32_16x16x32_bf16 v[36:39], v[166:169], v[210:213], v[36:39]
	v_mfma_f32_16x16x32_bf16 v[32:35], v[174:177], v[210:213], v[32:35]
	v_mfma_f32_16x16x32_bf16 v[28:31], v[214:217], v[182:185], v[28:31]
	v_mfma_f32_16x16x32_bf16 v[24:27], v[230:233], v[182:185], v[24:27]
	v_mfma_f32_16x16x32_bf16 v[20:23], v[214:217], v[190:193], v[20:23]
	v_mfma_f32_16x16x32_bf16 v[16:19], v[230:233], v[190:193], v[16:19]
	v_mfma_f32_16x16x32_bf16 v[12:15], v[214:217], v[198:201], v[12:15]
	v_mfma_f32_16x16x32_bf16 v[8:11], v[230:233], v[198:201], v[8:11]
	v_mfma_f32_16x16x32_bf16 v[4:7], v[214:217], v[206:209], v[4:7]
	v_mfma_f32_16x16x32_bf16 v[0:3], v[230:233], v[206:209], v[0:3]
	v_mfma_f32_16x16x32_bf16 v[28:31], v[218:221], v[186:189], v[28:31]
	v_mfma_f32_16x16x32_bf16 v[24:27], v[246:249], v[186:189], v[24:27]
	v_mfma_f32_16x16x32_bf16 v[20:23], v[218:221], v[194:197], v[20:23]
	v_mfma_f32_16x16x32_bf16 v[16:19], v[246:249], v[194:197], v[16:19]
	v_mfma_f32_16x16x32_bf16 v[12:15], v[218:221], v[202:205], v[12:15]
	v_mfma_f32_16x16x32_bf16 v[8:11], v[246:249], v[202:205], v[8:11]
	s_setprio 2
	s_barrier
	v_mfma_f32_16x16x32_bf16 v[4:7], v[218:221], v[210:213], v[4:7]
	v_mfma_f32_16x16x32_bf16 v[0:3], v[246:249], v[210:213], v[0:3]
	s_setprio 0
	s_add_u32 s10, s10, 0x100
	s_addc_u32 s11, s11, 0
	s_cmp_lt_u32 s22, 28
	s_cbranch_scc1 .LBB0_2501
	s_waitcnt vmcnt(6)
	v_not_b32_e32 v250, 63
	v_mov_b32_e32 v251, 0x41b17218
	s_lshl_b64 s[8:9], s[8:9], 1
	s_add_u32 s8, s31, s8
	s_addc_u32 s9, s34, s9
	v_lshl_add_u64 v[130:131], s[8:9], 0, v[130:131]
	v_readfirstlane_b32 s10, v159
	v_lshl_add_u64 v[130:131], v[130:131], 0, s[52:53]
	s_mov_b32 m0, s10
	v_lshl_add_u64 v[128:129], s[8:9], 0, v[128:129]
	v_readfirstlane_b32 s8, v160
	ds_read_b128 v[132:135], v149
	ds_read_b128 v[136:139], v149 offset:1024
	ds_read_b128 v[140:143], v149 offset:2048
	ds_read_b128 v[150:153], v149 offset:3072
	ds_read_b128 v[154:157], v146
	ds_read_b128 v[162:165], v146 offset:1024
	ds_read_b128 v[166:169], v146 offset:2048
	ds_read_b128 v[170:173], v146 offset:3072
	ds_read_b128 v[174:177], v146 offset:4096
	ds_read_b128 v[182:185], v146 offset:5120
	ds_read_b128 v[186:189], v146 offset:6144
	ds_read_b128 v[190:193], v146 offset:7168
	global_load_lds_dwordx4 v[130:131], off
	v_lshl_add_u64 v[128:129], v[128:129], 0, s[52:53]
	s_mov_b32 m0, s8
	s_nop 0
	global_load_lds_dwordx4 v[128:129], off
	s_barrier
; #define STAGE_A(P, br, kt) do { const char* _base = (const char*)(((kt) < G.ksplit ? G.A1 : A2m) + (long)(br) * G.lda + (long)(kt) * BK); \
;     __builtin_amdgcn_global_load_lds((const unsigned*)(_base + aoff0), (unsigned*)((char*)(P) + sb0), 16, 0, 0); \
;     __builtin_amdgcn_global_load_lds((const unsigned*)(_base + aoff1), (unsigned*)((char*)(P) + sb1), 16, 0, 0); } while (0)
; #define LDA(dst, b, h) for (int m = 0; m < 4; ++m) for (int k = 0; k < 2; ++k) \
;     dst[m][k] = *reinterpret_cast<const bf16x8*>(a_rd + ((b) * 2 + (h)) * (HT * 2) + m * 2048 + k * 1024)
; #define LDB(dst, b, h) for (int n = 0; n < 2; ++n) for (int k = 0; k < 2; ++k) \
;     dst[n][k] = *reinterpret_cast<const bf16x8*>(b_rd + ((b) * 2 + (h)) * (HT * 2) + n * 2048 + k * 1024)
; #define MMA(ai, bj, At_, Bt_) do { __builtin_amdgcn_s_setprio(1); \
;     for (int m = 0; m < 4; ++m) for (int n = 0; n < 2; ++n) for (int k = 0; k < 2; ++k) \
;       acc[ai][bj][m][n] = __builtin_amdgcn_mfma_f32_16x16x32_bf16(Bt_[n][k], At_[m][k], acc[ai][bj][m][n], 0, 0, 0); \
;     __builtin_amdgcn_s_setprio(0); } while (0)
; #define WAIT_V(n) asm volatile("s_waitcnt vmcnt(" #n ")" ::: "memory")
; #define WAIT_L(n) asm volatile("s_waitcnt lgkmcnt(" #n ")" ::: "memory")
; #define BAR __builtin_amdgcn_s_barrier()
;     ...
;   { LDB(B0, 0, 0); LDA(At, 0, 0); STAGE_A(SA(1, 1), brow + HALF, nt - 1);
;     BAR; WAIT_L(0); MMA(0, 0, At, B0); BAR;
;     LDB(B1, 0, 1); BAR; WAIT_L(0); MMA(0, 1, At, B1); BAR;
;     LDA(At, 0, 1); WAIT_V(4); BAR; WAIT_L(0); MMA(1, 0, At, B0); MMA(1, 1, At, B1); BAR; }
;   { LDB(B0, 1, 0); LDA(At, 1, 0); WAIT_V(2); BAR; WAIT_L(0); MMA(0, 0, At, B0); BAR;
	s_waitcnt lgkmcnt(0)
	s_setprio 1
	s_waitcnt lgkmcnt(0)
	v_mfma_f32_16x16x32_bf16 v[124:127], v[132:135], v[154:157], v[124:127]
	v_mfma_f32_16x16x32_bf16 v[120:123], v[140:143], v[154:157], v[120:123]
	v_mfma_f32_16x16x32_bf16 v[116:119], v[132:135], v[166:169], v[116:119]
	v_mfma_f32_16x16x32_bf16 v[112:115], v[140:143], v[166:169], v[112:115]
	v_mfma_f32_16x16x32_bf16 v[108:111], v[132:135], v[174:177], v[108:111]
	v_mfma_f32_16x16x32_bf16 v[104:107], v[140:143], v[174:177], v[104:107]
	v_mfma_f32_16x16x32_bf16 v[100:103], v[132:135], v[186:189], v[100:103]
	v_mfma_f32_16x16x32_bf16 v[96:99], v[140:143], v[186:189], v[96:99]
	v_mfma_f32_16x16x32_bf16 v[124:127], v[136:139], v[162:165], v[124:127]
	v_mfma_f32_16x16x32_bf16 v[120:123], v[150:153], v[162:165], v[120:123]
	v_mfma_f32_16x16x32_bf16 v[116:119], v[136:139], v[170:173], v[116:119]
	v_mfma_f32_16x16x32_bf16 v[112:115], v[150:153], v[170:173], v[112:115]
	v_mfma_f32_16x16x32_bf16 v[108:111], v[136:139], v[182:185], v[108:111]
	v_mfma_f32_16x16x32_bf16 v[104:107], v[150:153], v[182:185], v[104:107]
	s_setprio 2
	s_barrier
	v_mfma_f32_16x16x32_bf16 v[100:103], v[136:139], v[190:193], v[100:103]
	v_mfma_f32_16x16x32_bf16 v[96:99], v[150:153], v[190:193], v[96:99]
	s_setprio 0
	ds_read_b128 v[128:131], v149 offset:16384
	ds_read_b128 v[158:161], v149 offset:17408
	ds_read_b128 v[194:197], v149 offset:18432
	ds_read_b128 v[198:201], v149 offset:19456
	s_barrier
	s_waitcnt lgkmcnt(0)
	s_setprio 1
	s_waitcnt lgkmcnt(0)
	v_mfma_f32_16x16x32_bf16 v[92:95], v[128:131], v[154:157], v[92:95]
	v_mfma_f32_16x16x32_bf16 v[88:91], v[194:197], v[154:157], v[88:91]
	v_mfma_f32_16x16x32_bf16 v[84:87], v[128:131], v[166:169], v[84:87]
	v_mfma_f32_16x16x32_bf16 v[80:83], v[194:197], v[166:169], v[80:83]
	v_mfma_f32_16x16x32_bf16 v[76:79], v[128:131], v[174:177], v[76:79]
	v_mfma_f32_16x16x32_bf16 v[72:75], v[194:197], v[174:177], v[72:75]
	v_mfma_f32_16x16x32_bf16 v[68:71], v[128:131], v[186:189], v[68:71]
	v_mfma_f32_16x16x32_bf16 v[64:67], v[194:197], v[186:189], v[64:67]
	v_mfma_f32_16x16x32_bf16 v[202:205], v[158:161], v[162:165], v[92:95]
	v_mfma_f32_16x16x32_bf16 v[154:157], v[198:201], v[162:165], v[88:91]
	v_mfma_f32_16x16x32_bf16 v[162:165], v[158:161], v[170:173], v[84:87]
	v_mfma_f32_16x16x32_bf16 v[166:169], v[198:201], v[170:173], v[80:83]
	v_mfma_f32_16x16x32_bf16 v[170:173], v[158:161], v[182:185], v[76:79]
	v_mfma_f32_16x16x32_bf16 v[174:177], v[198:201], v[182:185], v[72:75]
	s_setprio 2
	s_barrier
	v_mfma_f32_16x16x32_bf16 v[182:185], v[158:161], v[190:193], v[68:71]
	v_mfma_f32_16x16x32_bf16 v[186:189], v[198:201], v[190:193], v[64:67]
	s_setprio 0
	s_nop 0
	ds_read_b128 v[64:67], v146 offset:16384
	ds_read_b128 v[68:71], v146 offset:17408
	ds_read_b128 v[72:75], v146 offset:18432
	ds_read_b128 v[76:79], v146 offset:19456
	ds_read_b128 v[80:83], v146 offset:20480
	ds_read_b128 v[84:87], v146 offset:21504
	ds_read_b128 v[88:91], v146 offset:22528
	ds_read_b128 v[92:95], v146 offset:23552
	s_waitcnt vmcnt(4)
	s_barrier
	s_waitcnt lgkmcnt(0)
	s_setprio 1
	s_waitcnt lgkmcnt(0)
	v_mfma_f32_16x16x32_bf16 v[60:63], v[132:135], v[64:67], v[60:63]
	v_mfma_f32_16x16x32_bf16 v[56:59], v[140:143], v[64:67], v[56:59]
	v_mfma_f32_16x16x32_bf16 v[52:55], v[132:135], v[72:75], v[52:55]
	v_mfma_f32_16x16x32_bf16 v[48:51], v[140:143], v[72:75], v[48:51]
	v_mfma_f32_16x16x32_bf16 v[44:47], v[132:135], v[80:83], v[44:47]
	v_mfma_f32_16x16x32_bf16 v[40:43], v[140:143], v[80:83], v[40:43]
	v_mfma_f32_16x16x32_bf16 v[36:39], v[132:135], v[88:91], v[36:39]
	v_mfma_f32_16x16x32_bf16 v[32:35], v[140:143], v[88:91], v[32:35]
	v_mfma_f32_16x16x32_bf16 v[60:63], v[136:139], v[68:71], v[60:63]
	v_mfma_f32_16x16x32_bf16 v[56:59], v[150:153], v[68:71], v[56:59]
	v_mfma_f32_16x16x32_bf16 v[52:55], v[136:139], v[76:79], v[52:55]
	v_mfma_f32_16x16x32_bf16 v[48:51], v[150:153], v[76:79], v[48:51]
	v_mfma_f32_16x16x32_bf16 v[44:47], v[136:139], v[84:87], v[44:47]
	v_mfma_f32_16x16x32_bf16 v[40:43], v[150:153], v[84:87], v[40:43]
	v_mfma_f32_16x16x32_bf16 v[36:39], v[136:139], v[92:95], v[36:39]
	v_mfma_f32_16x16x32_bf16 v[32:35], v[150:153], v[92:95], v[32:35]
	s_setprio 0
	s_setprio 1
	v_mfma_f32_16x16x32_bf16 v[28:31], v[128:131], v[64:67], v[28:31]
	v_mfma_f32_16x16x32_bf16 v[24:27], v[194:197], v[64:67], v[24:27]
	v_mfma_f32_16x16x32_bf16 v[20:23], v[128:131], v[72:75], v[20:23]
	v_mfma_f32_16x16x32_bf16 v[16:19], v[194:197], v[72:75], v[16:19]
	v_mfma_f32_16x16x32_bf16 v[12:15], v[128:131], v[80:83], v[12:15]
	v_mfma_f32_16x16x32_bf16 v[8:11], v[194:197], v[80:83], v[8:11]
	v_mfma_f32_16x16x32_bf16 v[4:7], v[128:131], v[88:91], v[4:7]
	v_mfma_f32_16x16x32_bf16 v[0:3], v[194:197], v[88:91], v[0:3]
	v_mfma_f32_16x16x32_bf16 v[132:135], v[158:161], v[68:71], v[28:31]
	v_mfma_f32_16x16x32_bf16 v[136:139], v[198:201], v[68:71], v[24:27]
	v_mfma_f32_16x16x32_bf16 v[140:143], v[158:161], v[76:79], v[20:23]
	v_mfma_f32_16x16x32_bf16 v[150:153], v[198:201], v[76:79], v[16:19]
	v_mfma_f32_16x16x32_bf16 v[190:193], v[158:161], v[84:87], v[12:15]
	v_mfma_f32_16x16x32_bf16 v[206:209], v[198:201], v[84:87], v[8:11]
	s_setprio 2
	s_barrier
	v_mfma_f32_16x16x32_bf16 v[128:131], v[158:161], v[92:95], v[4:7]
	v_mfma_f32_16x16x32_bf16 v[158:161], v[198:201], v[92:95], v[0:3]
	s_setprio 0
	ds_read_b128 v[24:27], v149 offset:32768
	ds_read_b128 v[28:31], v149 offset:33792
	ds_read_b128 v[194:197], v149 offset:34816
	ds_read_b128 v[198:201], v149 offset:35840
	ds_read_b128 v[0:3], v146 offset:32768
	ds_read_b128 v[4:7], v146 offset:33792
	ds_read_b128 v[8:11], v146 offset:34816
	ds_read_b128 v[12:15], v146 offset:35840
	ds_read_b128 v[16:19], v146 offset:36864
	ds_read_b128 v[20:23], v146 offset:37888
	ds_read_b128 v[210:213], v146 offset:38912
	ds_read_b128 v[214:217], v146 offset:39936
	s_waitcnt vmcnt(2)
	s_barrier
; #define LDA(dst, b, h) for (int m = 0; m < 4; ++m) for (int k = 0; k < 2; ++k) \
;     dst[m][k] = *reinterpret_cast<const bf16x8*>(a_rd + ((b) * 2 + (h)) * (HT * 2) + m * 2048 + k * 1024)
; #define LDB(dst, b, h) for (int n = 0; n < 2; ++n) for (int k = 0; k < 2; ++k) \
;     dst[n][k] = *reinterpret_cast<const bf16x8*>(b_rd + ((b) * 2 + (h)) * (HT * 2) + n * 2048 + k * 1024)
; #define MMA(ai, bj, At_, Bt_) do { __builtin_amdgcn_s_setprio(1); \
;     for (int m = 0; m < 4; ++m) for (int n = 0; n < 2; ++n) for (int k = 0; k < 2; ++k) \
;       acc[ai][bj][m][n] = __builtin_amdgcn_mfma_f32_16x16x32_bf16(Bt_[n][k], At_[m][k], acc[ai][bj][m][n], 0, 0, 0); \
;     __builtin_amdgcn_s_setprio(0); } while (0)
; #define WAIT_V(n) asm volatile("s_waitcnt vmcnt(" #n ")" ::: "memory")
; #define WAIT_L(n) asm volatile("s_waitcnt lgkmcnt(" #n ")" ::: "memory")
; #define BAR __builtin_amdgcn_s_barrier()
;     ...
;   { LDB(B0, 1, 0); LDA(At, 1, 0); WAIT_V(2); BAR; WAIT_L(0); MMA(0, 0, At, B0); BAR;
;     LDB(B1, 1, 1); WAIT_V(0); BAR; WAIT_L(0); MMA(0, 1, At, B1); BAR;
;     LDA(At, 1, 1); BAR; WAIT_L(0); MMA(1, 0, At, B0); MMA(1, 1, At, B1); BAR; }
;   if (wr == 0) BAR;
	s_waitcnt lgkmcnt(0)
	s_setprio 1
	s_waitcnt lgkmcnt(0)
	v_mfma_f32_16x16x32_bf16 v[64:67], v[24:27], v[0:3], v[124:127]
	v_mfma_f32_16x16x32_bf16 v[68:71], v[194:197], v[0:3], v[120:123]
	v_mfma_f32_16x16x32_bf16 v[72:75], v[24:27], v[8:11], v[116:119]
	v_mfma_f32_16x16x32_bf16 v[76:79], v[194:197], v[8:11], v[112:115]
	v_mfma_f32_16x16x32_bf16 v[80:83], v[24:27], v[16:19], v[108:111]
	v_mfma_f32_16x16x32_bf16 v[84:87], v[194:197], v[16:19], v[104:107]
	v_mfma_f32_16x16x32_bf16 v[88:91], v[24:27], v[210:213], v[100:103]
	v_mfma_f32_16x16x32_bf16 v[92:95], v[194:197], v[210:213], v[96:99]
	v_mfma_f32_16x16x32_bf16 v[64:67], v[28:31], v[4:7], v[64:67]
	v_mfma_f32_16x16x32_bf16 v[68:71], v[198:201], v[4:7], v[68:71]
	v_mfma_f32_16x16x32_bf16 v[72:75], v[28:31], v[12:15], v[72:75]
	v_mfma_f32_16x16x32_bf16 v[76:79], v[198:201], v[12:15], v[76:79]
	v_mfma_f32_16x16x32_bf16 v[80:83], v[28:31], v[20:23], v[80:83]
	v_mfma_f32_16x16x32_bf16 v[84:87], v[198:201], v[20:23], v[84:87]
	s_setprio 2
	s_barrier
	v_mfma_f32_16x16x32_bf16 v[88:91], v[28:31], v[214:217], v[88:91]
	v_mfma_f32_16x16x32_bf16 v[92:95], v[198:201], v[214:217], v[92:95]
	s_setprio 0
	ds_read_b128 v[218:221], v149 offset:49152
	ds_read_b128 v[230:233], v149 offset:50176
	ds_read_b128 v[246:249], v149 offset:51200
	ds_read_b128 v[238:241], v149 offset:52224
	s_waitcnt vmcnt(0)
	s_barrier
	s_waitcnt lgkmcnt(0)
	s_setprio 1
	s_waitcnt lgkmcnt(0)
	v_mfma_f32_16x16x32_bf16 v[96:99], v[218:221], v[0:3], v[202:205]
	v_mfma_f32_16x16x32_bf16 v[0:3], v[246:249], v[0:3], v[154:157]
	v_mfma_f32_16x16x32_bf16 v[100:103], v[238:241], v[4:7], v[0:3]
	v_mfma_f32_16x16x32_bf16 v[0:3], v[218:221], v[8:11], v[162:165]
	v_mfma_f32_16x16x32_bf16 v[104:107], v[230:233], v[12:15], v[0:3]
	v_mfma_f32_16x16x32_bf16 v[0:3], v[246:249], v[8:11], v[166:169]
	v_mfma_f32_16x16x32_bf16 v[108:111], v[238:241], v[12:15], v[0:3]
	v_mfma_f32_16x16x32_bf16 v[0:3], v[218:221], v[16:19], v[170:173]
	v_mfma_f32_16x16x32_bf16 v[112:115], v[230:233], v[20:23], v[0:3]
	v_mfma_f32_16x16x32_bf16 v[0:3], v[246:249], v[16:19], v[174:177]
	v_mfma_f32_16x16x32_bf16 v[116:119], v[238:241], v[20:23], v[0:3]
	v_mfma_f32_16x16x32_bf16 v[0:3], v[218:221], v[210:213], v[182:185]
	v_mfma_f32_16x16x32_bf16 v[120:123], v[230:233], v[214:217], v[0:3]
	v_mfma_f32_16x16x32_bf16 v[0:3], v[246:249], v[210:213], v[186:189]
	s_setprio 2
	s_barrier
	v_mfma_f32_16x16x32_bf16 v[96:99], v[230:233], v[4:7], v[96:99]
	v_mfma_f32_16x16x32_bf16 v[124:127], v[238:241], v[214:217], v[0:3]
	s_setprio 0
	ds_read_b128 v[154:157], v146 offset:49152
	ds_read_b128 v[162:165], v146 offset:50176
	ds_read_b128 v[166:169], v146 offset:51200
	ds_read_b128 v[170:173], v146 offset:52224
	ds_read_b128 v[174:177], v146 offset:53248
	ds_read_b128 v[182:185], v146 offset:54272
	ds_read_b128 v[186:189], v146 offset:55296
	ds_read_b128 v[146:149], v146 offset:56320
	s_barrier
	s_waitcnt lgkmcnt(0)
	s_setprio 1
	s_waitcnt lgkmcnt(0)
	v_mfma_f32_16x16x32_bf16 v[0:3], v[24:27], v[154:157], v[60:63]
	v_mfma_f32_16x16x32_bf16 v[8:11], v[24:27], v[166:169], v[52:55]
	v_mfma_f32_16x16x32_bf16 v[16:19], v[24:27], v[174:177], v[44:47]
	v_mfma_f32_16x16x32_bf16 v[24:27], v[24:27], v[186:189], v[36:39]
	v_mfma_f32_16x16x32_bf16 v[0:3], v[28:31], v[162:165], v[0:3]
	v_mfma_f32_16x16x32_bf16 v[4:7], v[194:197], v[154:157], v[56:59]
	v_mfma_f32_16x16x32_bf16 v[8:11], v[28:31], v[170:173], v[8:11]
	v_mfma_f32_16x16x32_bf16 v[12:15], v[194:197], v[166:169], v[48:51]
	v_mfma_f32_16x16x32_bf16 v[16:19], v[28:31], v[182:185], v[16:19]
	v_mfma_f32_16x16x32_bf16 v[20:23], v[194:197], v[174:177], v[40:43]
	v_mfma_f32_16x16x32_bf16 v[24:27], v[28:31], v[146:149], v[24:27]
	v_mfma_f32_16x16x32_bf16 v[28:31], v[194:197], v[186:189], v[32:35]
	v_mfma_f32_16x16x32_bf16 v[4:7], v[198:201], v[162:165], v[4:7]
	v_mfma_f32_16x16x32_bf16 v[12:15], v[198:201], v[170:173], v[12:15]
	v_mfma_f32_16x16x32_bf16 v[20:23], v[198:201], v[182:185], v[20:23]
	v_mfma_f32_16x16x32_bf16 v[28:31], v[198:201], v[146:149], v[28:31]
	s_setprio 0
	s_setprio 1
	v_mfma_f32_16x16x32_bf16 v[32:35], v[218:221], v[154:157], v[132:135]
	v_mfma_f32_16x16x32_bf16 v[36:39], v[246:249], v[154:157], v[136:139]
	v_mfma_f32_16x16x32_bf16 v[40:43], v[218:221], v[166:169], v[140:143]
	v_mfma_f32_16x16x32_bf16 v[44:47], v[246:249], v[166:169], v[150:153]
	v_mfma_f32_16x16x32_bf16 v[48:51], v[218:221], v[174:177], v[190:193]
	v_mfma_f32_16x16x32_bf16 v[52:55], v[246:249], v[174:177], v[206:209]
	v_mfma_f32_16x16x32_bf16 v[56:59], v[218:221], v[186:189], v[128:131]
	v_mfma_f32_16x16x32_bf16 v[60:63], v[246:249], v[186:189], v[158:161]
	v_mfma_f32_16x16x32_bf16 v[32:35], v[230:233], v[162:165], v[32:35]
	v_mfma_f32_16x16x32_bf16 v[36:39], v[238:241], v[162:165], v[36:39]
	v_mfma_f32_16x16x32_bf16 v[40:43], v[230:233], v[170:173], v[40:43]
	v_mfma_f32_16x16x32_bf16 v[44:47], v[238:241], v[170:173], v[44:47]
	v_mfma_f32_16x16x32_bf16 v[48:51], v[230:233], v[182:185], v[48:51]
	v_mfma_f32_16x16x32_bf16 v[52:55], v[238:241], v[182:185], v[52:55]
	s_setprio 2
	s_barrier
	v_mfma_f32_16x16x32_bf16 v[56:59], v[230:233], v[146:149], v[56:59]
	v_mfma_f32_16x16x32_bf16 v[60:63], v[238:241], v[146:149], v[60:63]
	s_setprio 0
	v_cmp_gt_u32_e32 vcc, s60, v144
	s_and_saveexec_b64 s[8:9], vcc
	s_cbranch_execz .LBB0_2504
	s_barrier

; #define STAGE_A(P, br, kt) do { const char* _base = (const char*)(((kt) < G.ksplit ? G.A1 : A2m) + (long)(br) * G.lda + (long)(kt) * BK); \
;     __builtin_amdgcn_global_load_lds((const unsigned*)(_base + aoff0), (unsigned*)((char*)(P) + sb0), 16, 0, 0); \
;     __builtin_amdgcn_global_load_lds((const unsigned*)(_base + aoff1), (unsigned*)((char*)(P) + sb1), 16, 0, 0); } while (0)
; #define STAGE_B(P, br, kt) do { const char* _base = (const char*)(G.Bt + (long)(br) * G.ldb + (long)(kt) * BK); \
;     __builtin_amdgcn_global_load_lds((const unsigned*)(_base + boff0), (unsigned*)((char*)(P) + sb0), 16, 0, 0); \
;     __builtin_amdgcn_global_load_lds((const unsigned*)(_base + boff1), (unsigned*)((char*)(P) + sb1), 16, 0, 0); } while (0)
; #define LDA(dst, b, h) for (int m = 0; m < 4; ++m) for (int k = 0; k < 2; ++k) \
;     dst[m][k] = *reinterpret_cast<const bf16x8*>(a_rd + ((b) * 2 + (h)) * (HT * 2) + m * 2048 + k * 1024)
; #define LDB(dst, b, h) for (int n = 0; n < 2; ++n) for (int k = 0; k < 2; ++k) \
;     dst[n][k] = *reinterpret_cast<const bf16x8*>(b_rd + ((b) * 2 + (h)) * (HT * 2) + n * 2048 + k * 1024)
; #define MMA(ai, bj, At_, Bt_) do { __builtin_amdgcn_s_setprio(1); \
;     for (int m = 0; m < 4; ++m) for (int n = 0; n < 2; ++n) for (int k = 0; k < 2; ++k) \
;       acc[ai][bj][m][n] = __builtin_amdgcn_mfma_f32_16x16x32_bf16(Bt_[n][k], At_[m][k], acc[ai][bj][m][n], 0, 0, 0); \
;     __builtin_amdgcn_s_setprio(0); } while (0)
; #define WAIT_V(n) asm volatile("s_waitcnt vmcnt(" #n ")" ::: "memory")
; #define WAIT_L(n) asm volatile("s_waitcnt lgkmcnt(" #n ")" ::: "memory")
; #define BAR __builtin_amdgcn_s_barrier()
; #define SCHED __builtin_amdgcn_sched_barrier(0)
;     ...
;     LDB(B0, 0, 0); SCHED; LDA(At, 0, 0); STAGE_A(SA(1, 1), brow + HALF, t + 1);
;     WAIT_L(8); BAR; WAIT_L(0); MMA(0, 0, At, B0); BAR; SCHED;
;     LDB(B1, 0, 1); STAGE_B(SB(0, 0), bcol, t + 2);
;     BAR; WAIT_L(0); MMA(0, 1, At, B1); BAR;
;     LDA(At, 0, 1); STAGE_A(SA(0, 0), brow, t + 2);
;     BAR; WAIT_L(0); MMA(1, 0, At, B0); BAR; SCHED;
;     STAGE_B(SB(0, 1), bcol + HALF, t + 2);
;     WAIT_V(6); BAR; MMA(1, 1, At, B1); BAR;
;     LDB(B0, 1, 0); SCHED; LDA(At, 1, 0); STAGE_A(SA(0, 1), brow + HALF, t + 2);
.LBB0_2566:
	ds_read_b128 v[164:167], v150
	ds_read_b128 v[168:171], v150 offset:1024
	ds_read_b128 v[172:175], v150 offset:2048
	ds_read_b128 v[176:179], v150 offset:3072
	v_add_u32_e32 v162, 0xc000, v147
	v_lshl_add_u64 v[222:223], s[18:19], 0, v[134:135]
	v_readfirstlane_b32 s34, v162
	v_add_u32_e32 v163, 0xe000, v147
	v_lshl_add_u64 v[160:161], v[222:223], 0, s[94:95]
	s_mov_b32 m0, s34
	v_lshl_add_u64 v[226:227], s[18:19], 0, v[136:137]
	v_readfirstlane_b32 s34, v163
	ds_read_b128 v[182:185], v149
	ds_read_b128 v[186:189], v149 offset:1024
	ds_read_b128 v[190:193], v149 offset:2048
	ds_read_b128 v[194:197], v149 offset:3072
	ds_read_b128 v[198:201], v149 offset:4096
	ds_read_b128 v[202:205], v149 offset:5120
	ds_read_b128 v[206:209], v149 offset:6144
	ds_read_b128 v[210:213], v149 offset:7168
	global_load_lds_dwordx4 v[160:161], off
	v_lshl_add_u64 v[160:161], v[226:227], 0, s[94:95]
	s_mov_b32 m0, s34
	s_nop 0
	global_load_lds_dwordx4 v[160:161], off
	ds_read_b128 v[214:217], v150 offset:16384
	ds_read_b128 v[218:221], v150 offset:17408
	ds_read_b128 v[230:233], v150 offset:18432
	ds_read_b128 v[238:241], v150 offset:19456
	s_waitcnt lgkmcnt(0)
	s_waitcnt vmcnt(8)
	s_barrier
	s_setprio 1
	v_mfma_f32_16x16x32_bf16 v[124:127], v[164:167], v[182:185], v[124:127]
	v_mfma_f32_16x16x32_bf16 v[120:123], v[172:175], v[182:185], v[120:123]
	v_mfma_f32_16x16x32_bf16 v[116:119], v[164:167], v[190:193], v[116:119]
	v_mfma_f32_16x16x32_bf16 v[112:115], v[172:175], v[190:193], v[112:115]
	v_mfma_f32_16x16x32_bf16 v[108:111], v[164:167], v[198:201], v[108:111]
	v_mfma_f32_16x16x32_bf16 v[104:107], v[172:175], v[198:201], v[104:107]
	v_mfma_f32_16x16x32_bf16 v[100:103], v[164:167], v[206:209], v[100:103]
	v_mfma_f32_16x16x32_bf16 v[96:99], v[172:175], v[206:209], v[96:99]
	v_mfma_f32_16x16x32_bf16 v[124:127], v[168:171], v[186:189], v[124:127]
	v_mfma_f32_16x16x32_bf16 v[120:123], v[176:179], v[186:189], v[120:123]
	v_mfma_f32_16x16x32_bf16 v[116:119], v[168:171], v[194:197], v[116:119]
	v_mfma_f32_16x16x32_bf16 v[112:115], v[176:179], v[194:197], v[112:115]
	v_mfma_f32_16x16x32_bf16 v[108:111], v[168:171], v[202:205], v[108:111]
	v_mfma_f32_16x16x32_bf16 v[104:107], v[176:179], v[202:205], v[104:107]
	v_mfma_f32_16x16x32_bf16 v[100:103], v[168:171], v[210:213], v[100:103]
	v_mfma_f32_16x16x32_bf16 v[96:99], v[176:179], v[210:213], v[96:99]
	v_mfma_f32_16x16x32_bf16 v[92:95], v[214:217], v[182:185], v[92:95]
	v_mfma_f32_16x16x32_bf16 v[88:91], v[230:233], v[182:185], v[88:91]
	v_mfma_f32_16x16x32_bf16 v[84:87], v[214:217], v[190:193], v[84:87]
	v_mfma_f32_16x16x32_bf16 v[80:83], v[230:233], v[190:193], v[80:83]
	v_mfma_f32_16x16x32_bf16 v[76:79], v[214:217], v[198:201], v[76:79]
	v_mfma_f32_16x16x32_bf16 v[72:75], v[230:233], v[198:201], v[72:75]
	v_mfma_f32_16x16x32_bf16 v[68:71], v[214:217], v[206:209], v[68:71]
	v_mfma_f32_16x16x32_bf16 v[64:67], v[230:233], v[206:209], v[64:67]
	v_mfma_f32_16x16x32_bf16 v[92:95], v[218:221], v[186:189], v[92:95]
	v_mfma_f32_16x16x32_bf16 v[88:91], v[238:241], v[186:189], v[88:91]
	v_mfma_f32_16x16x32_bf16 v[84:87], v[218:221], v[194:197], v[84:87]
	v_mfma_f32_16x16x32_bf16 v[80:83], v[238:241], v[194:197], v[80:83]
	v_mfma_f32_16x16x32_bf16 v[76:79], v[218:221], v[202:205], v[76:79]
	v_mfma_f32_16x16x32_bf16 v[72:75], v[238:241], v[202:205], v[72:75]
	s_setprio 2
	s_barrier
	v_mfma_f32_16x16x32_bf16 v[68:71], v[218:221], v[210:213], v[68:71]
	v_mfma_f32_16x16x32_bf16 v[64:67], v[238:241], v[210:213], v[64:67]
	s_setprio 0
	v_add_u32_e32 v159, s21, v148
	v_lshl_add_u64 v[234:235], s[18:19], 0, v[130:131]
	v_readfirstlane_b32 s34, v159
	v_lshl_add_u64 v[160:161], v[234:235], 0, s[90:91]
	s_mov_b32 m0, s34
	global_load_lds_dwordx4 v[160:161], off
	v_add_u32_e32 v160, 0x2000, v159
	v_lshl_add_u64 v[236:237], s[18:19], 0, v[132:133]
	v_readfirstlane_b32 s34, v160
	v_lshl_add_u64 v[246:247], v[236:237], 0, s[90:91]
	s_mov_b32 m0, s34
	s_nop 0
	global_load_lds_dwordx4 v[246:247], off
	v_readfirstlane_b32 s34, v147
	v_lshl_add_u64 v[246:247], v[222:223], 0, s[4:5]
	s_mov_b32 m0, s34
	v_readfirstlane_b32 s34, v146
	ds_read_b128 v[182:185], v149 offset:16384
	ds_read_b128 v[186:189], v149 offset:17408
	ds_read_b128 v[190:193], v149 offset:18432
	ds_read_b128 v[194:197], v149 offset:19456
	ds_read_b128 v[198:201], v149 offset:20480
	ds_read_b128 v[202:205], v149 offset:21504
	ds_read_b128 v[206:209], v149 offset:22528
	ds_read_b128 v[210:213], v149 offset:23552
	global_load_lds_dwordx4 v[246:247], off
	v_lshl_add_u64 v[246:247], v[226:227], 0, s[4:5]
	s_mov_b32 m0, s34
	s_nop 0
	global_load_lds_dwordx4 v[246:247], off
	v_lshl_add_u64 v[246:247], s[18:19], 0, v[138:139]
	v_readfirstlane_b32 s34, v145
	v_add_u32_e32 v161, 0x2000, v145
	v_lshl_add_u64 v[250:251], v[246:247], 0, s[68:69]
	s_mov_b32 m0, s34
	v_lshl_add_u64 v[248:249], s[18:19], 0, v[140:141]
	v_readfirstlane_b32 s34, v161
	global_load_lds_dwordx4 v[250:251], off
	v_lshl_add_u64 v[250:251], v[248:249], 0, s[68:69]
	s_mov_b32 m0, s34
	s_nop 0
	global_load_lds_dwordx4 v[250:251], off
	s_waitcnt lgkmcnt(0)
	s_waitcnt vmcnt(8)
	s_barrier
; #define STAGE_A(P, br, kt) do { const char* _base = (const char*)(((kt) < G.ksplit ? G.A1 : A2m) + (long)(br) * G.lda + (long)(kt) * BK); \
;     __builtin_amdgcn_global_load_lds((const unsigned*)(_base + aoff0), (unsigned*)((char*)(P) + sb0), 16, 0, 0); \
;     __builtin_amdgcn_global_load_lds((const unsigned*)(_base + aoff1), (unsigned*)((char*)(P) + sb1), 16, 0, 0); } while (0)
; #define STAGE_B(P, br, kt) do { const char* _base = (const char*)(G.Bt + (long)(br) * G.ldb + (long)(kt) * BK); \
;     __builtin_amdgcn_global_load_lds((const unsigned*)(_base + boff0), (unsigned*)((char*)(P) + sb0), 16, 0, 0); \
;     __builtin_amdgcn_global_load_lds((const unsigned*)(_base + boff1), (unsigned*)((char*)(P) + sb1), 16, 0, 0); } while (0)
; #define LDA(dst, b, h) for (int m = 0; m < 4; ++m) for (int k = 0; k < 2; ++k) \
;     dst[m][k] = *reinterpret_cast<const bf16x8*>(a_rd + ((b) * 2 + (h)) * (HT * 2) + m * 2048 + k * 1024)
; #define LDB(dst, b, h) for (int n = 0; n < 2; ++n) for (int k = 0; k < 2; ++k) \
;     dst[n][k] = *reinterpret_cast<const bf16x8*>(b_rd + ((b) * 2 + (h)) * (HT * 2) + n * 2048 + k * 1024)
; #define MMA(ai, bj, At_, Bt_) do { __builtin_amdgcn_s_setprio(1); \
;     for (int m = 0; m < 4; ++m) for (int n = 0; n < 2; ++n) for (int k = 0; k < 2; ++k) \
;       acc[ai][bj][m][n] = __builtin_amdgcn_mfma_f32_16x16x32_bf16(Bt_[n][k], At_[m][k], acc[ai][bj][m][n], 0, 0, 0); \
;     __builtin_amdgcn_s_setprio(0); } while (0)
; #define WAIT_V(n) asm volatile("s_waitcnt vmcnt(" #n ")" ::: "memory")
; #define WAIT_L(n) asm volatile("s_waitcnt lgkmcnt(" #n ")" ::: "memory")
; #define BAR __builtin_amdgcn_s_barrier()
; #define SCHED __builtin_amdgcn_sched_barrier(0)
;     ...
;     LDB(B0, 0, 0); SCHED; LDA(At, 0, 0); STAGE_A(SA(1, 1), brow + HALF, t + 1);
;     WAIT_L(8); BAR; WAIT_L(0); MMA(0, 0, At, B0); BAR; SCHED;
;     LDB(B1, 0, 1); STAGE_B(SB(0, 0), bcol, t + 2);
;     BAR; WAIT_L(0); MMA(0, 1, At, B1); BAR;
;     LDA(At, 0, 1); STAGE_A(SA(0, 0), brow, t + 2);
;     BAR; WAIT_L(0); MMA(1, 0, At, B0); BAR; SCHED;
;     STAGE_B(SB(0, 1), bcol + HALF, t + 2);
;     WAIT_V(6); BAR; MMA(1, 1, At, B1); BAR;
	s_setprio 1
	v_mfma_f32_16x16x32_bf16 v[60:63], v[164:167], v[182:185], v[60:63]
	v_mfma_f32_16x16x32_bf16 v[56:59], v[172:175], v[182:185], v[56:59]
	v_mfma_f32_16x16x32_bf16 v[52:55], v[164:167], v[190:193], v[52:55]
	v_mfma_f32_16x16x32_bf16 v[48:51], v[172:175], v[190:193], v[48:51]
	v_mfma_f32_16x16x32_bf16 v[44:47], v[164:167], v[198:201], v[44:47]
	v_mfma_f32_16x16x32_bf16 v[40:43], v[172:175], v[198:201], v[40:43]
	v_mfma_f32_16x16x32_bf16 v[36:39], v[164:167], v[206:209], v[36:39]
	v_mfma_f32_16x16x32_bf16 v[32:35], v[172:175], v[206:209], v[32:35]
	v_mfma_f32_16x16x32_bf16 v[60:63], v[168:171], v[186:189], v[60:63]
	v_mfma_f32_16x16x32_bf16 v[56:59], v[176:179], v[186:189], v[56:59]
	v_mfma_f32_16x16x32_bf16 v[52:55], v[168:171], v[194:197], v[52:55]
	v_mfma_f32_16x16x32_bf16 v[48:51], v[176:179], v[194:197], v[48:51]
	v_mfma_f32_16x16x32_bf16 v[44:47], v[168:171], v[202:205], v[44:47]
	v_mfma_f32_16x16x32_bf16 v[40:43], v[176:179], v[202:205], v[40:43]
	v_mfma_f32_16x16x32_bf16 v[36:39], v[168:171], v[210:213], v[36:39]
	v_mfma_f32_16x16x32_bf16 v[32:35], v[176:179], v[210:213], v[32:35]
	v_mfma_f32_16x16x32_bf16 v[28:31], v[214:217], v[182:185], v[28:31]
	v_mfma_f32_16x16x32_bf16 v[24:27], v[230:233], v[182:185], v[24:27]
	v_mfma_f32_16x16x32_bf16 v[20:23], v[214:217], v[190:193], v[20:23]
	v_mfma_f32_16x16x32_bf16 v[16:19], v[230:233], v[190:193], v[16:19]
	v_mfma_f32_16x16x32_bf16 v[12:15], v[214:217], v[198:201], v[12:15]
	v_mfma_f32_16x16x32_bf16 v[8:11], v[230:233], v[198:201], v[8:11]
	v_mfma_f32_16x16x32_bf16 v[4:7], v[214:217], v[206:209], v[4:7]
	v_mfma_f32_16x16x32_bf16 v[0:3], v[230:233], v[206:209], v[0:3]
	v_mfma_f32_16x16x32_bf16 v[28:31], v[218:221], v[186:189], v[28:31]
	v_mfma_f32_16x16x32_bf16 v[24:27], v[238:241], v[186:189], v[24:27]
	v_mfma_f32_16x16x32_bf16 v[20:23], v[218:221], v[194:197], v[20:23]
	v_mfma_f32_16x16x32_bf16 v[16:19], v[238:241], v[194:197], v[16:19]
	v_mfma_f32_16x16x32_bf16 v[12:15], v[218:221], v[202:205], v[12:15]
	v_mfma_f32_16x16x32_bf16 v[8:11], v[238:241], v[202:205], v[8:11]
	s_setprio 2
	s_barrier
	v_mfma_f32_16x16x32_bf16 v[4:7], v[218:221], v[210:213], v[4:7]
	v_mfma_f32_16x16x32_bf16 v[0:3], v[238:241], v[210:213], v[0:3]
	s_setprio 0
	ds_read_b128 v[164:167], v150 offset:32768
	ds_read_b128 v[168:171], v150 offset:33792
	ds_read_b128 v[172:175], v150 offset:34816
	ds_read_b128 v[176:179], v150 offset:35840
	v_readfirstlane_b32 s34, v143
	v_lshl_add_u64 v[214:215], v[222:223], 0, s[96:97]
	s_mov_b32 m0, s34
	v_readfirstlane_b32 s34, v142
	ds_read_b128 v[182:185], v149 offset:32768
	ds_read_b128 v[186:189], v149 offset:33792
	ds_read_b128 v[190:193], v149 offset:34816
	ds_read_b128 v[194:197], v149 offset:35840
	ds_read_b128 v[198:201], v149 offset:36864
	ds_read_b128 v[202:205], v149 offset:37888
	ds_read_b128 v[206:209], v149 offset:38912
	ds_read_b128 v[210:213], v149 offset:39936
	global_load_lds_dwordx4 v[214:215], off
	v_lshl_add_u64 v[214:215], v[226:227], 0, s[96:97]
	s_mov_b32 m0, s34
	s_nop 0
	global_load_lds_dwordx4 v[214:215], off
	ds_read_b128 v[214:217], v150 offset:49152
	ds_read_b128 v[218:221], v150 offset:50176
	ds_read_b128 v[230:233], v150 offset:51200
	ds_read_b128 v[238:241], v150 offset:52224
	s_waitcnt lgkmcnt(0)
	s_waitcnt vmcnt(8)
	s_barrier
	s_setprio 1
	v_mfma_f32_16x16x32_bf16 v[124:127], v[164:167], v[182:185], v[124:127]
	v_mfma_f32_16x16x32_bf16 v[120:123], v[172:175], v[182:185], v[120:123]
	v_mfma_f32_16x16x32_bf16 v[116:119], v[164:167], v[190:193], v[116:119]
	v_mfma_f32_16x16x32_bf16 v[112:115], v[172:175], v[190:193], v[112:115]
	v_mfma_f32_16x16x32_bf16 v[108:111], v[164:167], v[198:201], v[108:111]
	v_mfma_f32_16x16x32_bf16 v[104:107], v[172:175], v[198:201], v[104:107]
	v_mfma_f32_16x16x32_bf16 v[100:103], v[164:167], v[206:209], v[100:103]
	v_mfma_f32_16x16x32_bf16 v[96:99], v[172:175], v[206:209], v[96:99]
	v_mfma_f32_16x16x32_bf16 v[124:127], v[168:171], v[186:189], v[124:127]
	v_mfma_f32_16x16x32_bf16 v[120:123], v[176:179], v[186:189], v[120:123]
	v_mfma_f32_16x16x32_bf16 v[116:119], v[168:171], v[194:197], v[116:119]
	v_mfma_f32_16x16x32_bf16 v[112:115], v[176:179], v[194:197], v[112:115]
	v_mfma_f32_16x16x32_bf16 v[108:111], v[168:171], v[202:205], v[108:111]
	v_mfma_f32_16x16x32_bf16 v[104:107], v[176:179], v[202:205], v[104:107]
	v_mfma_f32_16x16x32_bf16 v[100:103], v[168:171], v[210:213], v[100:103]
	v_mfma_f32_16x16x32_bf16 v[96:99], v[176:179], v[210:213], v[96:99]
	v_mfma_f32_16x16x32_bf16 v[92:95], v[214:217], v[182:185], v[92:95]
	v_mfma_f32_16x16x32_bf16 v[88:91], v[230:233], v[182:185], v[88:91]
	v_mfma_f32_16x16x32_bf16 v[84:87], v[214:217], v[190:193], v[84:87]
	v_mfma_f32_16x16x32_bf16 v[80:83], v[230:233], v[190:193], v[80:83]
	v_mfma_f32_16x16x32_bf16 v[76:79], v[214:217], v[198:201], v[76:79]
	v_mfma_f32_16x16x32_bf16 v[72:75], v[230:233], v[198:201], v[72:75]
	v_mfma_f32_16x16x32_bf16 v[68:71], v[214:217], v[206:209], v[68:71]
	v_mfma_f32_16x16x32_bf16 v[64:67], v[230:233], v[206:209], v[64:67]
	v_mfma_f32_16x16x32_bf16 v[92:95], v[218:221], v[186:189], v[92:95]
	v_mfma_f32_16x16x32_bf16 v[88:91], v[238:241], v[186:189], v[88:91]
	v_mfma_f32_16x16x32_bf16 v[84:87], v[218:221], v[194:197], v[84:87]
	v_mfma_f32_16x16x32_bf16 v[80:83], v[238:241], v[194:197], v[80:83]
	v_mfma_f32_16x16x32_bf16 v[76:79], v[218:221], v[202:205], v[76:79]
	v_mfma_f32_16x16x32_bf16 v[72:75], v[238:241], v[202:205], v[72:75]
	s_setprio 2
	s_barrier
; #define STAGE_A(P, br, kt) do { const char* _base = (const char*)(((kt) < G.ksplit ? G.A1 : A2m) + (long)(br) * G.lda + (long)(kt) * BK); \
;     __builtin_amdgcn_global_load_lds((const unsigned*)(_base + aoff0), (unsigned*)((char*)(P) + sb0), 16, 0, 0); \
;     __builtin_amdgcn_global_load_lds((const unsigned*)(_base + aoff1), (unsigned*)((char*)(P) + sb1), 16, 0, 0); } while (0)
; #define STAGE_B(P, br, kt) do { const char* _base = (const char*)(G.Bt + (long)(br) * G.ldb + (long)(kt) * BK); \
;     __builtin_amdgcn_global_load_lds((const unsigned*)(_base + boff0), (unsigned*)((char*)(P) + sb0), 16, 0, 0); \
;     __builtin_amdgcn_global_load_lds((const unsigned*)(_base + boff1), (unsigned*)((char*)(P) + sb1), 16, 0, 0); } while (0)
; #define LDA(dst, b, h) for (int m = 0; m < 4; ++m) for (int k = 0; k < 2; ++k) \
;     dst[m][k] = *reinterpret_cast<const bf16x8*>(a_rd + ((b) * 2 + (h)) * (HT * 2) + m * 2048 + k * 1024)
; #define LDB(dst, b, h) for (int n = 0; n < 2; ++n) for (int k = 0; k < 2; ++k) \
;     dst[n][k] = *reinterpret_cast<const bf16x8*>(b_rd + ((b) * 2 + (h)) * (HT * 2) + n * 2048 + k * 1024)
; #define MMA(ai, bj, At_, Bt_) do { __builtin_amdgcn_s_setprio(1); \
;     for (int m = 0; m < 4; ++m) for (int n = 0; n < 2; ++n) for (int k = 0; k < 2; ++k) \
;       acc[ai][bj][m][n] = __builtin_amdgcn_mfma_f32_16x16x32_bf16(Bt_[n][k], At_[m][k], acc[ai][bj][m][n], 0, 0, 0); \
;     __builtin_amdgcn_s_setprio(0); } while (0)
; #define WAIT_V(n) asm volatile("s_waitcnt vmcnt(" #n ")" ::: "memory")
; #define BAR __builtin_amdgcn_s_barrier()
;     ...
;     LDB(B0, 1, 0); SCHED; LDA(At, 1, 0); STAGE_A(SA(0, 1), brow + HALF, t + 2);
;     WAIT_L(8); BAR; WAIT_L(0); MMA(0, 0, At, B0); BAR; SCHED;
;     LDB(B1, 1, 1); STAGE_B(SB(1, 0), bcol, t + 3);
;     BAR; WAIT_L(0); MMA(0, 1, At, B1); BAR;
;     LDA(At, 1, 1); STAGE_A(SA(1, 0), brow, t + 3);
;     BAR; WAIT_L(0); MMA(1, 0, At, B0); BAR; SCHED;
;     STAGE_B(SB(1, 1), bcol + HALF, t + 3);
;     WAIT_V(6); BAR; MMA(1, 1, At, B1); BAR;
;   }
;   float ssv[2][4] = {};
;   if constexpr (EPI == EPI_GU || EPI == EPI_EVIN || EPI == EPI_ODIN) {
; #pragma unroll
;     for (int ai = 0; ai < 2; ++ai)
; #pragma unroll
;       for (int m = 0; m < 4; ++m) ssv[ai][m] = G.ssr[brow + ai * HALF + wr * 64 + m * 16 + fr];
;   }
;   { LDB(B0, 0, 0); LDA(At, 0, 0); STAGE_A(SA(1, 1), brow + HALF, nt - 1);
	v_mfma_f32_16x16x32_bf16 v[68:71], v[218:221], v[210:213], v[68:71]
	v_mfma_f32_16x16x32_bf16 v[64:67], v[238:241], v[210:213], v[64:67]
	s_setprio 0
	v_readfirstlane_b32 s34, v153
	v_lshl_add_u64 v[234:235], v[234:235], 0, s[88:89]
	s_mov_b32 m0, s34
	v_readfirstlane_b32 s34, v154
	global_load_lds_dwordx4 v[234:235], off
	v_lshl_add_u64 v[234:235], v[236:237], 0, s[88:89]
	s_mov_b32 m0, s34
	s_nop 0
	global_load_lds_dwordx4 v[234:235], off
	v_readfirstlane_b32 s34, v155
	v_lshl_add_u64 v[222:223], v[222:223], 0, s[2:3]
	s_mov_b32 m0, s34
	v_readfirstlane_b32 s34, v156
	ds_read_b128 v[182:185], v149 offset:49152
	ds_read_b128 v[186:189], v149 offset:50176
	ds_read_b128 v[190:193], v149 offset:51200
	ds_read_b128 v[194:197], v149 offset:52224
	ds_read_b128 v[198:201], v149 offset:53248
	ds_read_b128 v[202:205], v149 offset:54272
	ds_read_b128 v[206:209], v149 offset:55296
	ds_read_b128 v[210:213], v149 offset:56320
	global_load_lds_dwordx4 v[222:223], off
	v_lshl_add_u64 v[222:223], v[226:227], 0, s[2:3]
	s_mov_b32 m0, s34
	s_nop 0
	global_load_lds_dwordx4 v[222:223], off
	v_readfirstlane_b32 s34, v157
	v_lshl_add_u64 v[250:251], v[246:247], 0, s[70:71]
	s_mov_b32 m0, s34
	v_readfirstlane_b32 s34, v158
	global_load_lds_dwordx4 v[250:251], off
	v_lshl_add_u64 v[250:251], v[248:249], 0, s[70:71]
	s_mov_b32 m0, s34
	s_nop 0
	global_load_lds_dwordx4 v[250:251], off
	s_waitcnt lgkmcnt(0)
	s_waitcnt vmcnt(8)
	s_barrier
	s_setprio 1
	v_mfma_f32_16x16x32_bf16 v[60:63], v[164:167], v[182:185], v[60:63]
	v_mfma_f32_16x16x32_bf16 v[56:59], v[172:175], v[182:185], v[56:59]
	v_mfma_f32_16x16x32_bf16 v[52:55], v[164:167], v[190:193], v[52:55]
	v_mfma_f32_16x16x32_bf16 v[48:51], v[172:175], v[190:193], v[48:51]
	v_mfma_f32_16x16x32_bf16 v[44:47], v[164:167], v[198:201], v[44:47]
	v_mfma_f32_16x16x32_bf16 v[40:43], v[172:175], v[198:201], v[40:43]
	v_mfma_f32_16x16x32_bf16 v[36:39], v[164:167], v[206:209], v[36:39]
	v_mfma_f32_16x16x32_bf16 v[32:35], v[172:175], v[206:209], v[32:35]
	v_mfma_f32_16x16x32_bf16 v[60:63], v[168:171], v[186:189], v[60:63]
	v_mfma_f32_16x16x32_bf16 v[56:59], v[176:179], v[186:189], v[56:59]
	v_mfma_f32_16x16x32_bf16 v[52:55], v[168:171], v[194:197], v[52:55]
	v_mfma_f32_16x16x32_bf16 v[48:51], v[176:179], v[194:197], v[48:51]
	v_mfma_f32_16x16x32_bf16 v[44:47], v[168:171], v[202:205], v[44:47]
	v_mfma_f32_16x16x32_bf16 v[40:43], v[176:179], v[202:205], v[40:43]
	v_mfma_f32_16x16x32_bf16 v[36:39], v[168:171], v[210:213], v[36:39]
	v_mfma_f32_16x16x32_bf16 v[32:35], v[176:179], v[210:213], v[32:35]
	v_mfma_f32_16x16x32_bf16 v[28:31], v[214:217], v[182:185], v[28:31]
	v_mfma_f32_16x16x32_bf16 v[24:27], v[230:233], v[182:185], v[24:27]
	v_mfma_f32_16x16x32_bf16 v[20:23], v[214:217], v[190:193], v[20:23]
	v_mfma_f32_16x16x32_bf16 v[16:19], v[230:233], v[190:193], v[16:19]
	v_mfma_f32_16x16x32_bf16 v[12:15], v[214:217], v[198:201], v[12:15]
	v_mfma_f32_16x16x32_bf16 v[8:11], v[230:233], v[198:201], v[8:11]
	v_mfma_f32_16x16x32_bf16 v[4:7], v[214:217], v[206:209], v[4:7]
	v_mfma_f32_16x16x32_bf16 v[0:3], v[230:233], v[206:209], v[0:3]
	v_mfma_f32_16x16x32_bf16 v[28:31], v[218:221], v[186:189], v[28:31]
	v_mfma_f32_16x16x32_bf16 v[24:27], v[238:241], v[186:189], v[24:27]
	v_mfma_f32_16x16x32_bf16 v[20:23], v[218:221], v[194:197], v[20:23]
	v_mfma_f32_16x16x32_bf16 v[16:19], v[238:241], v[194:197], v[16:19]
	v_mfma_f32_16x16x32_bf16 v[12:15], v[218:221], v[202:205], v[12:15]
	v_mfma_f32_16x16x32_bf16 v[8:11], v[238:241], v[202:205], v[8:11]
	s_setprio 2
	s_barrier
	v_mfma_f32_16x16x32_bf16 v[4:7], v[218:221], v[210:213], v[4:7]
	v_mfma_f32_16x16x32_bf16 v[0:3], v[238:241], v[210:213], v[0:3]
	s_setprio 0
	s_add_i32 s31, s31, 2
	s_add_u32 s18, s18, 0x100
	s_addc_u32 s19, s19, 0
	s_cmp_lt_u32 s31, 28
	s_cbranch_scc1 .LBB0_2566
	s_waitcnt vmcnt(6)
	v_not_b32_e32 v250, 63
	v_mov_b32_e32 v251, 0x41b17218
	v_or_b32_e32 v130, s28, v152
	v_lshl_add_u32 v130, v151, 6, v130
	v_add_u32_e32 v134, 0x80, v130
	v_ashrrev_i32_e32 v135, 31, v134
	v_lshl_add_u64 v[140:141], v[134:135], 2, s[12:13]
	v_add_u32_e32 v134, 0x90, v130
	v_ashrrev_i32_e32 v131, 31, v130
	v_ashrrev_i32_e32 v135, 31, v134
	v_lshl_add_u64 v[132:133], v[130:131], 2, s[12:13]
	v_lshl_add_u64 v[152:153], v[134:135], 2, s[12:13]
	v_add_u32_e32 v134, 0xa0, v130
	v_add_u32_e32 v130, 0xb0, v130
	s_or_b32 s21, s28, 0x80
	v_ashrrev_i32_e32 v135, 31, v134
	v_ashrrev_i32_e32 v131, 31, v130
	s_mul_i32 s18, s21, 0x1080
	v_lshl_add_u64 v[154:155], v[134:135], 2, s[12:13]
	v_lshl_add_u64 v[156:157], v[130:131], 2, s[12:13]
	global_load_dword v139, v[132:133], off
	global_load_dword v138, v[132:133], off offset:64
	global_load_dword v137, v[132:133], off offset:128
	global_load_dword v134, v[132:133], off offset:192
	s_nop 0
	global_load_dword v133, v[140:141], off
	global_load_dword v132, v[152:153], off
	global_load_dword v131, v[154:155], off
	global_load_dword v130, v[156:157], off
	s_mul_hi_i32 s19, s21, 0x1080
	s_add_u32 s18, s23, s18
	s_addc_u32 s19, s24, s19
	v_lshl_add_u64 v[140:141], s[18:19], 0, v[180:181]
	v_readfirstlane_b32 s31, v162
	v_lshl_add_u64 v[140:141], v[140:141], 0, s[46:47]
	s_mov_b32 m0, s31
	ds_read_b128 v[152:155], v150
	ds_read_b128 v[164:167], v150 offset:1024
	ds_read_b128 v[168:171], v150 offset:2048
	ds_read_b128 v[172:175], v150 offset:3072
	ds_read_b128 v[176:179], v149
	ds_read_b128 v[182:185], v149 offset:1024
	ds_read_b128 v[186:189], v149 offset:2048
	ds_read_b128 v[190:193], v149 offset:3072
	ds_read_b128 v[194:197], v149 offset:4096
	ds_read_b128 v[198:201], v149 offset:5120
	ds_read_b128 v[202:205], v149 offset:6144
	ds_read_b128 v[206:209], v149 offset:7168
	global_load_lds_dwordx4 v[140:141], off
	v_lshl_add_u64 v[140:141], s[18:19], 0, v[128:129]
	v_readfirstlane_b32 s18, v163
	v_lshl_add_u64 v[140:141], v[140:141], 0, s[46:47]
	s_mov_b32 m0, s18
	s_nop 0
	global_load_lds_dwordx4 v[140:141], off
	s_barrier
; #define STAGE_A(P, br, kt) do { const char* _base = (const char*)(((kt) < G.ksplit ? G.A1 : A2m) + (long)(br) * G.lda + (long)(kt) * BK); \
;     __builtin_amdgcn_global_load_lds((const unsigned*)(_base + aoff0), (unsigned*)((char*)(P) + sb0), 16, 0, 0); \
;     __builtin_amdgcn_global_load_lds((const unsigned*)(_base + aoff1), (unsigned*)((char*)(P) + sb1), 16, 0, 0); } while (0)
; #define LDA(dst, b, h) for (int m = 0; m < 4; ++m) for (int k = 0; k < 2; ++k) \
;     dst[m][k] = *reinterpret_cast<const bf16x8*>(a_rd + ((b) * 2 + (h)) * (HT * 2) + m * 2048 + k * 1024)
; #define LDB(dst, b, h) for (int n = 0; n < 2; ++n) for (int k = 0; k < 2; ++k) \
;     dst[n][k] = *reinterpret_cast<const bf16x8*>(b_rd + ((b) * 2 + (h)) * (HT * 2) + n * 2048 + k * 1024)
; #define MMA(ai, bj, At_, Bt_) do { __builtin_amdgcn_s_setprio(1); \
;     for (int m = 0; m < 4; ++m) for (int n = 0; n < 2; ++n) for (int k = 0; k < 2; ++k) \
;       acc[ai][bj][m][n] = __builtin_amdgcn_mfma_f32_16x16x32_bf16(Bt_[n][k], At_[m][k], acc[ai][bj][m][n], 0, 0, 0); \
;     __builtin_amdgcn_s_setprio(0); } while (0)
; #define WAIT_V(n) asm volatile("s_waitcnt vmcnt(" #n ")" ::: "memory")
; #define WAIT_L(n) asm volatile("s_waitcnt lgkmcnt(" #n ")" ::: "memory")
; #define BAR __builtin_amdgcn_s_barrier()
;     ...
;   { LDB(B0, 0, 0); LDA(At, 0, 0); STAGE_A(SA(1, 1), brow + HALF, nt - 1);
;     BAR; WAIT_L(0); MMA(0, 0, At, B0); BAR;
;     LDB(B1, 0, 1); BAR; WAIT_L(0); MMA(0, 1, At, B1); BAR;
;     LDA(At, 0, 1); WAIT_V(4); BAR; WAIT_L(0); MMA(1, 0, At, B0); MMA(1, 1, At, B1); BAR; }
;   { LDB(B0, 1, 0); LDA(At, 1, 0); WAIT_V(2); BAR; WAIT_L(0); MMA(0, 0, At, B0); BAR;
	s_waitcnt lgkmcnt(0)
	s_setprio 1
	s_waitcnt lgkmcnt(0)
	v_mfma_f32_16x16x32_bf16 v[124:127], v[152:155], v[176:179], v[124:127]
	v_mfma_f32_16x16x32_bf16 v[116:119], v[152:155], v[186:189], v[116:119]
	v_mfma_f32_16x16x32_bf16 v[108:111], v[152:155], v[194:197], v[108:111]
	v_mfma_f32_16x16x32_bf16 v[100:103], v[152:155], v[202:205], v[100:103]
	v_mfma_f32_16x16x32_bf16 v[124:127], v[164:167], v[182:185], v[124:127]
	v_mfma_f32_16x16x32_bf16 v[120:123], v[168:171], v[176:179], v[120:123]
	v_mfma_f32_16x16x32_bf16 v[116:119], v[164:167], v[190:193], v[116:119]
	v_mfma_f32_16x16x32_bf16 v[112:115], v[168:171], v[186:189], v[112:115]
	v_mfma_f32_16x16x32_bf16 v[108:111], v[164:167], v[198:201], v[108:111]
	v_mfma_f32_16x16x32_bf16 v[104:107], v[168:171], v[194:197], v[104:107]
	v_mfma_f32_16x16x32_bf16 v[100:103], v[164:167], v[206:209], v[100:103]
	v_mfma_f32_16x16x32_bf16 v[96:99], v[168:171], v[202:205], v[96:99]
	v_mfma_f32_16x16x32_bf16 v[210:213], v[172:175], v[182:185], v[120:123]
	v_mfma_f32_16x16x32_bf16 v[214:217], v[172:175], v[190:193], v[112:115]
	s_setprio 2
	s_barrier
	v_mfma_f32_16x16x32_bf16 v[218:221], v[172:175], v[198:201], v[104:107]
	v_mfma_f32_16x16x32_bf16 v[230:233], v[172:175], v[206:209], v[96:99]
	s_setprio 0
	s_nop 1
	ds_read_b128 v[96:99], v150 offset:16384
	ds_read_b128 v[104:107], v150 offset:17408
	ds_read_b128 v[112:115], v150 offset:18432
	ds_read_b128 v[120:123], v150 offset:19456
	s_barrier
	s_waitcnt lgkmcnt(0)
	s_setprio 1
	s_waitcnt lgkmcnt(0)
	v_mfma_f32_16x16x32_bf16 v[92:95], v[96:99], v[176:179], v[92:95]
	v_mfma_f32_16x16x32_bf16 v[84:87], v[96:99], v[186:189], v[84:87]
	v_mfma_f32_16x16x32_bf16 v[76:79], v[96:99], v[194:197], v[76:79]
	v_mfma_f32_16x16x32_bf16 v[68:71], v[96:99], v[202:205], v[68:71]
	v_mfma_f32_16x16x32_bf16 v[92:95], v[104:107], v[182:185], v[92:95]
	v_mfma_f32_16x16x32_bf16 v[88:91], v[112:115], v[176:179], v[88:91]
	v_mfma_f32_16x16x32_bf16 v[84:87], v[104:107], v[190:193], v[84:87]
	v_mfma_f32_16x16x32_bf16 v[80:83], v[112:115], v[186:189], v[80:83]
	v_mfma_f32_16x16x32_bf16 v[76:79], v[104:107], v[198:201], v[76:79]
	v_mfma_f32_16x16x32_bf16 v[72:75], v[112:115], v[194:197], v[72:75]
	v_mfma_f32_16x16x32_bf16 v[68:71], v[104:107], v[206:209], v[68:71]
	v_mfma_f32_16x16x32_bf16 v[64:67], v[112:115], v[202:205], v[64:67]
	v_mfma_f32_16x16x32_bf16 v[176:179], v[120:123], v[182:185], v[88:91]
	v_mfma_f32_16x16x32_bf16 v[182:185], v[120:123], v[190:193], v[80:83]
	s_setprio 2
	s_barrier
	v_mfma_f32_16x16x32_bf16 v[186:189], v[120:123], v[198:201], v[72:75]
	v_mfma_f32_16x16x32_bf16 v[190:193], v[120:123], v[206:209], v[64:67]
	s_setprio 0
	s_nop 1
	ds_read_b128 v[64:67], v149 offset:16384
	ds_read_b128 v[72:75], v149 offset:17408
	ds_read_b128 v[80:83], v149 offset:18432
	ds_read_b128 v[88:91], v149 offset:19456
	ds_read_b128 v[194:197], v149 offset:20480
	ds_read_b128 v[198:201], v149 offset:21504
	ds_read_b128 v[202:205], v149 offset:22528
	ds_read_b128 v[206:209], v149 offset:23552
	s_waitcnt vmcnt(4)
	s_barrier
	s_waitcnt lgkmcnt(0)
	s_setprio 1
	s_waitcnt lgkmcnt(0)
	v_mfma_f32_16x16x32_bf16 v[60:63], v[152:155], v[64:67], v[60:63]
	v_mfma_f32_16x16x32_bf16 v[52:55], v[152:155], v[80:83], v[52:55]
	v_mfma_f32_16x16x32_bf16 v[44:47], v[152:155], v[194:197], v[44:47]
	v_mfma_f32_16x16x32_bf16 v[36:39], v[152:155], v[202:205], v[36:39]
	v_mfma_f32_16x16x32_bf16 v[60:63], v[164:167], v[72:75], v[60:63]
	v_mfma_f32_16x16x32_bf16 v[56:59], v[168:171], v[64:67], v[56:59]
	v_mfma_f32_16x16x32_bf16 v[52:55], v[164:167], v[88:91], v[52:55]
	v_mfma_f32_16x16x32_bf16 v[48:51], v[168:171], v[80:83], v[48:51]
	v_mfma_f32_16x16x32_bf16 v[44:47], v[164:167], v[198:201], v[44:47]
	v_mfma_f32_16x16x32_bf16 v[40:43], v[168:171], v[194:197], v[40:43]
	v_mfma_f32_16x16x32_bf16 v[36:39], v[164:167], v[206:209], v[36:39]
	v_mfma_f32_16x16x32_bf16 v[32:35], v[168:171], v[202:205], v[32:35]
	v_mfma_f32_16x16x32_bf16 v[238:241], v[172:175], v[72:75], v[56:59]
	v_mfma_f32_16x16x32_bf16 v[246:249], v[172:175], v[88:91], v[48:51]
	v_mfma_f32_16x16x32_bf16 v[234:237], v[172:175], v[198:201], v[40:43]
	v_mfma_f32_16x16x32_bf16 v[152:155], v[172:175], v[206:209], v[32:35]
	s_setprio 0
	s_setprio 1
	v_mfma_f32_16x16x32_bf16 v[28:31], v[96:99], v[64:67], v[28:31]
	v_mfma_f32_16x16x32_bf16 v[20:23], v[96:99], v[80:83], v[20:23]
	v_mfma_f32_16x16x32_bf16 v[12:15], v[96:99], v[194:197], v[12:15]
	v_mfma_f32_16x16x32_bf16 v[4:7], v[96:99], v[202:205], v[4:7]
	v_mfma_f32_16x16x32_bf16 v[28:31], v[104:107], v[72:75], v[28:31]
	v_mfma_f32_16x16x32_bf16 v[24:27], v[112:115], v[64:67], v[24:27]
	v_mfma_f32_16x16x32_bf16 v[20:23], v[104:107], v[88:91], v[20:23]
	v_mfma_f32_16x16x32_bf16 v[16:19], v[112:115], v[80:83], v[16:19]
	v_mfma_f32_16x16x32_bf16 v[12:15], v[104:107], v[198:201], v[12:15]
	v_mfma_f32_16x16x32_bf16 v[8:11], v[112:115], v[194:197], v[8:11]
	v_mfma_f32_16x16x32_bf16 v[4:7], v[104:107], v[206:209], v[4:7]
	v_mfma_f32_16x16x32_bf16 v[0:3], v[112:115], v[202:205], v[0:3]
	v_mfma_f32_16x16x32_bf16 v[162:165], v[120:123], v[72:75], v[24:27]
	v_mfma_f32_16x16x32_bf16 v[166:169], v[120:123], v[88:91], v[16:19]
	s_setprio 2
	s_barrier
	v_mfma_f32_16x16x32_bf16 v[170:173], v[120:123], v[198:201], v[8:11]
	v_mfma_f32_16x16x32_bf16 v[194:197], v[120:123], v[206:209], v[0:3]
	s_setprio 0
	s_nop 1
	ds_read_b128 v[0:3], v150 offset:32768
	ds_read_b128 v[8:11], v150 offset:33792
	ds_read_b128 v[16:19], v150 offset:34816
	ds_read_b128 v[24:27], v150 offset:35840
	ds_read_b128 v[32:35], v149 offset:32768
	ds_read_b128 v[40:43], v149 offset:33792
	ds_read_b128 v[48:51], v149 offset:34816
	ds_read_b128 v[56:59], v149 offset:35840
	ds_read_b128 v[64:67], v149 offset:36864
	ds_read_b128 v[198:201], v149 offset:37888
	ds_read_b128 v[202:205], v149 offset:38912
	ds_read_b128 v[206:209], v149 offset:39936
	s_waitcnt vmcnt(2)
	s_barrier
; #define LDA(dst, b, h) for (int m = 0; m < 4; ++m) for (int k = 0; k < 2; ++k) \
;     dst[m][k] = *reinterpret_cast<const bf16x8*>(a_rd + ((b) * 2 + (h)) * (HT * 2) + m * 2048 + k * 1024)
; #define LDB(dst, b, h) for (int n = 0; n < 2; ++n) for (int k = 0; k < 2; ++k) \
;     dst[n][k] = *reinterpret_cast<const bf16x8*>(b_rd + ((b) * 2 + (h)) * (HT * 2) + n * 2048 + k * 1024)
; #define MMA(ai, bj, At_, Bt_) do { __builtin_amdgcn_s_setprio(1); \
;     for (int m = 0; m < 4; ++m) for (int n = 0; n < 2; ++n) for (int k = 0; k < 2; ++k) \
;       acc[ai][bj][m][n] = __builtin_amdgcn_mfma_f32_16x16x32_bf16(Bt_[n][k], At_[m][k], acc[ai][bj][m][n], 0, 0, 0); \
;     __builtin_amdgcn_s_setprio(0); } while (0)
; #define WAIT_V(n) asm volatile("s_waitcnt vmcnt(" #n ")" ::: "memory")
; #define WAIT_L(n) asm volatile("s_waitcnt lgkmcnt(" #n ")" ::: "memory")
; #define BAR __builtin_amdgcn_s_barrier()
;     ...
;   { LDB(B0, 1, 0); LDA(At, 1, 0); WAIT_V(2); BAR; WAIT_L(0); MMA(0, 0, At, B0); BAR;
;     LDB(B1, 1, 1); WAIT_V(0); BAR; WAIT_L(0); MMA(0, 1, At, B1); BAR;
;     LDA(At, 1, 1); BAR; WAIT_L(0); MMA(1, 0, At, B0); MMA(1, 1, At, B1); BAR; }
;   if (wr == 0) BAR;
	s_waitcnt lgkmcnt(0)
	s_setprio 1
	s_waitcnt lgkmcnt(0)
	v_mfma_f32_16x16x32_bf16 v[72:75], v[0:3], v[32:35], v[124:127]
	v_mfma_f32_16x16x32_bf16 v[120:123], v[8:11], v[40:43], v[72:75]
	v_mfma_f32_16x16x32_bf16 v[72:75], v[16:19], v[32:35], v[210:213]
	v_mfma_f32_16x16x32_bf16 v[124:127], v[24:27], v[40:43], v[72:75]
	v_mfma_f32_16x16x32_bf16 v[72:75], v[0:3], v[48:51], v[116:119]
	v_mfma_f32_16x16x32_bf16 v[112:115], v[8:11], v[56:59], v[72:75]
	v_mfma_f32_16x16x32_bf16 v[72:75], v[16:19], v[48:51], v[214:217]
	v_mfma_f32_16x16x32_bf16 v[116:119], v[24:27], v[56:59], v[72:75]
	v_mfma_f32_16x16x32_bf16 v[72:75], v[0:3], v[64:67], v[108:111]
	v_mfma_f32_16x16x32_bf16 v[104:107], v[8:11], v[198:201], v[72:75]
	v_mfma_f32_16x16x32_bf16 v[72:75], v[16:19], v[64:67], v[218:221]
	v_mfma_f32_16x16x32_bf16 v[108:111], v[24:27], v[198:201], v[72:75]
	v_mfma_f32_16x16x32_bf16 v[72:75], v[0:3], v[202:205], v[100:103]
	v_mfma_f32_16x16x32_bf16 v[96:99], v[8:11], v[206:209], v[72:75]
	s_setprio 2
	s_barrier
	v_mfma_f32_16x16x32_bf16 v[72:75], v[16:19], v[202:205], v[230:233]
	v_mfma_f32_16x16x32_bf16 v[100:103], v[24:27], v[206:209], v[72:75]
	s_setprio 0
	ds_read_b128 v[210:213], v150 offset:49152
	ds_read_b128 v[214:217], v150 offset:50176
	ds_read_b128 v[218:221], v150 offset:51200
	ds_read_b128 v[230:233], v150 offset:52224
	s_waitcnt vmcnt(0)
	s_barrier
	s_waitcnt lgkmcnt(0)
	s_setprio 1
	s_waitcnt lgkmcnt(0)
	v_mfma_f32_16x16x32_bf16 v[72:75], v[210:213], v[32:35], v[92:95]
	v_mfma_f32_16x16x32_bf16 v[32:35], v[218:221], v[32:35], v[176:179]
	v_mfma_f32_16x16x32_bf16 v[92:95], v[230:233], v[40:43], v[32:35]
	v_mfma_f32_16x16x32_bf16 v[32:35], v[210:213], v[48:51], v[84:87]
	v_mfma_f32_16x16x32_bf16 v[80:83], v[214:217], v[56:59], v[32:35]
	v_mfma_f32_16x16x32_bf16 v[32:35], v[218:221], v[48:51], v[182:185]
	v_mfma_f32_16x16x32_bf16 v[84:87], v[230:233], v[56:59], v[32:35]
	v_mfma_f32_16x16x32_bf16 v[32:35], v[210:213], v[64:67], v[76:79]
	v_mfma_f32_16x16x32_bf16 v[88:91], v[214:217], v[40:43], v[72:75]
	v_mfma_f32_16x16x32_bf16 v[72:75], v[214:217], v[198:201], v[32:35]
	v_mfma_f32_16x16x32_bf16 v[32:35], v[218:221], v[64:67], v[186:189]
	v_mfma_f32_16x16x32_bf16 v[76:79], v[230:233], v[198:201], v[32:35]
	v_mfma_f32_16x16x32_bf16 v[32:35], v[210:213], v[202:205], v[68:71]
	v_mfma_f32_16x16x32_bf16 v[64:67], v[214:217], v[206:209], v[32:35]
	s_setprio 2
	s_barrier
	v_mfma_f32_16x16x32_bf16 v[32:35], v[218:221], v[202:205], v[190:193]
	v_mfma_f32_16x16x32_bf16 v[68:71], v[230:233], v[206:209], v[32:35]
	s_setprio 0
	ds_read_b128 v[174:177], v149 offset:49152
	ds_read_b128 v[182:185], v149 offset:50176
	ds_read_b128 v[186:189], v149 offset:51200
	ds_read_b128 v[190:193], v149 offset:52224
	ds_read_b128 v[198:201], v149 offset:53248
	ds_read_b128 v[202:205], v149 offset:54272
	ds_read_b128 v[206:209], v149 offset:55296
	ds_read_b128 v[148:151], v149 offset:56320
	s_barrier
	s_waitcnt lgkmcnt(0)
	s_setprio 1
	s_waitcnt lgkmcnt(0)
	v_mfma_f32_16x16x32_bf16 v[32:35], v[0:3], v[174:177], v[60:63]
	v_mfma_f32_16x16x32_bf16 v[56:59], v[8:11], v[182:185], v[32:35]
	v_mfma_f32_16x16x32_bf16 v[32:35], v[16:19], v[174:177], v[238:241]
	v_mfma_f32_16x16x32_bf16 v[60:63], v[24:27], v[182:185], v[32:35]
	v_mfma_f32_16x16x32_bf16 v[32:35], v[0:3], v[186:189], v[52:55]
	v_mfma_f32_16x16x32_bf16 v[48:51], v[8:11], v[190:193], v[32:35]
	v_mfma_f32_16x16x32_bf16 v[32:35], v[16:19], v[186:189], v[246:249]
	v_mfma_f32_16x16x32_bf16 v[52:55], v[24:27], v[190:193], v[32:35]
	v_mfma_f32_16x16x32_bf16 v[32:35], v[0:3], v[198:201], v[44:47]
	v_mfma_f32_16x16x32_bf16 v[40:43], v[8:11], v[202:205], v[32:35]
	v_mfma_f32_16x16x32_bf16 v[32:35], v[16:19], v[198:201], v[234:237]
	v_mfma_f32_16x16x32_bf16 v[0:3], v[0:3], v[206:209], v[36:39]
	v_mfma_f32_16x16x32_bf16 v[44:47], v[24:27], v[202:205], v[32:35]
	v_mfma_f32_16x16x32_bf16 v[32:35], v[8:11], v[148:151], v[0:3]
	v_mfma_f32_16x16x32_bf16 v[0:3], v[16:19], v[206:209], v[152:155]
	v_mfma_f32_16x16x32_bf16 v[36:39], v[24:27], v[148:151], v[0:3]
	s_setprio 0
	s_setprio 1
	v_mfma_f32_16x16x32_bf16 v[0:3], v[210:213], v[174:177], v[28:31]
	v_mfma_f32_16x16x32_bf16 v[24:27], v[214:217], v[182:185], v[0:3]
	v_mfma_f32_16x16x32_bf16 v[0:3], v[218:221], v[174:177], v[162:165]
	v_mfma_f32_16x16x32_bf16 v[28:31], v[230:233], v[182:185], v[0:3]
	v_mfma_f32_16x16x32_bf16 v[0:3], v[210:213], v[186:189], v[20:23]
	v_mfma_f32_16x16x32_bf16 v[16:19], v[214:217], v[190:193], v[0:3]
	v_mfma_f32_16x16x32_bf16 v[0:3], v[218:221], v[186:189], v[166:169]
	v_mfma_f32_16x16x32_bf16 v[20:23], v[230:233], v[190:193], v[0:3]
	v_mfma_f32_16x16x32_bf16 v[0:3], v[210:213], v[198:201], v[12:15]
	v_mfma_f32_16x16x32_bf16 v[8:11], v[214:217], v[202:205], v[0:3]
	v_mfma_f32_16x16x32_bf16 v[0:3], v[218:221], v[198:201], v[170:173]
	v_mfma_f32_16x16x32_bf16 v[12:15], v[230:233], v[202:205], v[0:3]
	v_mfma_f32_16x16x32_bf16 v[0:3], v[210:213], v[206:209], v[4:7]
	v_mfma_f32_16x16x32_bf16 v[4:7], v[218:221], v[206:209], v[194:197]
	s_setprio 2
	s_barrier
	v_mfma_f32_16x16x32_bf16 v[0:3], v[214:217], v[148:151], v[0:3]
	v_mfma_f32_16x16x32_bf16 v[4:7], v[230:233], v[148:151], v[4:7]
	s_setprio 0
	v_cmp_gt_u32_e32 vcc, s60, v144
	s_and_saveexec_b64 s[18:19], vcc
	s_cbranch_execz .LBB0_2569
	s_barrier

; #define STAGE_A(P, br, kt) do { const char* _base = (const char*)(((kt) < G.ksplit ? G.A1 : A2m) + (long)(br) * G.lda + (long)(kt) * BK); \
;     __builtin_amdgcn_global_load_lds((const unsigned*)(_base + aoff0), (unsigned*)((char*)(P) + sb0), 16, 0, 0); \
;     __builtin_amdgcn_global_load_lds((const unsigned*)(_base + aoff1), (unsigned*)((char*)(P) + sb1), 16, 0, 0); } while (0)
; #define STAGE_B(P, br, kt) do { const char* _base = (const char*)(G.Bt + (long)(br) * G.ldb + (long)(kt) * BK); \
;     __builtin_amdgcn_global_load_lds((const unsigned*)(_base + boff0), (unsigned*)((char*)(P) + sb0), 16, 0, 0); \
;     __builtin_amdgcn_global_load_lds((const unsigned*)(_base + boff1), (unsigned*)((char*)(P) + sb1), 16, 0, 0); } while (0)
; #define LDA(dst, b, h) for (int m = 0; m < 4; ++m) for (int k = 0; k < 2; ++k) \
;     dst[m][k] = *reinterpret_cast<const bf16x8*>(a_rd + ((b) * 2 + (h)) * (HT * 2) + m * 2048 + k * 1024)
; #define LDB(dst, b, h) for (int n = 0; n < 2; ++n) for (int k = 0; k < 2; ++k) \
;     dst[n][k] = *reinterpret_cast<const bf16x8*>(b_rd + ((b) * 2 + (h)) * (HT * 2) + n * 2048 + k * 1024)
; #define MMA(ai, bj, At_, Bt_) do { __builtin_amdgcn_s_setprio(1); \
;     for (int m = 0; m < 4; ++m) for (int n = 0; n < 2; ++n) for (int k = 0; k < 2; ++k) \
;       acc[ai][bj][m][n] = __builtin_amdgcn_mfma_f32_16x16x32_bf16(Bt_[n][k], At_[m][k], acc[ai][bj][m][n], 0, 0, 0); \
;     __builtin_amdgcn_s_setprio(0); } while (0)
; #define WAIT_V(n) asm volatile("s_waitcnt vmcnt(" #n ")" ::: "memory")
; #define WAIT_L(n) asm volatile("s_waitcnt lgkmcnt(" #n ")" ::: "memory")
; #define BAR __builtin_amdgcn_s_barrier()
; #define SCHED __builtin_amdgcn_sched_barrier(0)
;     ...
;   for (int t = 0; t < nt - 2; t += 2) {
;     LDB(B0, 0, 0); SCHED; LDA(At, 0, 0); STAGE_A(SA(1, 1), brow + HALF, t + 1);
;     WAIT_L(8); BAR; WAIT_L(0); MMA(0, 0, At, B0); BAR; SCHED;
;     LDB(B1, 0, 1); STAGE_B(SB(0, 0), bcol, t + 2);
;     BAR; WAIT_L(0); MMA(0, 1, At, B1); BAR;
;     LDA(At, 0, 1); STAGE_A(SA(0, 0), brow, t + 2);
;     BAR; WAIT_L(0); MMA(1, 0, At, B0); BAR; SCHED;
;     STAGE_B(SB(0, 1), bcol + HALF, t + 2);
;     WAIT_V(6); BAR; MMA(1, 1, At, B1); BAR;
.LBB0_2622:
	ds_read_b128 v[160:163], v147
	ds_read_b128 v[164:167], v147 offset:1024
	ds_read_b128 v[168:171], v147 offset:2048
	ds_read_b128 v[172:175], v147 offset:3072
	v_add_u32_e32 v157, 0xc000, v145
	v_lshl_add_u64 v[222:223], s[86:87], 0, v[134:135]
	v_readfirstlane_b32 s9, v157
	v_lshl_add_u64 v[158:159], v[222:223], 0, s[72:73]
	s_mov_b32 m0, s9
	ds_read_b128 v[176:179], v144
	ds_read_b128 v[182:185], v144 offset:1024
	ds_read_b128 v[186:189], v144 offset:2048
	ds_read_b128 v[190:193], v144 offset:3072
	ds_read_b128 v[194:197], v144 offset:4096
	ds_read_b128 v[198:201], v144 offset:5120
	ds_read_b128 v[202:205], v144 offset:6144
	ds_read_b128 v[206:209], v144 offset:7168
	global_load_lds_dwordx4 v[158:159], off
	v_add_u32_e32 v158, 0xe000, v145
	v_lshl_add_u64 v[226:227], s[86:87], 0, v[136:137]
	v_readfirstlane_b32 s9, v158
	v_lshl_add_u64 v[210:211], v[226:227], 0, s[72:73]
	s_mov_b32 m0, s9
	s_nop 0
	global_load_lds_dwordx4 v[210:211], off
	ds_read_b128 v[210:213], v147 offset:16384
	ds_read_b128 v[214:217], v147 offset:17408
	ds_read_b128 v[218:221], v147 offset:18432
	ds_read_b128 v[230:233], v147 offset:19456
	s_waitcnt lgkmcnt(0)
	s_waitcnt vmcnt(8)
	s_barrier
	s_setprio 1
	v_mfma_f32_16x16x32_bf16 v[124:127], v[160:163], v[176:179], v[124:127]
	v_mfma_f32_16x16x32_bf16 v[120:123], v[168:171], v[176:179], v[120:123]
	v_mfma_f32_16x16x32_bf16 v[116:119], v[160:163], v[186:189], v[116:119]
	v_mfma_f32_16x16x32_bf16 v[112:115], v[168:171], v[186:189], v[112:115]
	v_mfma_f32_16x16x32_bf16 v[108:111], v[160:163], v[194:197], v[108:111]
	v_mfma_f32_16x16x32_bf16 v[104:107], v[168:171], v[194:197], v[104:107]
	v_mfma_f32_16x16x32_bf16 v[100:103], v[160:163], v[202:205], v[100:103]
	v_mfma_f32_16x16x32_bf16 v[96:99], v[168:171], v[202:205], v[96:99]
	v_mfma_f32_16x16x32_bf16 v[124:127], v[164:167], v[182:185], v[124:127]
	v_mfma_f32_16x16x32_bf16 v[120:123], v[172:175], v[182:185], v[120:123]
	v_mfma_f32_16x16x32_bf16 v[116:119], v[164:167], v[190:193], v[116:119]
	v_mfma_f32_16x16x32_bf16 v[112:115], v[172:175], v[190:193], v[112:115]
	v_mfma_f32_16x16x32_bf16 v[108:111], v[164:167], v[198:201], v[108:111]
	v_mfma_f32_16x16x32_bf16 v[104:107], v[172:175], v[198:201], v[104:107]
	v_mfma_f32_16x16x32_bf16 v[100:103], v[164:167], v[206:209], v[100:103]
	v_mfma_f32_16x16x32_bf16 v[96:99], v[172:175], v[206:209], v[96:99]
	v_mfma_f32_16x16x32_bf16 v[92:95], v[210:213], v[176:179], v[92:95]
	v_mfma_f32_16x16x32_bf16 v[88:91], v[218:221], v[176:179], v[88:91]
	v_mfma_f32_16x16x32_bf16 v[84:87], v[210:213], v[186:189], v[84:87]
	v_mfma_f32_16x16x32_bf16 v[80:83], v[218:221], v[186:189], v[80:83]
	v_mfma_f32_16x16x32_bf16 v[76:79], v[210:213], v[194:197], v[76:79]
	v_mfma_f32_16x16x32_bf16 v[72:75], v[218:221], v[194:197], v[72:75]
	v_mfma_f32_16x16x32_bf16 v[68:71], v[210:213], v[202:205], v[68:71]
	v_mfma_f32_16x16x32_bf16 v[64:67], v[218:221], v[202:205], v[64:67]
	v_mfma_f32_16x16x32_bf16 v[92:95], v[214:217], v[182:185], v[92:95]
	v_mfma_f32_16x16x32_bf16 v[88:91], v[230:233], v[182:185], v[88:91]
	v_mfma_f32_16x16x32_bf16 v[84:87], v[214:217], v[190:193], v[84:87]
	v_mfma_f32_16x16x32_bf16 v[80:83], v[230:233], v[190:193], v[80:83]
	v_mfma_f32_16x16x32_bf16 v[76:79], v[214:217], v[198:201], v[76:79]
	v_mfma_f32_16x16x32_bf16 v[72:75], v[230:233], v[198:201], v[72:75]
	s_setprio 2
	s_barrier
	v_mfma_f32_16x16x32_bf16 v[68:71], v[214:217], v[206:209], v[68:71]
	v_mfma_f32_16x16x32_bf16 v[64:67], v[230:233], v[206:209], v[64:67]
	s_setprio 0
	v_lshl_add_u64 v[234:235], s[86:87], 0, v[130:131]
	v_readfirstlane_b32 s9, v143
	v_lshl_add_u64 v[236:237], v[234:235], 0, s[74:75]
	s_mov_b32 m0, s9
	v_add_u32_e32 v159, 0x2000, v143
	global_load_lds_dwordx4 v[236:237], off
	v_lshl_add_u64 v[236:237], s[86:87], 0, v[132:133]
	v_readfirstlane_b32 s9, v159
	v_lshl_add_u64 v[238:239], v[236:237], 0, s[74:75]
	s_mov_b32 m0, s9
	s_nop 0
	global_load_lds_dwordx4 v[238:239], off
	v_readfirstlane_b32 s9, v145
	v_lshl_add_u64 v[238:239], v[222:223], 0, s[76:77]
	s_mov_b32 m0, s9
	v_readfirstlane_b32 s9, v146
	ds_read_b128 v[176:179], v144 offset:16384
	ds_read_b128 v[182:185], v144 offset:17408
	ds_read_b128 v[186:189], v144 offset:18432
	ds_read_b128 v[190:193], v144 offset:19456
	ds_read_b128 v[194:197], v144 offset:20480
	ds_read_b128 v[198:201], v144 offset:21504
	ds_read_b128 v[202:205], v144 offset:22528
	ds_read_b128 v[206:209], v144 offset:23552
	global_load_lds_dwordx4 v[238:239], off
	v_lshl_add_u64 v[238:239], v[226:227], 0, s[76:77]
	s_mov_b32 m0, s9
	s_nop 0
	global_load_lds_dwordx4 v[238:239], off
	v_lshl_add_u64 v[238:239], s[86:87], 0, v[138:139]
	v_readfirstlane_b32 s9, v148
	v_add_u32_e32 v159, 0x2000, v148
	v_lshl_add_u64 v[250:251], v[238:239], 0, s[78:79]
	s_mov_b32 m0, s9
	v_lshl_add_u64 v[240:241], s[86:87], 0, v[140:141]
	v_readfirstlane_b32 s9, v159
	global_load_lds_dwordx4 v[250:251], off
	v_lshl_add_u64 v[250:251], v[240:241], 0, s[78:79]
	s_mov_b32 m0, s9
	s_nop 0
	global_load_lds_dwordx4 v[250:251], off
	s_waitcnt lgkmcnt(0)
	s_waitcnt vmcnt(8)
	s_barrier
; #define STAGE_A(P, br, kt) do { const char* _base = (const char*)(((kt) < G.ksplit ? G.A1 : A2m) + (long)(br) * G.lda + (long)(kt) * BK); \
;     __builtin_amdgcn_global_load_lds((const unsigned*)(_base + aoff0), (unsigned*)((char*)(P) + sb0), 16, 0, 0); \
;     __builtin_amdgcn_global_load_lds((const unsigned*)(_base + aoff1), (unsigned*)((char*)(P) + sb1), 16, 0, 0); } while (0)
; #define STAGE_B(P, br, kt) do { const char* _base = (const char*)(G.Bt + (long)(br) * G.ldb + (long)(kt) * BK); \
;     __builtin_amdgcn_global_load_lds((const unsigned*)(_base + boff0), (unsigned*)((char*)(P) + sb0), 16, 0, 0); \
;     __builtin_amdgcn_global_load_lds((const unsigned*)(_base + boff1), (unsigned*)((char*)(P) + sb1), 16, 0, 0); } while (0)
; #define LDA(dst, b, h) for (int m = 0; m < 4; ++m) for (int k = 0; k < 2; ++k) \
;     dst[m][k] = *reinterpret_cast<const bf16x8*>(a_rd + ((b) * 2 + (h)) * (HT * 2) + m * 2048 + k * 1024)
; #define LDB(dst, b, h) for (int n = 0; n < 2; ++n) for (int k = 0; k < 2; ++k) \
;     dst[n][k] = *reinterpret_cast<const bf16x8*>(b_rd + ((b) * 2 + (h)) * (HT * 2) + n * 2048 + k * 1024)
; #define MMA(ai, bj, At_, Bt_) do { __builtin_amdgcn_s_setprio(1); \
;     for (int m = 0; m < 4; ++m) for (int n = 0; n < 2; ++n) for (int k = 0; k < 2; ++k) \
;       acc[ai][bj][m][n] = __builtin_amdgcn_mfma_f32_16x16x32_bf16(Bt_[n][k], At_[m][k], acc[ai][bj][m][n], 0, 0, 0); \
;     __builtin_amdgcn_s_setprio(0); } while (0)
; #define WAIT_V(n) asm volatile("s_waitcnt vmcnt(" #n ")" ::: "memory")
; #define WAIT_L(n) asm volatile("s_waitcnt lgkmcnt(" #n ")" ::: "memory")
; #define BAR __builtin_amdgcn_s_barrier()
; #define SCHED __builtin_amdgcn_sched_barrier(0)
;     ...
;     BAR; WAIT_L(0); MMA(0, 1, At, B1); BAR;
;     LDA(At, 0, 1); STAGE_A(SA(0, 0), brow, t + 2);
;     BAR; WAIT_L(0); MMA(1, 0, At, B0); BAR; SCHED;
;     STAGE_B(SB(0, 1), bcol + HALF, t + 2);
;     WAIT_V(6); BAR; MMA(1, 1, At, B1); BAR;
;     LDB(B0, 1, 0); SCHED; LDA(At, 1, 0); STAGE_A(SA(0, 1), brow + HALF, t + 2);
;     WAIT_L(8); BAR; WAIT_L(0); MMA(0, 0, At, B0); BAR; SCHED;
;     LDB(B1, 1, 1); STAGE_B(SB(1, 0), bcol, t + 3);
;     BAR; WAIT_L(0); MMA(0, 1, At, B1); BAR;
	s_setprio 1
	v_mfma_f32_16x16x32_bf16 v[60:63], v[160:163], v[176:179], v[60:63]
	v_mfma_f32_16x16x32_bf16 v[56:59], v[168:171], v[176:179], v[56:59]
	v_mfma_f32_16x16x32_bf16 v[52:55], v[160:163], v[186:189], v[52:55]
	v_mfma_f32_16x16x32_bf16 v[48:51], v[168:171], v[186:189], v[48:51]
	v_mfma_f32_16x16x32_bf16 v[44:47], v[160:163], v[194:197], v[44:47]
	v_mfma_f32_16x16x32_bf16 v[40:43], v[168:171], v[194:197], v[40:43]
	v_mfma_f32_16x16x32_bf16 v[36:39], v[160:163], v[202:205], v[36:39]
	v_mfma_f32_16x16x32_bf16 v[32:35], v[168:171], v[202:205], v[32:35]
	v_mfma_f32_16x16x32_bf16 v[60:63], v[164:167], v[182:185], v[60:63]
	v_mfma_f32_16x16x32_bf16 v[56:59], v[172:175], v[182:185], v[56:59]
	v_mfma_f32_16x16x32_bf16 v[52:55], v[164:167], v[190:193], v[52:55]
	v_mfma_f32_16x16x32_bf16 v[48:51], v[172:175], v[190:193], v[48:51]
	v_mfma_f32_16x16x32_bf16 v[44:47], v[164:167], v[198:201], v[44:47]
	v_mfma_f32_16x16x32_bf16 v[40:43], v[172:175], v[198:201], v[40:43]
	v_mfma_f32_16x16x32_bf16 v[36:39], v[164:167], v[206:209], v[36:39]
	v_mfma_f32_16x16x32_bf16 v[32:35], v[172:175], v[206:209], v[32:35]
	v_mfma_f32_16x16x32_bf16 v[28:31], v[210:213], v[176:179], v[28:31]
	v_mfma_f32_16x16x32_bf16 v[24:27], v[218:221], v[176:179], v[24:27]
	v_mfma_f32_16x16x32_bf16 v[20:23], v[210:213], v[186:189], v[20:23]
	v_mfma_f32_16x16x32_bf16 v[16:19], v[218:221], v[186:189], v[16:19]
	v_mfma_f32_16x16x32_bf16 v[12:15], v[210:213], v[194:197], v[12:15]
	v_mfma_f32_16x16x32_bf16 v[8:11], v[218:221], v[194:197], v[8:11]
	v_mfma_f32_16x16x32_bf16 v[4:7], v[210:213], v[202:205], v[4:7]
	v_mfma_f32_16x16x32_bf16 v[0:3], v[218:221], v[202:205], v[0:3]
	v_mfma_f32_16x16x32_bf16 v[28:31], v[214:217], v[182:185], v[28:31]
	v_mfma_f32_16x16x32_bf16 v[24:27], v[230:233], v[182:185], v[24:27]
	v_mfma_f32_16x16x32_bf16 v[20:23], v[214:217], v[190:193], v[20:23]
	v_mfma_f32_16x16x32_bf16 v[16:19], v[230:233], v[190:193], v[16:19]
	v_mfma_f32_16x16x32_bf16 v[12:15], v[214:217], v[198:201], v[12:15]
	v_mfma_f32_16x16x32_bf16 v[8:11], v[230:233], v[198:201], v[8:11]
	s_setprio 2
	s_barrier
	v_mfma_f32_16x16x32_bf16 v[4:7], v[214:217], v[206:209], v[4:7]
	v_mfma_f32_16x16x32_bf16 v[0:3], v[230:233], v[206:209], v[0:3]
	s_setprio 0
	ds_read_b128 v[160:163], v147 offset:32768
	ds_read_b128 v[164:167], v147 offset:33792
	ds_read_b128 v[168:171], v147 offset:34816
	ds_read_b128 v[172:175], v147 offset:35840
	v_readfirstlane_b32 s9, v149
	v_lshl_add_u64 v[210:211], v[222:223], 0, s[80:81]
	s_mov_b32 m0, s9
	v_readfirstlane_b32 s9, v150
	ds_read_b128 v[176:179], v144 offset:32768
	ds_read_b128 v[182:185], v144 offset:33792
	ds_read_b128 v[186:189], v144 offset:34816
	ds_read_b128 v[190:193], v144 offset:35840
	ds_read_b128 v[194:197], v144 offset:36864
	ds_read_b128 v[198:201], v144 offset:37888
	ds_read_b128 v[202:205], v144 offset:38912
	ds_read_b128 v[206:209], v144 offset:39936
	global_load_lds_dwordx4 v[210:211], off
	v_lshl_add_u64 v[210:211], v[226:227], 0, s[80:81]
	s_mov_b32 m0, s9
	s_nop 0
	global_load_lds_dwordx4 v[210:211], off
	ds_read_b128 v[210:213], v147 offset:49152
	ds_read_b128 v[214:217], v147 offset:50176
	ds_read_b128 v[218:221], v147 offset:51200
	ds_read_b128 v[230:233], v147 offset:52224
	s_waitcnt lgkmcnt(0)
	s_waitcnt vmcnt(8)
	s_barrier
	s_setprio 1
	v_mfma_f32_16x16x32_bf16 v[124:127], v[160:163], v[176:179], v[124:127]
	v_mfma_f32_16x16x32_bf16 v[120:123], v[168:171], v[176:179], v[120:123]
	v_mfma_f32_16x16x32_bf16 v[116:119], v[160:163], v[186:189], v[116:119]
	v_mfma_f32_16x16x32_bf16 v[112:115], v[168:171], v[186:189], v[112:115]
	v_mfma_f32_16x16x32_bf16 v[108:111], v[160:163], v[194:197], v[108:111]
	v_mfma_f32_16x16x32_bf16 v[104:107], v[168:171], v[194:197], v[104:107]
	v_mfma_f32_16x16x32_bf16 v[100:103], v[160:163], v[202:205], v[100:103]
	v_mfma_f32_16x16x32_bf16 v[96:99], v[168:171], v[202:205], v[96:99]
	v_mfma_f32_16x16x32_bf16 v[124:127], v[164:167], v[182:185], v[124:127]
	v_mfma_f32_16x16x32_bf16 v[120:123], v[172:175], v[182:185], v[120:123]
	v_mfma_f32_16x16x32_bf16 v[116:119], v[164:167], v[190:193], v[116:119]
	v_mfma_f32_16x16x32_bf16 v[112:115], v[172:175], v[190:193], v[112:115]
	v_mfma_f32_16x16x32_bf16 v[108:111], v[164:167], v[198:201], v[108:111]
	v_mfma_f32_16x16x32_bf16 v[104:107], v[172:175], v[198:201], v[104:107]
	v_mfma_f32_16x16x32_bf16 v[100:103], v[164:167], v[206:209], v[100:103]
	v_mfma_f32_16x16x32_bf16 v[96:99], v[172:175], v[206:209], v[96:99]
	v_mfma_f32_16x16x32_bf16 v[92:95], v[210:213], v[176:179], v[92:95]
	v_mfma_f32_16x16x32_bf16 v[88:91], v[218:221], v[176:179], v[88:91]
	v_mfma_f32_16x16x32_bf16 v[84:87], v[210:213], v[186:189], v[84:87]
	v_mfma_f32_16x16x32_bf16 v[80:83], v[218:221], v[186:189], v[80:83]
	v_mfma_f32_16x16x32_bf16 v[76:79], v[210:213], v[194:197], v[76:79]
	v_mfma_f32_16x16x32_bf16 v[72:75], v[218:221], v[194:197], v[72:75]
	v_mfma_f32_16x16x32_bf16 v[68:71], v[210:213], v[202:205], v[68:71]
	v_mfma_f32_16x16x32_bf16 v[64:67], v[218:221], v[202:205], v[64:67]
	v_mfma_f32_16x16x32_bf16 v[92:95], v[214:217], v[182:185], v[92:95]
	v_mfma_f32_16x16x32_bf16 v[88:91], v[230:233], v[182:185], v[88:91]
	v_mfma_f32_16x16x32_bf16 v[84:87], v[214:217], v[190:193], v[84:87]
	v_mfma_f32_16x16x32_bf16 v[80:83], v[230:233], v[190:193], v[80:83]
	v_mfma_f32_16x16x32_bf16 v[76:79], v[214:217], v[198:201], v[76:79]
	v_mfma_f32_16x16x32_bf16 v[72:75], v[230:233], v[198:201], v[72:75]
	s_setprio 2
	s_barrier
; #define STAGE_A(P, br, kt) do { const char* _base = (const char*)(((kt) < G.ksplit ? G.A1 : A2m) + (long)(br) * G.lda + (long)(kt) * BK); \
;     __builtin_amdgcn_global_load_lds((const unsigned*)(_base + aoff0), (unsigned*)((char*)(P) + sb0), 16, 0, 0); \
;     __builtin_amdgcn_global_load_lds((const unsigned*)(_base + aoff1), (unsigned*)((char*)(P) + sb1), 16, 0, 0); } while (0)
; #define STAGE_B(P, br, kt) do { const char* _base = (const char*)(G.Bt + (long)(br) * G.ldb + (long)(kt) * BK); \
;     __builtin_amdgcn_global_load_lds((const unsigned*)(_base + boff0), (unsigned*)((char*)(P) + sb0), 16, 0, 0); \
;     __builtin_amdgcn_global_load_lds((const unsigned*)(_base + boff1), (unsigned*)((char*)(P) + sb1), 16, 0, 0); } while (0)
; #define LDA(dst, b, h) for (int m = 0; m < 4; ++m) for (int k = 0; k < 2; ++k) \
;     dst[m][k] = *reinterpret_cast<const bf16x8*>(a_rd + ((b) * 2 + (h)) * (HT * 2) + m * 2048 + k * 1024)
; #define LDB(dst, b, h) for (int n = 0; n < 2; ++n) for (int k = 0; k < 2; ++k) \
;     dst[n][k] = *reinterpret_cast<const bf16x8*>(b_rd + ((b) * 2 + (h)) * (HT * 2) + n * 2048 + k * 1024)
; #define MMA(ai, bj, At_, Bt_) do { __builtin_amdgcn_s_setprio(1); \
;     for (int m = 0; m < 4; ++m) for (int n = 0; n < 2; ++n) for (int k = 0; k < 2; ++k) \
;       acc[ai][bj][m][n] = __builtin_amdgcn_mfma_f32_16x16x32_bf16(Bt_[n][k], At_[m][k], acc[ai][bj][m][n], 0, 0, 0); \
;     __builtin_amdgcn_s_setprio(0); } while (0)
; #define WAIT_V(n) asm volatile("s_waitcnt vmcnt(" #n ")" ::: "memory")
; #define WAIT_L(n) asm volatile("s_waitcnt lgkmcnt(" #n ")" ::: "memory")
; #define BAR __builtin_amdgcn_s_barrier()
; #define SCHED __builtin_amdgcn_sched_barrier(0)
;     ...
;     LDB(B1, 1, 1); STAGE_B(SB(1, 0), bcol, t + 3);
;     BAR; WAIT_L(0); MMA(0, 1, At, B1); BAR;
;     LDA(At, 1, 1); STAGE_A(SA(1, 0), brow, t + 3);
;     BAR; WAIT_L(0); MMA(1, 0, At, B0); BAR; SCHED;
;     STAGE_B(SB(1, 1), bcol + HALF, t + 3);
;     WAIT_V(6); BAR; MMA(1, 1, At, B1); BAR;
;   }
;   float ssv[2][4] = {};
;   if constexpr (EPI == EPI_GU || EPI == EPI_EVIN || EPI == EPI_ODIN) {
; #pragma unroll
;     for (int ai = 0; ai < 2; ++ai)
; #pragma unroll
;       for (int m = 0; m < 4; ++m) ssv[ai][m] = G.ssr[brow + ai * HALF + wr * 64 + m * 16 + fr];
;   }
;   { LDB(B0, 0, 0); LDA(At, 0, 0); STAGE_A(SA(1, 1), brow + HALF, nt - 1);
;     BAR; WAIT_L(0); MMA(0, 0, At, B0); BAR;
	v_mfma_f32_16x16x32_bf16 v[68:71], v[214:217], v[206:209], v[68:71]
	v_mfma_f32_16x16x32_bf16 v[64:67], v[230:233], v[206:209], v[64:67]
	s_setprio 0
	v_readfirstlane_b32 s9, v151
	v_lshl_add_u64 v[234:235], v[234:235], 0, s[82:83]
	s_mov_b32 m0, s9
	v_readfirstlane_b32 s9, v152
	global_load_lds_dwordx4 v[234:235], off
	v_lshl_add_u64 v[234:235], v[236:237], 0, s[82:83]
	s_mov_b32 m0, s9
	s_nop 0
	global_load_lds_dwordx4 v[234:235], off
	v_readfirstlane_b32 s9, v153
	v_lshl_add_u64 v[222:223], v[222:223], 0, s[54:55]
	s_mov_b32 m0, s9
	v_readfirstlane_b32 s9, v154
	ds_read_b128 v[176:179], v144 offset:49152
	ds_read_b128 v[182:185], v144 offset:50176
	ds_read_b128 v[186:189], v144 offset:51200
	ds_read_b128 v[190:193], v144 offset:52224
	ds_read_b128 v[194:197], v144 offset:53248
	ds_read_b128 v[198:201], v144 offset:54272
	ds_read_b128 v[202:205], v144 offset:55296
	ds_read_b128 v[206:209], v144 offset:56320
	global_load_lds_dwordx4 v[222:223], off
	v_lshl_add_u64 v[222:223], v[226:227], 0, s[54:55]
	s_mov_b32 m0, s9
	s_nop 0
	global_load_lds_dwordx4 v[222:223], off
	v_readfirstlane_b32 s9, v155
	v_lshl_add_u64 v[250:251], v[238:239], 0, s[92:93]
	s_mov_b32 m0, s9
	v_readfirstlane_b32 s9, v156
	global_load_lds_dwordx4 v[250:251], off
	v_lshl_add_u64 v[250:251], v[240:241], 0, s[92:93]
	s_mov_b32 m0, s9
	s_nop 0
	global_load_lds_dwordx4 v[250:251], off
	s_waitcnt lgkmcnt(0)
	s_waitcnt vmcnt(8)
	s_barrier
	s_setprio 1
	v_mfma_f32_16x16x32_bf16 v[60:63], v[160:163], v[176:179], v[60:63]
	v_mfma_f32_16x16x32_bf16 v[56:59], v[168:171], v[176:179], v[56:59]
	v_mfma_f32_16x16x32_bf16 v[52:55], v[160:163], v[186:189], v[52:55]
	v_mfma_f32_16x16x32_bf16 v[48:51], v[168:171], v[186:189], v[48:51]
	v_mfma_f32_16x16x32_bf16 v[44:47], v[160:163], v[194:197], v[44:47]
	v_mfma_f32_16x16x32_bf16 v[40:43], v[168:171], v[194:197], v[40:43]
	v_mfma_f32_16x16x32_bf16 v[36:39], v[160:163], v[202:205], v[36:39]
	v_mfma_f32_16x16x32_bf16 v[32:35], v[168:171], v[202:205], v[32:35]
	v_mfma_f32_16x16x32_bf16 v[60:63], v[164:167], v[182:185], v[60:63]
	v_mfma_f32_16x16x32_bf16 v[56:59], v[172:175], v[182:185], v[56:59]
	v_mfma_f32_16x16x32_bf16 v[52:55], v[164:167], v[190:193], v[52:55]
	v_mfma_f32_16x16x32_bf16 v[48:51], v[172:175], v[190:193], v[48:51]
	v_mfma_f32_16x16x32_bf16 v[44:47], v[164:167], v[198:201], v[44:47]
	v_mfma_f32_16x16x32_bf16 v[40:43], v[172:175], v[198:201], v[40:43]
	v_mfma_f32_16x16x32_bf16 v[36:39], v[164:167], v[206:209], v[36:39]
	v_mfma_f32_16x16x32_bf16 v[32:35], v[172:175], v[206:209], v[32:35]
	v_mfma_f32_16x16x32_bf16 v[28:31], v[210:213], v[176:179], v[28:31]
	v_mfma_f32_16x16x32_bf16 v[24:27], v[218:221], v[176:179], v[24:27]
	v_mfma_f32_16x16x32_bf16 v[20:23], v[210:213], v[186:189], v[20:23]
	v_mfma_f32_16x16x32_bf16 v[16:19], v[218:221], v[186:189], v[16:19]
	v_mfma_f32_16x16x32_bf16 v[12:15], v[210:213], v[194:197], v[12:15]
	v_mfma_f32_16x16x32_bf16 v[8:11], v[218:221], v[194:197], v[8:11]
	v_mfma_f32_16x16x32_bf16 v[4:7], v[210:213], v[202:205], v[4:7]
	v_mfma_f32_16x16x32_bf16 v[0:3], v[218:221], v[202:205], v[0:3]
	v_mfma_f32_16x16x32_bf16 v[28:31], v[214:217], v[182:185], v[28:31]
	v_mfma_f32_16x16x32_bf16 v[24:27], v[230:233], v[182:185], v[24:27]
	v_mfma_f32_16x16x32_bf16 v[20:23], v[214:217], v[190:193], v[20:23]
	v_mfma_f32_16x16x32_bf16 v[16:19], v[230:233], v[190:193], v[16:19]
	v_mfma_f32_16x16x32_bf16 v[12:15], v[214:217], v[198:201], v[12:15]
	v_mfma_f32_16x16x32_bf16 v[8:11], v[230:233], v[198:201], v[8:11]
	s_setprio 2
	s_barrier
	v_mfma_f32_16x16x32_bf16 v[4:7], v[214:217], v[206:209], v[4:7]
	v_mfma_f32_16x16x32_bf16 v[0:3], v[230:233], v[206:209], v[0:3]
	s_setprio 0
	s_add_i32 s8, s8, 2
	v_lshl_add_u64 v[130:131], v[130:131], 0, s[90:91]
	v_lshl_add_u64 v[132:133], v[132:133], 0, s[90:91]
	v_lshl_add_u64 v[134:135], v[134:135], 0, s[90:91]
	v_lshl_add_u64 v[136:137], v[136:137], 0, s[90:91]
	v_lshl_add_u64 v[138:139], v[138:139], 0, s[90:91]
	s_cmpk_lt_u32 s8, 0x54
	v_lshl_add_u64 v[140:141], v[140:141], 0, s[90:91]
	s_cbranch_scc1 .LBB0_2622
	s_waitcnt vmcnt(6)
	v_not_b32_e32 v250, 63
	v_mov_b32_e32 v251, 0x41b17218
	s_add_u32 s6, s6, 0x2b80
	s_addc_u32 s7, s7, 0
	v_readfirstlane_b32 s8, v157
	v_lshl_add_u64 v[190:191], s[6:7], 0, v[180:181]
	s_mov_b32 m0, s8
	v_lshl_add_u64 v[128:129], s[6:7], 0, v[128:129]
	v_readfirstlane_b32 s6, v158
	ds_read_b128 v[130:133], v147
	ds_read_b128 v[134:137], v147 offset:1024
	ds_read_b128 v[138:141], v147 offset:2048
	ds_read_b128 v[148:151], v147 offset:3072
	ds_read_b128 v[152:155], v144
	ds_read_b128 v[160:163], v144 offset:1024
	ds_read_b128 v[164:167], v144 offset:2048
	ds_read_b128 v[168:171], v144 offset:3072
	ds_read_b128 v[172:175], v144 offset:4096
	ds_read_b128 v[176:179], v144 offset:5120
	ds_read_b128 v[182:185], v144 offset:6144
	ds_read_b128 v[186:189], v144 offset:7168
	global_load_lds_dwordx4 v[190:191], off
	s_mov_b32 m0, s6
	s_nop 0
	global_load_lds_dwordx4 v[128:129], off
	s_barrier
	s_waitcnt lgkmcnt(0)
	s_setprio 1
	s_waitcnt lgkmcnt(0)
	v_mfma_f32_16x16x32_bf16 v[124:127], v[130:133], v[152:155], v[124:127]
	v_mfma_f32_16x16x32_bf16 v[120:123], v[138:141], v[152:155], v[120:123]
	v_mfma_f32_16x16x32_bf16 v[116:119], v[130:133], v[164:167], v[116:119]
	v_mfma_f32_16x16x32_bf16 v[112:115], v[138:141], v[164:167], v[112:115]
	v_mfma_f32_16x16x32_bf16 v[108:111], v[130:133], v[172:175], v[108:111]
	v_mfma_f32_16x16x32_bf16 v[104:107], v[138:141], v[172:175], v[104:107]
	v_mfma_f32_16x16x32_bf16 v[100:103], v[130:133], v[182:185], v[100:103]
	v_mfma_f32_16x16x32_bf16 v[96:99], v[138:141], v[182:185], v[96:99]
	v_mfma_f32_16x16x32_bf16 v[124:127], v[134:137], v[160:163], v[124:127]
	v_mfma_f32_16x16x32_bf16 v[120:123], v[148:151], v[160:163], v[120:123]
	v_mfma_f32_16x16x32_bf16 v[116:119], v[134:137], v[168:171], v[116:119]
	v_mfma_f32_16x16x32_bf16 v[112:115], v[148:151], v[168:171], v[112:115]
	v_mfma_f32_16x16x32_bf16 v[108:111], v[134:137], v[176:179], v[108:111]
	v_mfma_f32_16x16x32_bf16 v[104:107], v[148:151], v[176:179], v[104:107]
	s_setprio 2
	s_barrier
; #define LDA(dst, b, h) for (int m = 0; m < 4; ++m) for (int k = 0; k < 2; ++k) \
;     dst[m][k] = *reinterpret_cast<const bf16x8*>(a_rd + ((b) * 2 + (h)) * (HT * 2) + m * 2048 + k * 1024)
; #define LDB(dst, b, h) for (int n = 0; n < 2; ++n) for (int k = 0; k < 2; ++k) \
;     dst[n][k] = *reinterpret_cast<const bf16x8*>(b_rd + ((b) * 2 + (h)) * (HT * 2) + n * 2048 + k * 1024)
; #define MMA(ai, bj, At_, Bt_) do { __builtin_amdgcn_s_setprio(1); \
;     for (int m = 0; m < 4; ++m) for (int n = 0; n < 2; ++n) for (int k = 0; k < 2; ++k) \
;       acc[ai][bj][m][n] = __builtin_amdgcn_mfma_f32_16x16x32_bf16(Bt_[n][k], At_[m][k], acc[ai][bj][m][n], 0, 0, 0); \
;     __builtin_amdgcn_s_setprio(0); } while (0)
; #define WAIT_V(n) asm volatile("s_waitcnt vmcnt(" #n ")" ::: "memory")
; #define WAIT_L(n) asm volatile("s_waitcnt lgkmcnt(" #n ")" ::: "memory")
; #define BAR __builtin_amdgcn_s_barrier()
;     ...
;     BAR; WAIT_L(0); MMA(0, 0, At, B0); BAR;
;     LDB(B1, 0, 1); BAR; WAIT_L(0); MMA(0, 1, At, B1); BAR;
;     LDA(At, 0, 1); WAIT_V(4); BAR; WAIT_L(0); MMA(1, 0, At, B0); MMA(1, 1, At, B1); BAR; }
;   { LDB(B0, 1, 0); LDA(At, 1, 0); WAIT_V(2); BAR; WAIT_L(0); MMA(0, 0, At, B0); BAR;
	v_mfma_f32_16x16x32_bf16 v[100:103], v[134:137], v[186:189], v[100:103]
	v_mfma_f32_16x16x32_bf16 v[96:99], v[148:151], v[186:189], v[96:99]
	s_setprio 0
	ds_read_b128 v[156:159], v147 offset:16384
	ds_read_b128 v[190:193], v147 offset:17408
	ds_read_b128 v[194:197], v147 offset:18432
	ds_read_b128 v[198:201], v147 offset:19456
	s_barrier
	s_waitcnt lgkmcnt(0)
	s_setprio 1
	s_waitcnt lgkmcnt(0)
	v_mfma_f32_16x16x32_bf16 v[92:95], v[156:159], v[152:155], v[92:95]
	v_mfma_f32_16x16x32_bf16 v[88:91], v[194:197], v[152:155], v[88:91]
	v_mfma_f32_16x16x32_bf16 v[84:87], v[156:159], v[164:167], v[84:87]
	v_mfma_f32_16x16x32_bf16 v[80:83], v[194:197], v[164:167], v[80:83]
	v_mfma_f32_16x16x32_bf16 v[76:79], v[156:159], v[172:175], v[76:79]
	v_mfma_f32_16x16x32_bf16 v[72:75], v[194:197], v[172:175], v[72:75]
	v_mfma_f32_16x16x32_bf16 v[68:71], v[156:159], v[182:185], v[68:71]
	v_mfma_f32_16x16x32_bf16 v[64:67], v[194:197], v[182:185], v[64:67]
	v_mfma_f32_16x16x32_bf16 v[202:205], v[190:193], v[160:163], v[92:95]
	v_mfma_f32_16x16x32_bf16 v[152:155], v[198:201], v[160:163], v[88:91]
	v_mfma_f32_16x16x32_bf16 v[160:163], v[190:193], v[168:171], v[84:87]
	v_mfma_f32_16x16x32_bf16 v[164:167], v[198:201], v[168:171], v[80:83]
	v_mfma_f32_16x16x32_bf16 v[168:171], v[190:193], v[176:179], v[76:79]
	v_mfma_f32_16x16x32_bf16 v[172:175], v[198:201], v[176:179], v[72:75]
	s_setprio 2
	s_barrier
	v_mfma_f32_16x16x32_bf16 v[176:179], v[190:193], v[186:189], v[68:71]
	v_mfma_f32_16x16x32_bf16 v[182:185], v[198:201], v[186:189], v[64:67]
	s_setprio 0
	s_nop 0
	ds_read_b128 v[64:67], v144 offset:16384
	ds_read_b128 v[68:71], v144 offset:17408
	ds_read_b128 v[72:75], v144 offset:18432
	ds_read_b128 v[76:79], v144 offset:19456
	ds_read_b128 v[80:83], v144 offset:20480
	ds_read_b128 v[84:87], v144 offset:21504
	ds_read_b128 v[88:91], v144 offset:22528
	ds_read_b128 v[92:95], v144 offset:23552
	s_waitcnt vmcnt(4)
	s_barrier
	s_waitcnt lgkmcnt(0)
	s_setprio 1
	s_waitcnt lgkmcnt(0)
	v_mfma_f32_16x16x32_bf16 v[60:63], v[130:133], v[64:67], v[60:63]
	v_mfma_f32_16x16x32_bf16 v[56:59], v[138:141], v[64:67], v[56:59]
	v_mfma_f32_16x16x32_bf16 v[52:55], v[130:133], v[72:75], v[52:55]
	v_mfma_f32_16x16x32_bf16 v[48:51], v[138:141], v[72:75], v[48:51]
	v_mfma_f32_16x16x32_bf16 v[44:47], v[130:133], v[80:83], v[44:47]
	v_mfma_f32_16x16x32_bf16 v[40:43], v[138:141], v[80:83], v[40:43]
	v_mfma_f32_16x16x32_bf16 v[36:39], v[130:133], v[88:91], v[36:39]
	v_mfma_f32_16x16x32_bf16 v[32:35], v[138:141], v[88:91], v[32:35]
	v_mfma_f32_16x16x32_bf16 v[60:63], v[134:137], v[68:71], v[60:63]
	v_mfma_f32_16x16x32_bf16 v[56:59], v[148:151], v[68:71], v[56:59]
	v_mfma_f32_16x16x32_bf16 v[52:55], v[134:137], v[76:79], v[52:55]
	v_mfma_f32_16x16x32_bf16 v[48:51], v[148:151], v[76:79], v[48:51]
	v_mfma_f32_16x16x32_bf16 v[44:47], v[134:137], v[84:87], v[44:47]
	v_mfma_f32_16x16x32_bf16 v[40:43], v[148:151], v[84:87], v[40:43]
	v_mfma_f32_16x16x32_bf16 v[36:39], v[134:137], v[92:95], v[36:39]
	v_mfma_f32_16x16x32_bf16 v[32:35], v[148:151], v[92:95], v[32:35]
	s_setprio 0
	s_setprio 1
	v_mfma_f32_16x16x32_bf16 v[28:31], v[156:159], v[64:67], v[28:31]
	v_mfma_f32_16x16x32_bf16 v[24:27], v[194:197], v[64:67], v[24:27]
	v_mfma_f32_16x16x32_bf16 v[20:23], v[156:159], v[72:75], v[20:23]
	v_mfma_f32_16x16x32_bf16 v[16:19], v[194:197], v[72:75], v[16:19]
	v_mfma_f32_16x16x32_bf16 v[12:15], v[156:159], v[80:83], v[12:15]
	v_mfma_f32_16x16x32_bf16 v[8:11], v[194:197], v[80:83], v[8:11]
	v_mfma_f32_16x16x32_bf16 v[4:7], v[156:159], v[88:91], v[4:7]
	v_mfma_f32_16x16x32_bf16 v[0:3], v[194:197], v[88:91], v[0:3]
	v_mfma_f32_16x16x32_bf16 v[128:131], v[190:193], v[68:71], v[28:31]
	v_mfma_f32_16x16x32_bf16 v[132:135], v[198:201], v[68:71], v[24:27]
	v_mfma_f32_16x16x32_bf16 v[136:139], v[190:193], v[76:79], v[20:23]
	v_mfma_f32_16x16x32_bf16 v[148:151], v[198:201], v[76:79], v[16:19]
	v_mfma_f32_16x16x32_bf16 v[186:189], v[190:193], v[84:87], v[12:15]
	v_mfma_f32_16x16x32_bf16 v[206:209], v[198:201], v[84:87], v[8:11]
	s_setprio 2
	s_barrier
	v_mfma_f32_16x16x32_bf16 v[156:159], v[190:193], v[92:95], v[4:7]
	v_mfma_f32_16x16x32_bf16 v[190:193], v[198:201], v[92:95], v[0:3]
	s_setprio 0
	ds_read_b128 v[24:27], v147 offset:32768
	ds_read_b128 v[28:31], v147 offset:33792
	ds_read_b128 v[194:197], v147 offset:34816
	ds_read_b128 v[198:201], v147 offset:35840
	ds_read_b128 v[0:3], v144 offset:32768
	ds_read_b128 v[4:7], v144 offset:33792
	ds_read_b128 v[8:11], v144 offset:34816
	ds_read_b128 v[12:15], v144 offset:35840
	ds_read_b128 v[16:19], v144 offset:36864
	ds_read_b128 v[20:23], v144 offset:37888
	ds_read_b128 v[210:213], v144 offset:38912
	ds_read_b128 v[214:217], v144 offset:39936
	s_waitcnt vmcnt(2)
	s_barrier
; #define LDA(dst, b, h) for (int m = 0; m < 4; ++m) for (int k = 0; k < 2; ++k) \
;     dst[m][k] = *reinterpret_cast<const bf16x8*>(a_rd + ((b) * 2 + (h)) * (HT * 2) + m * 2048 + k * 1024)
; #define LDB(dst, b, h) for (int n = 0; n < 2; ++n) for (int k = 0; k < 2; ++k) \
;     dst[n][k] = *reinterpret_cast<const bf16x8*>(b_rd + ((b) * 2 + (h)) * (HT * 2) + n * 2048 + k * 1024)
; #define MMA(ai, bj, At_, Bt_) do { __builtin_amdgcn_s_setprio(1); \
;     for (int m = 0; m < 4; ++m) for (int n = 0; n < 2; ++n) for (int k = 0; k < 2; ++k) \
;       acc[ai][bj][m][n] = __builtin_amdgcn_mfma_f32_16x16x32_bf16(Bt_[n][k], At_[m][k], acc[ai][bj][m][n], 0, 0, 0); \
;     __builtin_amdgcn_s_setprio(0); } while (0)
; #define WAIT_V(n) asm volatile("s_waitcnt vmcnt(" #n ")" ::: "memory")
; #define WAIT_L(n) asm volatile("s_waitcnt lgkmcnt(" #n ")" ::: "memory")
; #define BAR __builtin_amdgcn_s_barrier()
;     ...
;   { LDB(B0, 1, 0); LDA(At, 1, 0); WAIT_V(2); BAR; WAIT_L(0); MMA(0, 0, At, B0); BAR;
;     LDB(B1, 1, 1); WAIT_V(0); BAR; WAIT_L(0); MMA(0, 1, At, B1); BAR;
;     LDA(At, 1, 1); BAR; WAIT_L(0); MMA(1, 0, At, B0); MMA(1, 1, At, B1); BAR; }
;   if (wr == 0) BAR;
	s_waitcnt lgkmcnt(0)
	s_setprio 1
	s_waitcnt lgkmcnt(0)
	v_mfma_f32_16x16x32_bf16 v[64:67], v[24:27], v[0:3], v[124:127]
	v_mfma_f32_16x16x32_bf16 v[68:71], v[194:197], v[0:3], v[120:123]
	v_mfma_f32_16x16x32_bf16 v[72:75], v[24:27], v[8:11], v[116:119]
	v_mfma_f32_16x16x32_bf16 v[76:79], v[194:197], v[8:11], v[112:115]
	v_mfma_f32_16x16x32_bf16 v[80:83], v[24:27], v[16:19], v[108:111]
	v_mfma_f32_16x16x32_bf16 v[84:87], v[194:197], v[16:19], v[104:107]
	v_mfma_f32_16x16x32_bf16 v[88:91], v[24:27], v[210:213], v[100:103]
	v_mfma_f32_16x16x32_bf16 v[92:95], v[194:197], v[210:213], v[96:99]
	v_mfma_f32_16x16x32_bf16 v[64:67], v[28:31], v[4:7], v[64:67]
	v_mfma_f32_16x16x32_bf16 v[68:71], v[198:201], v[4:7], v[68:71]
	v_mfma_f32_16x16x32_bf16 v[72:75], v[28:31], v[12:15], v[72:75]
	v_mfma_f32_16x16x32_bf16 v[76:79], v[198:201], v[12:15], v[76:79]
	v_mfma_f32_16x16x32_bf16 v[80:83], v[28:31], v[20:23], v[80:83]
	v_mfma_f32_16x16x32_bf16 v[84:87], v[198:201], v[20:23], v[84:87]
	s_setprio 2
	s_barrier
	v_mfma_f32_16x16x32_bf16 v[88:91], v[28:31], v[214:217], v[88:91]
	v_mfma_f32_16x16x32_bf16 v[92:95], v[198:201], v[214:217], v[92:95]
	s_setprio 0
	ds_read_b128 v[218:221], v147 offset:49152
	ds_read_b128 v[230:233], v147 offset:50176
	ds_read_b128 v[234:237], v147 offset:51200
	ds_read_b128 v[238:241], v147 offset:52224
	s_waitcnt vmcnt(0)
	s_barrier
	s_waitcnt lgkmcnt(0)
	s_setprio 1
	s_waitcnt lgkmcnt(0)
	v_mfma_f32_16x16x32_bf16 v[96:99], v[218:221], v[0:3], v[202:205]
	v_mfma_f32_16x16x32_bf16 v[0:3], v[234:237], v[0:3], v[152:155]
	v_mfma_f32_16x16x32_bf16 v[100:103], v[238:241], v[4:7], v[0:3]
	v_mfma_f32_16x16x32_bf16 v[0:3], v[218:221], v[8:11], v[160:163]
	v_mfma_f32_16x16x32_bf16 v[104:107], v[230:233], v[12:15], v[0:3]
	v_mfma_f32_16x16x32_bf16 v[0:3], v[234:237], v[8:11], v[164:167]
	v_mfma_f32_16x16x32_bf16 v[108:111], v[238:241], v[12:15], v[0:3]
	v_mfma_f32_16x16x32_bf16 v[0:3], v[218:221], v[16:19], v[168:171]
	v_mfma_f32_16x16x32_bf16 v[112:115], v[230:233], v[20:23], v[0:3]
	v_mfma_f32_16x16x32_bf16 v[0:3], v[234:237], v[16:19], v[172:175]
	v_mfma_f32_16x16x32_bf16 v[116:119], v[238:241], v[20:23], v[0:3]
	v_mfma_f32_16x16x32_bf16 v[0:3], v[218:221], v[210:213], v[176:179]
	v_mfma_f32_16x16x32_bf16 v[120:123], v[230:233], v[214:217], v[0:3]
	v_mfma_f32_16x16x32_bf16 v[0:3], v[234:237], v[210:213], v[182:185]
	s_setprio 2
	s_barrier
	v_mfma_f32_16x16x32_bf16 v[96:99], v[230:233], v[4:7], v[96:99]
	v_mfma_f32_16x16x32_bf16 v[124:127], v[238:241], v[214:217], v[0:3]
	s_setprio 0
	ds_read_b128 v[152:155], v144 offset:49152
	ds_read_b128 v[160:163], v144 offset:50176
	ds_read_b128 v[164:167], v144 offset:51200
	ds_read_b128 v[168:171], v144 offset:52224
	ds_read_b128 v[172:175], v144 offset:53248
	ds_read_b128 v[176:179], v144 offset:54272
	ds_read_b128 v[182:185], v144 offset:55296
	ds_read_b128 v[144:147], v144 offset:56320
	s_barrier
	s_waitcnt lgkmcnt(0)
	s_setprio 1
	s_waitcnt lgkmcnt(0)
	v_mfma_f32_16x16x32_bf16 v[0:3], v[24:27], v[152:155], v[60:63]
	v_mfma_f32_16x16x32_bf16 v[8:11], v[24:27], v[164:167], v[52:55]
	v_mfma_f32_16x16x32_bf16 v[16:19], v[24:27], v[172:175], v[44:47]
	v_mfma_f32_16x16x32_bf16 v[24:27], v[24:27], v[182:185], v[36:39]
	v_mfma_f32_16x16x32_bf16 v[0:3], v[28:31], v[160:163], v[0:3]
	v_mfma_f32_16x16x32_bf16 v[4:7], v[194:197], v[152:155], v[56:59]
	v_mfma_f32_16x16x32_bf16 v[8:11], v[28:31], v[168:171], v[8:11]
	v_mfma_f32_16x16x32_bf16 v[12:15], v[194:197], v[164:167], v[48:51]
	v_mfma_f32_16x16x32_bf16 v[16:19], v[28:31], v[176:179], v[16:19]
	v_mfma_f32_16x16x32_bf16 v[20:23], v[194:197], v[172:175], v[40:43]
	v_mfma_f32_16x16x32_bf16 v[24:27], v[28:31], v[144:147], v[24:27]
	v_mfma_f32_16x16x32_bf16 v[28:31], v[194:197], v[182:185], v[32:35]
	v_mfma_f32_16x16x32_bf16 v[4:7], v[198:201], v[160:163], v[4:7]
	v_mfma_f32_16x16x32_bf16 v[12:15], v[198:201], v[168:171], v[12:15]
	v_mfma_f32_16x16x32_bf16 v[20:23], v[198:201], v[176:179], v[20:23]
	v_mfma_f32_16x16x32_bf16 v[28:31], v[198:201], v[144:147], v[28:31]
	s_setprio 0
	s_setprio 1
	v_mfma_f32_16x16x32_bf16 v[32:35], v[218:221], v[152:155], v[128:131]
	v_mfma_f32_16x16x32_bf16 v[36:39], v[234:237], v[152:155], v[132:135]
	v_mfma_f32_16x16x32_bf16 v[40:43], v[218:221], v[164:167], v[136:139]
	v_mfma_f32_16x16x32_bf16 v[44:47], v[234:237], v[164:167], v[148:151]
	v_mfma_f32_16x16x32_bf16 v[48:51], v[218:221], v[172:175], v[186:189]
	v_mfma_f32_16x16x32_bf16 v[52:55], v[234:237], v[172:175], v[206:209]
	v_mfma_f32_16x16x32_bf16 v[56:59], v[218:221], v[182:185], v[156:159]
	v_mfma_f32_16x16x32_bf16 v[60:63], v[234:237], v[182:185], v[190:193]
	v_mfma_f32_16x16x32_bf16 v[32:35], v[230:233], v[160:163], v[32:35]
	v_mfma_f32_16x16x32_bf16 v[36:39], v[238:241], v[160:163], v[36:39]
	v_mfma_f32_16x16x32_bf16 v[40:43], v[230:233], v[168:171], v[40:43]
	v_mfma_f32_16x16x32_bf16 v[44:47], v[238:241], v[168:171], v[44:47]
	v_mfma_f32_16x16x32_bf16 v[48:51], v[230:233], v[176:179], v[48:51]
	v_mfma_f32_16x16x32_bf16 v[52:55], v[238:241], v[176:179], v[52:55]
	s_setprio 2
	s_barrier
	v_mfma_f32_16x16x32_bf16 v[56:59], v[230:233], v[144:147], v[56:59]
	v_mfma_f32_16x16x32_bf16 v[60:63], v[238:241], v[144:147], v[60:63]
	s_setprio 0
	v_cmp_gt_u32_e32 vcc, s60, v142
	s_and_saveexec_b64 s[6:7], vcc
	s_cbranch_execz .LBB0_2625
	s_barrier
